# v11: gelu tail fused: out = fma(-|v|, q*e, max(v,0)) replaces mul + fma + 2 cmp + 2 cndmask (same roundings)
# baseline (speedup 1.0000x reference)
; __device__ __forceinline__ f32x4 sigm4(f32x4 v) { return (f32x4){sigmoid_f(v[0]), sigmoid_f(v[1]), sigmoid_f(v[2]), sigmoid_f(v[3])}; }
; __device__ __forceinline__ f32x2 gelu_pk(f32x2 v) {
;     const f32x2 av = __builtin_elementwise_abs(v), d = av * 0.2316418882f + 1.0f;
;     f32x2 t; t.x = __builtin_amdgcn_rcpf(d.x); t.y = __builtin_amdgcn_rcpf(d.y);
;     f32x2 q = t * 0.5307027145f + (-0.7265760135f); q = q * t + 0.7107068705f; q = q * t + (-0.142248368f); q = q * t + 0.127414796f; q = q * t;
;     const f32x2 s = (v * v) * (-0.72134752044f);
;     f32x2 e; e.x = __builtin_amdgcn_exp2f(s.x); e.y = __builtin_amdgcn_exp2f(s.y);
;     const f32x2 m = v * (q * e), r = v - m;
;     f32x2 o; o.x = v.x < 0.f ? m.x : r.x; o.y = v.y < 0.f ? m.y : r.y; return o;
; }
; __device__ __forceinline__ f32x4 gelu4(f32x4 v) { f32x2 a = gelu_pk((f32x2){v[0], v[1]}), b = gelu_pk((f32x2){v[2], v[3]}); return (f32x4){a.x, a.y, b.x, b.y}; }
;     __device__ __forceinline__ void operator()(const f32x4 (&acc)[2][2][4][2], const pg8::Unit& u, int wr, int wc, int fr, int fq) const {
;     ...
;                     for (int bj = 0; bj < 2; ++bj) {
;                         f32x4 v0 = acc[ai][bj][m][0], v1 = acc[ai][bj][m][1];
;                         if (act == 5) { v0 = sigm4(v0); v1 = sigm4(v1);
;                             if (bj == 0) { const f32x4 b0 = sigm4(acc[ai][1][m][0]), b1 = sigm4(acc[ai][1][m][1]);
; #pragma unroll
;                                 for (int e = 0; e < 4; ++e) { v0[e] *= __builtin_amdgcn_rcpf(fmaxf(b0[e], 1e-20f)); v1[e] *= __builtin_amdgcn_rcpf(fmaxf(b1[e], 1e-20f)); } } }
;                         else if (act == 1) { v0 = gelu4(v0); v1 = gelu4(v1); }
.LBB0_195:
	s_andn2_b64 vcc, exec, s[16:17]
	s_cbranch_vccnz .LBB0_197
	v_and_b32_e32 v249, 0x7fffffff, v125
	v_and_b32_e32 v248, 0x7fffffff, v124
	v_pk_fma_f32 v[148:149], v[248:249], s[28:29], 1.0 op_sel_hi:[1,0,0]
	v_mov_b64_e32 v[152:153], s[34:35]
	v_rcp_f32_e32 v148, v148
	v_rcp_f32_e32 v149, v149
	v_pk_mul_f32 v[156:157], v[126:127], v[126:127]
	v_pk_mul_f32 v[160:161], v[118:119], v[118:119]
	v_pk_fma_f32 v[154:155], v[148:149], s[30:31], v[152:153] op_sel_hi:[1,0,0]
	v_pk_mul_f32 v[156:157], v[156:157], s[74:75] op_sel_hi:[1,0]
	v_pk_fma_f32 v[154:155], v[148:149], v[154:155], s[36:37] op_sel_hi:[1,1,0]
	v_exp_f32_e32 v156, v156
	v_pk_fma_f32 v[154:155], v[148:149], v[154:155], s[50:51] op_sel_hi:[1,1,0]
	v_exp_f32_e32 v157, v157
	v_pk_fma_f32 v[154:155], v[148:149], v[154:155], s[72:73] op_sel_hi:[1,1,0]
	s_nop 0
	v_pk_mul_f32 v[148:149], v[148:149], v[154:155]
	v_pk_mul_f32 v[154:155], v[124:125], v[124:125]
	s_nop 0
	v_pk_mul_f32 v[154:155], v[154:155], s[74:75] op_sel_hi:[1,0]
	s_nop 0
	v_exp_f32_e32 v154, v154
	v_exp_f32_e32 v155, v155
	s_nop 0
	v_pk_mul_f32 v[148:149], v[154:155], v[148:149]
	s_nop 0
	v_max_f32_e32 v240, 0, v124
	v_max_f32_e32 v241, 0, v125
	v_pk_fma_f32 v[154:155], v[248:249], v[148:149], v[240:241] neg_lo:[1,0,0] neg_hi:[1,0,0]
	s_nop 0
	v_and_b32_e32 v248, 0x7fffffff, v126
	s_nop 0
	v_and_b32_e32 v249, 0x7fffffff, v127
	v_pk_fma_f32 v[148:149], v[248:249], s[28:29], 1.0 op_sel_hi:[1,0,0]
	s_nop 0
	v_rcp_f32_e32 v148, v148
	v_rcp_f32_e32 v149, v149
	s_nop 0
	v_pk_fma_f32 v[158:159], v[148:149], s[30:31], v[152:153] op_sel_hi:[1,0,0]
	s_nop 0
	v_pk_fma_f32 v[158:159], v[148:149], v[158:159], s[36:37] op_sel_hi:[1,1,0]
	s_nop 0
	v_pk_fma_f32 v[158:159], v[148:149], v[158:159], s[50:51] op_sel_hi:[1,1,0]
	s_nop 0
	v_pk_fma_f32 v[158:159], v[148:149], v[158:159], s[72:73] op_sel_hi:[1,1,0]
	s_nop 0
	v_pk_mul_f32 v[148:149], v[148:149], v[158:159]
	s_nop 0
	v_pk_mul_f32 v[148:149], v[156:157], v[148:149]
	s_nop 0
	v_max_f32_e32 v240, 0, v126
	v_max_f32_e32 v241, 0, v127
	v_pk_fma_f32 v[156:157], v[248:249], v[148:149], v[240:241] neg_lo:[1,0,0] neg_hi:[1,0,0]
	s_nop 0
	v_and_b32_e32 v248, 0x7fffffff, v116
	s_nop 0
	v_and_b32_e32 v249, 0x7fffffff, v117
	v_pk_fma_f32 v[148:149], v[248:249], s[28:29], 1.0 op_sel_hi:[1,0,0]
	s_nop 0
	v_rcp_f32_e32 v148, v148
	v_rcp_f32_e32 v149, v149
	s_nop 0
	v_pk_fma_f32 v[158:159], v[148:149], s[30:31], v[152:153] op_sel_hi:[1,0,0]
	s_nop 0
	v_pk_fma_f32 v[158:159], v[148:149], v[158:159], s[36:37] op_sel_hi:[1,1,0]
	s_nop 0
	v_pk_fma_f32 v[158:159], v[148:149], v[158:159], s[50:51] op_sel_hi:[1,1,0]
	s_nop 0
	v_pk_fma_f32 v[158:159], v[148:149], v[158:159], s[72:73] op_sel_hi:[1,1,0]
	s_nop 0
	v_pk_mul_f32 v[148:149], v[148:149], v[158:159]
	v_pk_mul_f32 v[158:159], v[116:117], v[116:117]
	s_nop 0
	v_pk_mul_f32 v[158:159], v[158:159], s[74:75] op_sel_hi:[1,0]
	s_nop 0
	v_exp_f32_e32 v158, v158
	v_exp_f32_e32 v159, v159
	s_nop 0
	v_pk_mul_f32 v[148:149], v[158:159], v[148:149]
	s_nop 0
	v_max_f32_e32 v240, 0, v116
	v_max_f32_e32 v241, 0, v117
	v_pk_fma_f32 v[158:159], v[248:249], v[148:149], v[240:241] neg_lo:[1,0,0] neg_hi:[1,0,0]
	s_nop 0
	v_and_b32_e32 v248, 0x7fffffff, v118
	s_nop 0
	v_and_b32_e32 v249, 0x7fffffff, v119
	v_pk_fma_f32 v[148:149], v[248:249], s[28:29], 1.0 op_sel_hi:[1,0,0]
	s_nop 0
	v_rcp_f32_e32 v148, v148
	v_rcp_f32_e32 v149, v149
	s_nop 0
	v_pk_fma_f32 v[152:153], v[148:149], s[30:31], v[152:153] op_sel_hi:[1,0,0]
	s_nop 0
	v_pk_fma_f32 v[152:153], v[148:149], v[152:153], s[36:37] op_sel_hi:[1,1,0]
	s_nop 0
	v_pk_fma_f32 v[152:153], v[148:149], v[152:153], s[50:51] op_sel_hi:[1,1,0]
	s_nop 0
	v_pk_fma_f32 v[152:153], v[148:149], v[152:153], s[72:73] op_sel_hi:[1,1,0]
	s_nop 0
	v_pk_mul_f32 v[148:149], v[148:149], v[152:153]
	v_pk_mul_f32 v[152:153], v[160:161], s[74:75] op_sel_hi:[1,0]
	s_nop 0
	v_exp_f32_e32 v152, v152
	v_exp_f32_e32 v153, v153
	s_nop 0
	v_pk_mul_f32 v[148:149], v[152:153], v[148:149]
	s_nop 0
	v_max_f32_e32 v240, 0, v118
	v_max_f32_e32 v241, 0, v119
	v_pk_fma_f32 v[160:161], v[248:249], v[148:149], v[240:241] neg_lo:[1,0,0] neg_hi:[1,0,0]
	s_nop 0
	s_nop 1

; __device__ __forceinline__ f32x4 sigm4(f32x4 v) { return (f32x4){sigmoid_f(v[0]), sigmoid_f(v[1]), sigmoid_f(v[2]), sigmoid_f(v[3])}; }
; __device__ __forceinline__ f32x2 gelu_pk(f32x2 v) {
;     const f32x2 av = __builtin_elementwise_abs(v), d = av * 0.2316418882f + 1.0f;
;     f32x2 t; t.x = __builtin_amdgcn_rcpf(d.x); t.y = __builtin_amdgcn_rcpf(d.y);
;     f32x2 q = t * 0.5307027145f + (-0.7265760135f); q = q * t + 0.7107068705f; q = q * t + (-0.142248368f); q = q * t + 0.127414796f; q = q * t;
;     const f32x2 s = (v * v) * (-0.72134752044f);
;     f32x2 e; e.x = __builtin_amdgcn_exp2f(s.x); e.y = __builtin_amdgcn_exp2f(s.y);
;     const f32x2 m = v * (q * e), r = v - m;
;     f32x2 o; o.x = v.x < 0.f ? m.x : r.x; o.y = v.y < 0.f ? m.y : r.y; return o;
; }
; __device__ __forceinline__ f32x4 gelu4(f32x4 v) { f32x2 a = gelu_pk((f32x2){v[0], v[1]}), b = gelu_pk((f32x2){v[2], v[3]}); return (f32x4){a.x, a.y, b.x, b.y}; }
;     __device__ __forceinline__ void operator()(const f32x4 (&acc)[2][2][4][2], const pg8::Unit& u, int wr, int wc, int fr, int fq) const {
;     ...
;                     for (int bj = 0; bj < 2; ++bj) {
;                         f32x4 v0 = acc[ai][bj][m][0], v1 = acc[ai][bj][m][1];
;                         if (act == 5) { v0 = sigm4(v0); v1 = sigm4(v1);
;                             if (bj == 0) { const f32x4 b0 = sigm4(acc[ai][1][m][0]), b1 = sigm4(acc[ai][1][m][1]);
; #pragma unroll
;                                 for (int e = 0; e < 4; ++e) { v0[e] *= __builtin_amdgcn_rcpf(fmaxf(b0[e], 1e-20f)); v1[e] *= __builtin_amdgcn_rcpf(fmaxf(b1[e], 1e-20f)); } } }
;                         else if (act == 1) { v0 = gelu4(v0); v1 = gelu4(v1); }
.LBB0_209:
	s_andn2_b64 vcc, exec, s[16:17]
	s_cbranch_vccnz .LBB0_211
	v_and_b32_e32 v249, 0x7fffffff, v121
	v_and_b32_e32 v248, 0x7fffffff, v120
	v_pk_fma_f32 v[154:155], v[248:249], s[28:29], 1.0 op_sel_hi:[1,0,0]
	v_mov_b64_e32 v[160:161], s[34:35]
	v_rcp_f32_e32 v154, v154
	v_rcp_f32_e32 v155, v155
	v_pk_mul_f32 v[158:159], v[120:121], v[120:121]
	v_and_b32_e32 v251, 0x7fffffff, v123
	v_pk_mul_f32 v[158:159], v[158:159], s[74:75] op_sel_hi:[1,0]
	v_pk_fma_f32 v[156:157], v[154:155], s[30:31], v[160:161] op_sel_hi:[1,0,0]
	v_exp_f32_e32 v158, v158
	v_pk_fma_f32 v[156:157], v[154:155], v[156:157], s[36:37] op_sel_hi:[1,1,0]
	v_exp_f32_e32 v159, v159
	v_pk_fma_f32 v[156:157], v[154:155], v[156:157], s[50:51] op_sel_hi:[1,1,0]
	v_and_b32_e32 v250, 0x7fffffff, v122
	v_pk_fma_f32 v[156:157], v[154:155], v[156:157], s[72:73] op_sel_hi:[1,1,0]
	v_pk_fma_f32 v[168:169], v[250:251], s[28:29], 1.0 op_sel_hi:[1,0,0]
	v_pk_mul_f32 v[154:155], v[154:155], v[156:157]
	v_rcp_f32_e32 v168, v168
	v_rcp_f32_e32 v169, v169
	v_pk_mul_f32 v[154:155], v[158:159], v[154:155]
	v_max_f32_e32 v240, 0, v120
	v_max_f32_e32 v241, 0, v121
	v_pk_fma_f32 v[154:155], v[248:249], v[154:155], v[240:241] neg_lo:[1,0,0] neg_hi:[1,0,0]
	v_pk_mul_f32 v[156:157], v[122:123], v[122:123]
	s_nop 0
	v_pk_mul_f32 v[156:157], v[156:157], s[74:75] op_sel_hi:[1,0]
	v_and_b32_e32 v253, 0x7fffffff, v115
	v_pk_fma_f32 v[158:159], v[168:169], s[30:31], v[160:161] op_sel_hi:[1,0,0]
	v_exp_f32_e32 v156, v156
	v_pk_fma_f32 v[158:159], v[168:169], v[158:159], s[36:37] op_sel_hi:[1,1,0]
	v_exp_f32_e32 v157, v157
	v_pk_fma_f32 v[158:159], v[168:169], v[158:159], s[50:51] op_sel_hi:[1,1,0]
	s_nop 0
	v_pk_fma_f32 v[158:159], v[168:169], v[158:159], s[72:73] op_sel_hi:[1,1,0]
	v_and_b32_e32 v252, 0x7fffffff, v114
	v_pk_mul_f32 v[158:159], v[168:169], v[158:159]
	v_and_b32_e32 v249, 0x7fffffff, v113
	v_and_b32_e32 v248, 0x7fffffff, v112
	v_pk_fma_f32 v[168:169], v[248:249], s[28:29], 1.0 op_sel_hi:[1,0,0]
	v_pk_mul_f32 v[156:157], v[156:157], v[158:159]
	v_rcp_f32_e32 v168, v168
	v_rcp_f32_e32 v169, v169
	v_max_f32_e32 v240, 0, v122
	v_max_f32_e32 v241, 0, v123
	v_pk_fma_f32 v[156:157], v[250:251], v[156:157], v[240:241] neg_lo:[1,0,0] neg_hi:[1,0,0]
	v_pk_fma_f32 v[172:173], v[252:253], s[28:29], 1.0 op_sel_hi:[1,0,0]
	s_nop 0
	v_rcp_f32_e32 v172, v172
	v_rcp_f32_e32 v173, v173
	v_pk_fma_f32 v[158:159], v[168:169], s[30:31], v[160:161] op_sel_hi:[1,0,0]
	v_pk_mul_f32 v[170:171], v[112:113], v[112:113]
	v_pk_fma_f32 v[158:159], v[168:169], v[158:159], s[36:37] op_sel_hi:[1,1,0]
	v_pk_mul_f32 v[170:171], v[170:171], s[74:75] op_sel_hi:[1,0]
	v_pk_fma_f32 v[158:159], v[168:169], v[158:159], s[50:51] op_sel_hi:[1,1,0]
	v_exp_f32_e32 v170, v170
	v_pk_fma_f32 v[158:159], v[168:169], v[158:159], s[72:73] op_sel_hi:[1,1,0]
	v_exp_f32_e32 v171, v171
	v_pk_mul_f32 v[158:159], v[168:169], v[158:159]
	v_pk_mul_f32 v[168:169], v[114:115], v[114:115]
	v_pk_fma_f32 v[160:161], v[172:173], s[30:31], v[160:161] op_sel_hi:[1,0,0]
	v_pk_mul_f32 v[168:169], v[168:169], s[74:75] op_sel_hi:[1,0]
	v_pk_fma_f32 v[160:161], v[172:173], v[160:161], s[36:37] op_sel_hi:[1,1,0]
	v_exp_f32_e32 v168, v168
	v_exp_f32_e32 v169, v169
	v_pk_fma_f32 v[160:161], v[172:173], v[160:161], s[50:51] op_sel_hi:[1,1,0]
	v_pk_mul_f32 v[158:159], v[170:171], v[158:159]
	v_pk_fma_f32 v[160:161], v[172:173], v[160:161], s[72:73] op_sel_hi:[1,1,0]
	v_max_f32_e32 v240, 0, v112
	v_max_f32_e32 v241, 0, v113
	v_pk_fma_f32 v[158:159], v[248:249], v[158:159], v[240:241] neg_lo:[1,0,0] neg_hi:[1,0,0]
	v_pk_mul_f32 v[160:161], v[172:173], v[160:161]
	s_nop 0
	v_pk_mul_f32 v[160:161], v[168:169], v[160:161]
	s_nop 0
	v_max_f32_e32 v240, 0, v114
	v_max_f32_e32 v241, 0, v115
	v_pk_fma_f32 v[160:161], v[252:253], v[160:161], v[240:241] neg_lo:[1,0,0] neg_hi:[1,0,0]
	s_nop 1
	s_nop 1

; __device__ __forceinline__ f32x4 sigm4(f32x4 v) { return (f32x4){sigmoid_f(v[0]), sigmoid_f(v[1]), sigmoid_f(v[2]), sigmoid_f(v[3])}; }
; __device__ __forceinline__ f32x2 gelu_pk(f32x2 v) {
;     const f32x2 av = __builtin_elementwise_abs(v), d = av * 0.2316418882f + 1.0f;
;     f32x2 t; t.x = __builtin_amdgcn_rcpf(d.x); t.y = __builtin_amdgcn_rcpf(d.y);
;     f32x2 q = t * 0.5307027145f + (-0.7265760135f); q = q * t + 0.7107068705f; q = q * t + (-0.142248368f); q = q * t + 0.127414796f; q = q * t;
;     const f32x2 s = (v * v) * (-0.72134752044f);
;     f32x2 e; e.x = __builtin_amdgcn_exp2f(s.x); e.y = __builtin_amdgcn_exp2f(s.y);
;     const f32x2 m = v * (q * e), r = v - m;
;     f32x2 o; o.x = v.x < 0.f ? m.x : r.x; o.y = v.y < 0.f ? m.y : r.y; return o;
; }
; __device__ __forceinline__ f32x4 gelu4(f32x4 v) { f32x2 a = gelu_pk((f32x2){v[0], v[1]}), b = gelu_pk((f32x2){v[2], v[3]}); return (f32x4){a.x, a.y, b.x, b.y}; }
;     __device__ __forceinline__ void operator()(const f32x4 (&acc)[2][2][4][2], const pg8::Unit& u, int wr, int wc, int fr, int fq) const {
;     ...
;                     for (int bj = 0; bj < 2; ++bj) {
;                         f32x4 v0 = acc[ai][bj][m][0], v1 = acc[ai][bj][m][1];
;                         if (act == 5) { v0 = sigm4(v0); v1 = sigm4(v1);
;                             if (bj == 0) { const f32x4 b0 = sigm4(acc[ai][1][m][0]), b1 = sigm4(acc[ai][1][m][1]);
; #pragma unroll
;                                 for (int e = 0; e < 4; ++e) { v0[e] *= __builtin_amdgcn_rcpf(fmaxf(b0[e], 1e-20f)); v1[e] *= __builtin_amdgcn_rcpf(fmaxf(b1[e], 1e-20f)); } } }
;                         else if (act == 1) { v0 = gelu4(v0); v1 = gelu4(v1); }
.LBB0_223:
	s_andn2_b64 vcc, exec, s[16:17]
	s_cbranch_vccnz .LBB0_225
	v_and_b32_e32 v249, 0x7fffffff, v109
	v_and_b32_e32 v248, 0x7fffffff, v108
	v_pk_fma_f32 v[152:153], v[248:249], s[28:29], 1.0 op_sel_hi:[1,0,0]
	v_mov_b64_e32 v[160:161], s[34:35]
	v_rcp_f32_e32 v152, v152
	v_rcp_f32_e32 v153, v153
	v_pk_mul_f32 v[156:157], v[108:109], v[108:109]
	s_nop 0
	v_pk_mul_f32 v[156:157], v[156:157], s[74:75] op_sel_hi:[1,0]
	v_pk_fma_f32 v[154:155], v[152:153], s[30:31], v[160:161] op_sel_hi:[1,0,0]
	v_exp_f32_e32 v156, v156
	v_pk_fma_f32 v[154:155], v[152:153], v[154:155], s[36:37] op_sel_hi:[1,1,0]
	v_exp_f32_e32 v157, v157
	v_pk_fma_f32 v[154:155], v[152:153], v[154:155], s[50:51] op_sel_hi:[1,1,0]
	v_pk_mul_f32 v[158:159], v[110:111], v[110:111]
	v_pk_fma_f32 v[154:155], v[152:153], v[154:155], s[72:73] op_sel_hi:[1,1,0]
	v_pk_mul_f32 v[158:159], v[158:159], s[74:75] op_sel_hi:[1,0]
	v_pk_mul_f32 v[152:153], v[152:153], v[154:155]
	v_exp_f32_e32 v158, v158
	v_pk_mul_f32 v[152:153], v[156:157], v[152:153]
	v_and_b32_e32 v251, 0x7fffffff, v111
	v_and_b32_e32 v250, 0x7fffffff, v110
	v_pk_fma_f32 v[156:157], v[250:251], s[28:29], 1.0 op_sel_hi:[1,0,0]
	s_nop 0
	v_rcp_f32_e32 v156, v156
	v_rcp_f32_e32 v157, v157
	v_max_f32_e32 v240, 0, v108
	v_max_f32_e32 v241, 0, v109
	v_pk_fma_f32 v[154:155], v[248:249], v[152:153], v[240:241] neg_lo:[1,0,0] neg_hi:[1,0,0]
	v_exp_f32_e32 v159, v159
	v_pk_mul_f32 v[168:169], v[100:101], v[100:101]
	v_pk_mul_f32 v[170:171], v[102:103], v[102:103]
	v_pk_fma_f32 v[152:153], v[156:157], s[30:31], v[160:161] op_sel_hi:[1,0,0]
	s_nop 0
	v_pk_fma_f32 v[152:153], v[156:157], v[152:153], s[36:37] op_sel_hi:[1,1,0]
	v_pk_mul_f32 v[168:169], v[168:169], s[74:75] op_sel_hi:[1,0]
	v_pk_fma_f32 v[152:153], v[156:157], v[152:153], s[50:51] op_sel_hi:[1,1,0]
	v_exp_f32_e32 v168, v168
	v_pk_fma_f32 v[152:153], v[156:157], v[152:153], s[72:73] op_sel_hi:[1,1,0]
	v_exp_f32_e32 v169, v169
	v_pk_mul_f32 v[152:153], v[156:157], v[152:153]
	s_nop 0
	v_pk_mul_f32 v[152:153], v[158:159], v[152:153]
	v_and_b32_e32 v249, 0x7fffffff, v101
	v_and_b32_e32 v248, 0x7fffffff, v100
	v_pk_fma_f32 v[158:159], v[248:249], s[28:29], 1.0 op_sel_hi:[1,0,0]
	s_nop 0
	v_rcp_f32_e32 v158, v158
	v_rcp_f32_e32 v159, v159
	v_max_f32_e32 v240, 0, v110
	v_max_f32_e32 v241, 0, v111
	v_pk_fma_f32 v[156:157], v[250:251], v[152:153], v[240:241] neg_lo:[1,0,0] neg_hi:[1,0,0]
	s_nop 0
	s_nop 1
	v_pk_fma_f32 v[152:153], v[158:159], s[30:31], v[160:161] op_sel_hi:[1,0,0]
	s_nop 0
	v_pk_fma_f32 v[152:153], v[158:159], v[152:153], s[36:37] op_sel_hi:[1,1,0]
	s_nop 0
	v_pk_fma_f32 v[152:153], v[158:159], v[152:153], s[50:51] op_sel_hi:[1,1,0]
	s_nop 0
	v_pk_fma_f32 v[152:153], v[158:159], v[152:153], s[72:73] op_sel_hi:[1,1,0]
	s_nop 0
	v_pk_mul_f32 v[152:153], v[158:159], v[152:153]
	s_nop 0
	v_pk_mul_f32 v[152:153], v[168:169], v[152:153]
	v_and_b32_e32 v251, 0x7fffffff, v103
	v_and_b32_e32 v250, 0x7fffffff, v102
	v_pk_fma_f32 v[168:169], v[250:251], s[28:29], 1.0 op_sel_hi:[1,0,0]
	s_nop 0
	v_rcp_f32_e32 v168, v168
	v_rcp_f32_e32 v169, v169
	v_max_f32_e32 v240, 0, v100
	v_max_f32_e32 v241, 0, v101
	v_pk_fma_f32 v[158:159], v[248:249], v[152:153], v[240:241] neg_lo:[1,0,0] neg_hi:[1,0,0]
	s_nop 0
	s_nop 1
	v_pk_fma_f32 v[152:153], v[168:169], s[30:31], v[160:161] op_sel_hi:[1,0,0]
	v_pk_mul_f32 v[160:161], v[170:171], s[74:75] op_sel_hi:[1,0]
	v_pk_fma_f32 v[152:153], v[168:169], v[152:153], s[36:37] op_sel_hi:[1,1,0]
	v_exp_f32_e32 v160, v160
	v_exp_f32_e32 v161, v161
	v_pk_fma_f32 v[152:153], v[168:169], v[152:153], s[50:51] op_sel_hi:[1,1,0]
	s_nop 0
	v_pk_fma_f32 v[152:153], v[168:169], v[152:153], s[72:73] op_sel_hi:[1,1,0]
	s_nop 0
	v_pk_mul_f32 v[152:153], v[168:169], v[152:153]
	s_nop 0
	v_pk_mul_f32 v[152:153], v[160:161], v[152:153]
	s_nop 0
	v_max_f32_e32 v240, 0, v102
	v_max_f32_e32 v241, 0, v103
	v_pk_fma_f32 v[160:161], v[250:251], v[152:153], v[240:241] neg_lo:[1,0,0] neg_hi:[1,0,0]
	s_nop 0
	s_nop 1

; __device__ __forceinline__ f32x4 sigm4(f32x4 v) { return (f32x4){sigmoid_f(v[0]), sigmoid_f(v[1]), sigmoid_f(v[2]), sigmoid_f(v[3])}; }
; __device__ __forceinline__ f32x2 gelu_pk(f32x2 v) {
;     const f32x2 av = __builtin_elementwise_abs(v), d = av * 0.2316418882f + 1.0f;
;     f32x2 t; t.x = __builtin_amdgcn_rcpf(d.x); t.y = __builtin_amdgcn_rcpf(d.y);
;     f32x2 q = t * 0.5307027145f + (-0.7265760135f); q = q * t + 0.7107068705f; q = q * t + (-0.142248368f); q = q * t + 0.127414796f; q = q * t;
;     const f32x2 s = (v * v) * (-0.72134752044f);
;     f32x2 e; e.x = __builtin_amdgcn_exp2f(s.x); e.y = __builtin_amdgcn_exp2f(s.y);
;     const f32x2 m = v * (q * e), r = v - m;
;     f32x2 o; o.x = v.x < 0.f ? m.x : r.x; o.y = v.y < 0.f ? m.y : r.y; return o;
; }
; __device__ __forceinline__ f32x4 gelu4(f32x4 v) { f32x2 a = gelu_pk((f32x2){v[0], v[1]}), b = gelu_pk((f32x2){v[2], v[3]}); return (f32x4){a.x, a.y, b.x, b.y}; }
;     __device__ __forceinline__ void operator()(const f32x4 (&acc)[2][2][4][2], const pg8::Unit& u, int wr, int wc, int fr, int fq) const {
;     ...
;                     for (int bj = 0; bj < 2; ++bj) {
;                         f32x4 v0 = acc[ai][bj][m][0], v1 = acc[ai][bj][m][1];
;                         if (act == 5) { v0 = sigm4(v0); v1 = sigm4(v1);
;                             if (bj == 0) { const f32x4 b0 = sigm4(acc[ai][1][m][0]), b1 = sigm4(acc[ai][1][m][1]);
; #pragma unroll
;                                 for (int e = 0; e < 4; ++e) { v0[e] *= __builtin_amdgcn_rcpf(fmaxf(b0[e], 1e-20f)); v1[e] *= __builtin_amdgcn_rcpf(fmaxf(b1[e], 1e-20f)); } } }
;                         else if (act == 1) { v0 = gelu4(v0); v1 = gelu4(v1); }
.LBB0_237:
	s_andn2_b64 vcc, exec, s[16:17]
	s_cbranch_vccnz .LBB0_239
	v_and_b32_e32 v249, 0x7fffffff, v105
	v_and_b32_e32 v248, 0x7fffffff, v104
	v_pk_fma_f32 v[154:155], v[248:249], s[28:29], 1.0 op_sel_hi:[1,0,0]
	v_mov_b64_e32 v[160:161], s[34:35]
	v_rcp_f32_e32 v154, v154
	v_rcp_f32_e32 v155, v155
	v_pk_mul_f32 v[158:159], v[104:105], v[104:105]
	v_and_b32_e32 v251, 0x7fffffff, v107
	v_pk_mul_f32 v[158:159], v[158:159], s[74:75] op_sel_hi:[1,0]
	v_pk_fma_f32 v[156:157], v[154:155], s[30:31], v[160:161] op_sel_hi:[1,0,0]
	v_exp_f32_e32 v158, v158
	v_pk_fma_f32 v[156:157], v[154:155], v[156:157], s[36:37] op_sel_hi:[1,1,0]
	v_exp_f32_e32 v159, v159
	v_pk_fma_f32 v[156:157], v[154:155], v[156:157], s[50:51] op_sel_hi:[1,1,0]
	v_and_b32_e32 v250, 0x7fffffff, v106
	v_pk_fma_f32 v[156:157], v[154:155], v[156:157], s[72:73] op_sel_hi:[1,1,0]
	v_pk_fma_f32 v[168:169], v[250:251], s[28:29], 1.0 op_sel_hi:[1,0,0]
	v_pk_mul_f32 v[154:155], v[154:155], v[156:157]
	v_rcp_f32_e32 v168, v168
	v_rcp_f32_e32 v169, v169
	v_pk_mul_f32 v[154:155], v[158:159], v[154:155]
	v_max_f32_e32 v240, 0, v104
	v_max_f32_e32 v241, 0, v105
	v_pk_fma_f32 v[154:155], v[248:249], v[154:155], v[240:241] neg_lo:[1,0,0] neg_hi:[1,0,0]
	v_pk_mul_f32 v[156:157], v[106:107], v[106:107]
	s_nop 0
	v_pk_mul_f32 v[156:157], v[156:157], s[74:75] op_sel_hi:[1,0]
	v_and_b32_e32 v253, 0x7fffffff, v99
	v_pk_fma_f32 v[158:159], v[168:169], s[30:31], v[160:161] op_sel_hi:[1,0,0]
	v_exp_f32_e32 v156, v156
	v_pk_fma_f32 v[158:159], v[168:169], v[158:159], s[36:37] op_sel_hi:[1,1,0]
	v_exp_f32_e32 v157, v157
	v_pk_fma_f32 v[158:159], v[168:169], v[158:159], s[50:51] op_sel_hi:[1,1,0]
	s_nop 0
	v_pk_fma_f32 v[158:159], v[168:169], v[158:159], s[72:73] op_sel_hi:[1,1,0]
	v_and_b32_e32 v252, 0x7fffffff, v98
	v_pk_mul_f32 v[158:159], v[168:169], v[158:159]
	v_and_b32_e32 v249, 0x7fffffff, v97
	v_and_b32_e32 v248, 0x7fffffff, v96
	v_pk_fma_f32 v[168:169], v[248:249], s[28:29], 1.0 op_sel_hi:[1,0,0]
	v_pk_mul_f32 v[156:157], v[156:157], v[158:159]
	v_rcp_f32_e32 v168, v168
	v_rcp_f32_e32 v169, v169
	v_max_f32_e32 v240, 0, v106
	v_max_f32_e32 v241, 0, v107
	v_pk_fma_f32 v[156:157], v[250:251], v[156:157], v[240:241] neg_lo:[1,0,0] neg_hi:[1,0,0]
	v_pk_fma_f32 v[172:173], v[252:253], s[28:29], 1.0 op_sel_hi:[1,0,0]
	s_nop 0
	v_rcp_f32_e32 v172, v172
	v_rcp_f32_e32 v173, v173
	v_pk_fma_f32 v[158:159], v[168:169], s[30:31], v[160:161] op_sel_hi:[1,0,0]
	v_pk_mul_f32 v[170:171], v[96:97], v[96:97]
	v_pk_fma_f32 v[158:159], v[168:169], v[158:159], s[36:37] op_sel_hi:[1,1,0]
	v_pk_mul_f32 v[170:171], v[170:171], s[74:75] op_sel_hi:[1,0]
	v_pk_fma_f32 v[158:159], v[168:169], v[158:159], s[50:51] op_sel_hi:[1,1,0]
	v_exp_f32_e32 v170, v170
	v_pk_fma_f32 v[158:159], v[168:169], v[158:159], s[72:73] op_sel_hi:[1,1,0]
	v_exp_f32_e32 v171, v171
	v_pk_mul_f32 v[158:159], v[168:169], v[158:159]
	v_pk_mul_f32 v[168:169], v[98:99], v[98:99]
	v_pk_fma_f32 v[160:161], v[172:173], s[30:31], v[160:161] op_sel_hi:[1,0,0]
	v_pk_mul_f32 v[168:169], v[168:169], s[74:75] op_sel_hi:[1,0]
	v_pk_fma_f32 v[160:161], v[172:173], v[160:161], s[36:37] op_sel_hi:[1,1,0]
	v_exp_f32_e32 v168, v168
	v_exp_f32_e32 v169, v169
	v_pk_fma_f32 v[160:161], v[172:173], v[160:161], s[50:51] op_sel_hi:[1,1,0]
	v_pk_mul_f32 v[158:159], v[170:171], v[158:159]
	v_pk_fma_f32 v[160:161], v[172:173], v[160:161], s[72:73] op_sel_hi:[1,1,0]
	v_max_f32_e32 v240, 0, v96
	v_max_f32_e32 v241, 0, v97
	v_pk_fma_f32 v[158:159], v[248:249], v[158:159], v[240:241] neg_lo:[1,0,0] neg_hi:[1,0,0]
	v_pk_mul_f32 v[160:161], v[172:173], v[160:161]
	s_nop 0
	v_pk_mul_f32 v[160:161], v[168:169], v[160:161]
	s_nop 0
	v_max_f32_e32 v240, 0, v98
	v_max_f32_e32 v241, 0, v99
	v_pk_fma_f32 v[160:161], v[252:253], v[160:161], v[240:241] neg_lo:[1,0,0] neg_hi:[1,0,0]
	s_nop 1
	s_nop 1

; __device__ __forceinline__ f32x4 sigm4(f32x4 v) { return (f32x4){sigmoid_f(v[0]), sigmoid_f(v[1]), sigmoid_f(v[2]), sigmoid_f(v[3])}; }
; __device__ __forceinline__ f32x2 gelu_pk(f32x2 v) {
;     const f32x2 av = __builtin_elementwise_abs(v), d = av * 0.2316418882f + 1.0f;
;     f32x2 t; t.x = __builtin_amdgcn_rcpf(d.x); t.y = __builtin_amdgcn_rcpf(d.y);
;     f32x2 q = t * 0.5307027145f + (-0.7265760135f); q = q * t + 0.7107068705f; q = q * t + (-0.142248368f); q = q * t + 0.127414796f; q = q * t;
;     const f32x2 s = (v * v) * (-0.72134752044f);
;     f32x2 e; e.x = __builtin_amdgcn_exp2f(s.x); e.y = __builtin_amdgcn_exp2f(s.y);
;     const f32x2 m = v * (q * e), r = v - m;
;     f32x2 o; o.x = v.x < 0.f ? m.x : r.x; o.y = v.y < 0.f ? m.y : r.y; return o;
; }
; __device__ __forceinline__ f32x4 gelu4(f32x4 v) { f32x2 a = gelu_pk((f32x2){v[0], v[1]}), b = gelu_pk((f32x2){v[2], v[3]}); return (f32x4){a.x, a.y, b.x, b.y}; }
;     __device__ __forceinline__ void operator()(const f32x4 (&acc)[2][2][4][2], const pg8::Unit& u, int wr, int wc, int fr, int fq) const {
;     ...
;                     for (int bj = 0; bj < 2; ++bj) {
;                         f32x4 v0 = acc[ai][bj][m][0], v1 = acc[ai][bj][m][1];
;                         if (act == 5) { v0 = sigm4(v0); v1 = sigm4(v1);
;                             if (bj == 0) { const f32x4 b0 = sigm4(acc[ai][1][m][0]), b1 = sigm4(acc[ai][1][m][1]);
; #pragma unroll
;                                 for (int e = 0; e < 4; ++e) { v0[e] *= __builtin_amdgcn_rcpf(fmaxf(b0[e], 1e-20f)); v1[e] *= __builtin_amdgcn_rcpf(fmaxf(b1[e], 1e-20f)); } } }
;                         else if (act == 1) { v0 = gelu4(v0); v1 = gelu4(v1); }
.LBB0_251:
	s_andn2_b64 vcc, exec, s[16:17]
	s_cbranch_vccnz .LBB0_253
	v_and_b32_e32 v249, 0x7fffffff, v93
	v_and_b32_e32 v248, 0x7fffffff, v92
	v_pk_fma_f32 v[152:153], v[248:249], s[28:29], 1.0 op_sel_hi:[1,0,0]
	v_mov_b64_e32 v[160:161], s[34:35]
	v_rcp_f32_e32 v152, v152
	v_rcp_f32_e32 v153, v153
	v_pk_mul_f32 v[156:157], v[92:93], v[92:93]
	s_nop 0
	v_pk_mul_f32 v[156:157], v[156:157], s[74:75] op_sel_hi:[1,0]
	v_pk_fma_f32 v[154:155], v[152:153], s[30:31], v[160:161] op_sel_hi:[1,0,0]
	v_exp_f32_e32 v156, v156
	v_pk_fma_f32 v[154:155], v[152:153], v[154:155], s[36:37] op_sel_hi:[1,1,0]
	v_exp_f32_e32 v157, v157
	v_pk_fma_f32 v[154:155], v[152:153], v[154:155], s[50:51] op_sel_hi:[1,1,0]
	v_pk_mul_f32 v[158:159], v[94:95], v[94:95]
	v_pk_fma_f32 v[154:155], v[152:153], v[154:155], s[72:73] op_sel_hi:[1,1,0]
	v_pk_mul_f32 v[158:159], v[158:159], s[74:75] op_sel_hi:[1,0]
	v_pk_mul_f32 v[152:153], v[152:153], v[154:155]
	v_exp_f32_e32 v158, v158
	v_pk_mul_f32 v[152:153], v[156:157], v[152:153]
	v_and_b32_e32 v251, 0x7fffffff, v95
	v_and_b32_e32 v250, 0x7fffffff, v94
	v_pk_fma_f32 v[156:157], v[250:251], s[28:29], 1.0 op_sel_hi:[1,0,0]
	s_nop 0
	v_rcp_f32_e32 v156, v156
	v_rcp_f32_e32 v157, v157
	v_max_f32_e32 v240, 0, v92
	v_max_f32_e32 v241, 0, v93
	v_pk_fma_f32 v[154:155], v[248:249], v[152:153], v[240:241] neg_lo:[1,0,0] neg_hi:[1,0,0]
	v_exp_f32_e32 v159, v159
	v_pk_mul_f32 v[168:169], v[84:85], v[84:85]
	v_pk_mul_f32 v[170:171], v[86:87], v[86:87]
	v_pk_fma_f32 v[152:153], v[156:157], s[30:31], v[160:161] op_sel_hi:[1,0,0]
	s_nop 0
	v_pk_fma_f32 v[152:153], v[156:157], v[152:153], s[36:37] op_sel_hi:[1,1,0]
	v_pk_mul_f32 v[168:169], v[168:169], s[74:75] op_sel_hi:[1,0]
	v_pk_fma_f32 v[152:153], v[156:157], v[152:153], s[50:51] op_sel_hi:[1,1,0]
	v_exp_f32_e32 v168, v168
	v_pk_fma_f32 v[152:153], v[156:157], v[152:153], s[72:73] op_sel_hi:[1,1,0]
	v_exp_f32_e32 v169, v169
	v_pk_mul_f32 v[152:153], v[156:157], v[152:153]
	s_nop 0
	v_pk_mul_f32 v[152:153], v[158:159], v[152:153]
	v_and_b32_e32 v249, 0x7fffffff, v85
	v_and_b32_e32 v248, 0x7fffffff, v84
	v_pk_fma_f32 v[158:159], v[248:249], s[28:29], 1.0 op_sel_hi:[1,0,0]
	s_nop 0
	v_rcp_f32_e32 v158, v158
	v_rcp_f32_e32 v159, v159
	v_max_f32_e32 v240, 0, v94
	v_max_f32_e32 v241, 0, v95
	v_pk_fma_f32 v[156:157], v[250:251], v[152:153], v[240:241] neg_lo:[1,0,0] neg_hi:[1,0,0]
	s_nop 0
	s_nop 1
	v_pk_fma_f32 v[152:153], v[158:159], s[30:31], v[160:161] op_sel_hi:[1,0,0]
	s_nop 0
	v_pk_fma_f32 v[152:153], v[158:159], v[152:153], s[36:37] op_sel_hi:[1,1,0]
	s_nop 0
	v_pk_fma_f32 v[152:153], v[158:159], v[152:153], s[50:51] op_sel_hi:[1,1,0]
	s_nop 0
	v_pk_fma_f32 v[152:153], v[158:159], v[152:153], s[72:73] op_sel_hi:[1,1,0]
	s_nop 0
	v_pk_mul_f32 v[152:153], v[158:159], v[152:153]
	s_nop 0
	v_pk_mul_f32 v[152:153], v[168:169], v[152:153]
	v_and_b32_e32 v251, 0x7fffffff, v87
	v_and_b32_e32 v250, 0x7fffffff, v86
	v_pk_fma_f32 v[168:169], v[250:251], s[28:29], 1.0 op_sel_hi:[1,0,0]
	s_nop 0
	v_rcp_f32_e32 v168, v168
	v_rcp_f32_e32 v169, v169
	v_max_f32_e32 v240, 0, v84
	v_max_f32_e32 v241, 0, v85
	v_pk_fma_f32 v[158:159], v[248:249], v[152:153], v[240:241] neg_lo:[1,0,0] neg_hi:[1,0,0]
	s_nop 0
	s_nop 1
	v_pk_fma_f32 v[152:153], v[168:169], s[30:31], v[160:161] op_sel_hi:[1,0,0]
	v_pk_mul_f32 v[160:161], v[170:171], s[74:75] op_sel_hi:[1,0]
	v_pk_fma_f32 v[152:153], v[168:169], v[152:153], s[36:37] op_sel_hi:[1,1,0]
	v_exp_f32_e32 v160, v160
	v_exp_f32_e32 v161, v161
	v_pk_fma_f32 v[152:153], v[168:169], v[152:153], s[50:51] op_sel_hi:[1,1,0]
	s_nop 0
	v_pk_fma_f32 v[152:153], v[168:169], v[152:153], s[72:73] op_sel_hi:[1,1,0]
	s_nop 0
	v_pk_mul_f32 v[152:153], v[168:169], v[152:153]
	s_nop 0
	v_pk_mul_f32 v[152:153], v[160:161], v[152:153]
	s_nop 0
	v_max_f32_e32 v240, 0, v86
	v_max_f32_e32 v241, 0, v87
	v_pk_fma_f32 v[160:161], v[250:251], v[152:153], v[240:241] neg_lo:[1,0,0] neg_hi:[1,0,0]
	s_nop 0
	s_nop 1

; __device__ __forceinline__ f32x4 sigm4(f32x4 v) { return (f32x4){sigmoid_f(v[0]), sigmoid_f(v[1]), sigmoid_f(v[2]), sigmoid_f(v[3])}; }
; __device__ __forceinline__ f32x2 gelu_pk(f32x2 v) {
;     const f32x2 av = __builtin_elementwise_abs(v), d = av * 0.2316418882f + 1.0f;
;     f32x2 t; t.x = __builtin_amdgcn_rcpf(d.x); t.y = __builtin_amdgcn_rcpf(d.y);
;     f32x2 q = t * 0.5307027145f + (-0.7265760135f); q = q * t + 0.7107068705f; q = q * t + (-0.142248368f); q = q * t + 0.127414796f; q = q * t;
;     const f32x2 s = (v * v) * (-0.72134752044f);
;     f32x2 e; e.x = __builtin_amdgcn_exp2f(s.x); e.y = __builtin_amdgcn_exp2f(s.y);
;     const f32x2 m = v * (q * e), r = v - m;
;     f32x2 o; o.x = v.x < 0.f ? m.x : r.x; o.y = v.y < 0.f ? m.y : r.y; return o;
; }
; __device__ __forceinline__ f32x4 gelu4(f32x4 v) { f32x2 a = gelu_pk((f32x2){v[0], v[1]}), b = gelu_pk((f32x2){v[2], v[3]}); return (f32x4){a.x, a.y, b.x, b.y}; }
;     __device__ __forceinline__ void operator()(const f32x4 (&acc)[2][2][4][2], const pg8::Unit& u, int wr, int wc, int fr, int fq) const {
;     ...
;                     for (int bj = 0; bj < 2; ++bj) {
;                         f32x4 v0 = acc[ai][bj][m][0], v1 = acc[ai][bj][m][1];
;                         if (act == 5) { v0 = sigm4(v0); v1 = sigm4(v1);
;                             if (bj == 0) { const f32x4 b0 = sigm4(acc[ai][1][m][0]), b1 = sigm4(acc[ai][1][m][1]);
; #pragma unroll
;                                 for (int e = 0; e < 4; ++e) { v0[e] *= __builtin_amdgcn_rcpf(fmaxf(b0[e], 1e-20f)); v1[e] *= __builtin_amdgcn_rcpf(fmaxf(b1[e], 1e-20f)); } } }
;                         else if (act == 1) { v0 = gelu4(v0); v1 = gelu4(v1); }
.LBB0_265:
	s_andn2_b64 vcc, exec, s[16:17]
	s_cbranch_vccnz .LBB0_267
	v_and_b32_e32 v249, 0x7fffffff, v89
	v_and_b32_e32 v248, 0x7fffffff, v88
	v_pk_fma_f32 v[154:155], v[248:249], s[28:29], 1.0 op_sel_hi:[1,0,0]
	v_mov_b64_e32 v[160:161], s[34:35]
	v_rcp_f32_e32 v154, v154
	v_rcp_f32_e32 v155, v155
	v_pk_mul_f32 v[158:159], v[88:89], v[88:89]
	v_and_b32_e32 v251, 0x7fffffff, v91
	v_pk_mul_f32 v[158:159], v[158:159], s[74:75] op_sel_hi:[1,0]
	v_pk_fma_f32 v[156:157], v[154:155], s[30:31], v[160:161] op_sel_hi:[1,0,0]
	v_exp_f32_e32 v158, v158
	v_pk_fma_f32 v[156:157], v[154:155], v[156:157], s[36:37] op_sel_hi:[1,1,0]
	v_exp_f32_e32 v159, v159
	v_pk_fma_f32 v[156:157], v[154:155], v[156:157], s[50:51] op_sel_hi:[1,1,0]
	v_and_b32_e32 v250, 0x7fffffff, v90
	v_pk_fma_f32 v[156:157], v[154:155], v[156:157], s[72:73] op_sel_hi:[1,1,0]
	v_pk_fma_f32 v[168:169], v[250:251], s[28:29], 1.0 op_sel_hi:[1,0,0]
	v_pk_mul_f32 v[154:155], v[154:155], v[156:157]
	v_rcp_f32_e32 v168, v168
	v_rcp_f32_e32 v169, v169
	v_pk_mul_f32 v[154:155], v[158:159], v[154:155]
	v_max_f32_e32 v240, 0, v88
	v_max_f32_e32 v241, 0, v89
	v_pk_fma_f32 v[154:155], v[248:249], v[154:155], v[240:241] neg_lo:[1,0,0] neg_hi:[1,0,0]
	v_pk_mul_f32 v[156:157], v[90:91], v[90:91]
	s_nop 0
	v_pk_mul_f32 v[156:157], v[156:157], s[74:75] op_sel_hi:[1,0]
	v_and_b32_e32 v253, 0x7fffffff, v83
	v_pk_fma_f32 v[158:159], v[168:169], s[30:31], v[160:161] op_sel_hi:[1,0,0]
	v_exp_f32_e32 v156, v156
	v_pk_fma_f32 v[158:159], v[168:169], v[158:159], s[36:37] op_sel_hi:[1,1,0]
	v_exp_f32_e32 v157, v157
	v_pk_fma_f32 v[158:159], v[168:169], v[158:159], s[50:51] op_sel_hi:[1,1,0]
	s_nop 0
	v_pk_fma_f32 v[158:159], v[168:169], v[158:159], s[72:73] op_sel_hi:[1,1,0]
	v_and_b32_e32 v252, 0x7fffffff, v82
	v_pk_mul_f32 v[158:159], v[168:169], v[158:159]
	v_and_b32_e32 v249, 0x7fffffff, v81
	v_and_b32_e32 v248, 0x7fffffff, v80
	v_pk_fma_f32 v[168:169], v[248:249], s[28:29], 1.0 op_sel_hi:[1,0,0]
	v_pk_mul_f32 v[156:157], v[156:157], v[158:159]
	v_rcp_f32_e32 v168, v168
	v_rcp_f32_e32 v169, v169
	v_max_f32_e32 v240, 0, v90
	v_max_f32_e32 v241, 0, v91
	v_pk_fma_f32 v[156:157], v[250:251], v[156:157], v[240:241] neg_lo:[1,0,0] neg_hi:[1,0,0]
	v_pk_fma_f32 v[172:173], v[252:253], s[28:29], 1.0 op_sel_hi:[1,0,0]
	s_nop 0
	v_rcp_f32_e32 v172, v172
	v_rcp_f32_e32 v173, v173
	v_pk_fma_f32 v[158:159], v[168:169], s[30:31], v[160:161] op_sel_hi:[1,0,0]
	v_pk_mul_f32 v[170:171], v[80:81], v[80:81]
	v_pk_fma_f32 v[158:159], v[168:169], v[158:159], s[36:37] op_sel_hi:[1,1,0]
	v_pk_mul_f32 v[170:171], v[170:171], s[74:75] op_sel_hi:[1,0]
	v_pk_fma_f32 v[158:159], v[168:169], v[158:159], s[50:51] op_sel_hi:[1,1,0]
	v_exp_f32_e32 v170, v170
	v_pk_fma_f32 v[158:159], v[168:169], v[158:159], s[72:73] op_sel_hi:[1,1,0]
	v_exp_f32_e32 v171, v171
	v_pk_mul_f32 v[158:159], v[168:169], v[158:159]
	v_pk_mul_f32 v[168:169], v[82:83], v[82:83]
	v_pk_fma_f32 v[160:161], v[172:173], s[30:31], v[160:161] op_sel_hi:[1,0,0]
	v_pk_mul_f32 v[168:169], v[168:169], s[74:75] op_sel_hi:[1,0]
	v_pk_fma_f32 v[160:161], v[172:173], v[160:161], s[36:37] op_sel_hi:[1,1,0]
	v_exp_f32_e32 v168, v168
	v_exp_f32_e32 v169, v169
	v_pk_fma_f32 v[160:161], v[172:173], v[160:161], s[50:51] op_sel_hi:[1,1,0]
	v_pk_mul_f32 v[158:159], v[170:171], v[158:159]
	v_pk_fma_f32 v[160:161], v[172:173], v[160:161], s[72:73] op_sel_hi:[1,1,0]
	v_max_f32_e32 v240, 0, v80
	v_max_f32_e32 v241, 0, v81
	v_pk_fma_f32 v[158:159], v[248:249], v[158:159], v[240:241] neg_lo:[1,0,0] neg_hi:[1,0,0]
	v_pk_mul_f32 v[160:161], v[172:173], v[160:161]
	s_nop 0
	v_pk_mul_f32 v[160:161], v[168:169], v[160:161]
	s_nop 0
	v_max_f32_e32 v240, 0, v82
	v_max_f32_e32 v241, 0, v83
	v_pk_fma_f32 v[160:161], v[252:253], v[160:161], v[240:241] neg_lo:[1,0,0] neg_hi:[1,0,0]
	s_nop 1
	s_nop 1

; __device__ __forceinline__ f32x4 sigm4(f32x4 v) { return (f32x4){sigmoid_f(v[0]), sigmoid_f(v[1]), sigmoid_f(v[2]), sigmoid_f(v[3])}; }
; __device__ __forceinline__ f32x2 gelu_pk(f32x2 v) {
;     const f32x2 av = __builtin_elementwise_abs(v), d = av * 0.2316418882f + 1.0f;
;     f32x2 t; t.x = __builtin_amdgcn_rcpf(d.x); t.y = __builtin_amdgcn_rcpf(d.y);
;     f32x2 q = t * 0.5307027145f + (-0.7265760135f); q = q * t + 0.7107068705f; q = q * t + (-0.142248368f); q = q * t + 0.127414796f; q = q * t;
;     const f32x2 s = (v * v) * (-0.72134752044f);
;     f32x2 e; e.x = __builtin_amdgcn_exp2f(s.x); e.y = __builtin_amdgcn_exp2f(s.y);
;     const f32x2 m = v * (q * e), r = v - m;
;     f32x2 o; o.x = v.x < 0.f ? m.x : r.x; o.y = v.y < 0.f ? m.y : r.y; return o;
; }
; __device__ __forceinline__ f32x4 gelu4(f32x4 v) { f32x2 a = gelu_pk((f32x2){v[0], v[1]}), b = gelu_pk((f32x2){v[2], v[3]}); return (f32x4){a.x, a.y, b.x, b.y}; }
;     __device__ __forceinline__ void operator()(const f32x4 (&acc)[2][2][4][2], const pg8::Unit& u, int wr, int wc, int fr, int fq) const {
;     ...
;                     for (int bj = 0; bj < 2; ++bj) {
;                         f32x4 v0 = acc[ai][bj][m][0], v1 = acc[ai][bj][m][1];
;                         if (act == 5) { v0 = sigm4(v0); v1 = sigm4(v1);
;                             if (bj == 0) { const f32x4 b0 = sigm4(acc[ai][1][m][0]), b1 = sigm4(acc[ai][1][m][1]);
; #pragma unroll
;                                 for (int e = 0; e < 4; ++e) { v0[e] *= __builtin_amdgcn_rcpf(fmaxf(b0[e], 1e-20f)); v1[e] *= __builtin_amdgcn_rcpf(fmaxf(b1[e], 1e-20f)); } } }
;                         else if (act == 1) { v0 = gelu4(v0); v1 = gelu4(v1); }
.LBB0_279:
	s_andn2_b64 vcc, exec, s[16:17]
	s_cbranch_vccnz .LBB0_281
	v_and_b32_e32 v249, 0x7fffffff, v77
	v_and_b32_e32 v248, 0x7fffffff, v76
	v_pk_fma_f32 v[152:153], v[248:249], s[28:29], 1.0 op_sel_hi:[1,0,0]
	v_mov_b64_e32 v[160:161], s[34:35]
	v_rcp_f32_e32 v152, v152
	v_rcp_f32_e32 v153, v153
	v_pk_mul_f32 v[156:157], v[76:77], v[76:77]
	s_nop 0
	v_pk_mul_f32 v[156:157], v[156:157], s[74:75] op_sel_hi:[1,0]
	v_pk_fma_f32 v[154:155], v[152:153], s[30:31], v[160:161] op_sel_hi:[1,0,0]
	v_exp_f32_e32 v156, v156
	v_pk_fma_f32 v[154:155], v[152:153], v[154:155], s[36:37] op_sel_hi:[1,1,0]
	v_exp_f32_e32 v157, v157
	v_pk_fma_f32 v[154:155], v[152:153], v[154:155], s[50:51] op_sel_hi:[1,1,0]
	v_pk_mul_f32 v[158:159], v[78:79], v[78:79]
	v_pk_fma_f32 v[154:155], v[152:153], v[154:155], s[72:73] op_sel_hi:[1,1,0]
	v_pk_mul_f32 v[158:159], v[158:159], s[74:75] op_sel_hi:[1,0]
	v_pk_mul_f32 v[152:153], v[152:153], v[154:155]
	v_exp_f32_e32 v158, v158
	v_pk_mul_f32 v[152:153], v[156:157], v[152:153]
	v_and_b32_e32 v251, 0x7fffffff, v79
	v_and_b32_e32 v250, 0x7fffffff, v78
	v_pk_fma_f32 v[156:157], v[250:251], s[28:29], 1.0 op_sel_hi:[1,0,0]
	s_nop 0
	v_rcp_f32_e32 v156, v156
	v_rcp_f32_e32 v157, v157
	v_max_f32_e32 v240, 0, v76
	v_max_f32_e32 v241, 0, v77
	v_pk_fma_f32 v[154:155], v[248:249], v[152:153], v[240:241] neg_lo:[1,0,0] neg_hi:[1,0,0]
	v_exp_f32_e32 v159, v159
	v_pk_mul_f32 v[168:169], v[68:69], v[68:69]
	v_pk_mul_f32 v[170:171], v[70:71], v[70:71]
	v_pk_fma_f32 v[152:153], v[156:157], s[30:31], v[160:161] op_sel_hi:[1,0,0]
	s_nop 0
	v_pk_fma_f32 v[152:153], v[156:157], v[152:153], s[36:37] op_sel_hi:[1,1,0]
	v_pk_mul_f32 v[168:169], v[168:169], s[74:75] op_sel_hi:[1,0]
	v_pk_fma_f32 v[152:153], v[156:157], v[152:153], s[50:51] op_sel_hi:[1,1,0]
	v_exp_f32_e32 v168, v168
	v_pk_fma_f32 v[152:153], v[156:157], v[152:153], s[72:73] op_sel_hi:[1,1,0]
	v_exp_f32_e32 v169, v169
	v_pk_mul_f32 v[152:153], v[156:157], v[152:153]
	s_nop 0
	v_pk_mul_f32 v[152:153], v[158:159], v[152:153]
	v_and_b32_e32 v249, 0x7fffffff, v69
	v_and_b32_e32 v248, 0x7fffffff, v68
	v_pk_fma_f32 v[158:159], v[248:249], s[28:29], 1.0 op_sel_hi:[1,0,0]
	s_nop 0
	v_rcp_f32_e32 v158, v158
	v_rcp_f32_e32 v159, v159
	v_max_f32_e32 v240, 0, v78
	v_max_f32_e32 v241, 0, v79
	v_pk_fma_f32 v[156:157], v[250:251], v[152:153], v[240:241] neg_lo:[1,0,0] neg_hi:[1,0,0]
	s_nop 0
	s_nop 1
	v_pk_fma_f32 v[152:153], v[158:159], s[30:31], v[160:161] op_sel_hi:[1,0,0]
	s_nop 0
	v_pk_fma_f32 v[152:153], v[158:159], v[152:153], s[36:37] op_sel_hi:[1,1,0]
	s_nop 0
	v_pk_fma_f32 v[152:153], v[158:159], v[152:153], s[50:51] op_sel_hi:[1,1,0]
	s_nop 0
	v_pk_fma_f32 v[152:153], v[158:159], v[152:153], s[72:73] op_sel_hi:[1,1,0]
	s_nop 0
	v_pk_mul_f32 v[152:153], v[158:159], v[152:153]
	s_nop 0
	v_pk_mul_f32 v[152:153], v[168:169], v[152:153]
	v_and_b32_e32 v251, 0x7fffffff, v71
	v_and_b32_e32 v250, 0x7fffffff, v70
	v_pk_fma_f32 v[168:169], v[250:251], s[28:29], 1.0 op_sel_hi:[1,0,0]
	s_nop 0
	v_rcp_f32_e32 v168, v168
	v_rcp_f32_e32 v169, v169
	v_max_f32_e32 v240, 0, v68
	v_max_f32_e32 v241, 0, v69
	v_pk_fma_f32 v[158:159], v[248:249], v[152:153], v[240:241] neg_lo:[1,0,0] neg_hi:[1,0,0]
	s_nop 0
	s_nop 1
	v_pk_fma_f32 v[152:153], v[168:169], s[30:31], v[160:161] op_sel_hi:[1,0,0]
	v_pk_mul_f32 v[160:161], v[170:171], s[74:75] op_sel_hi:[1,0]
	v_pk_fma_f32 v[152:153], v[168:169], v[152:153], s[36:37] op_sel_hi:[1,1,0]
	v_exp_f32_e32 v160, v160
	v_exp_f32_e32 v161, v161
	v_pk_fma_f32 v[152:153], v[168:169], v[152:153], s[50:51] op_sel_hi:[1,1,0]
	s_nop 0
	v_pk_fma_f32 v[152:153], v[168:169], v[152:153], s[72:73] op_sel_hi:[1,1,0]
	s_nop 0
	v_pk_mul_f32 v[152:153], v[168:169], v[152:153]
	s_nop 0
	v_pk_mul_f32 v[152:153], v[160:161], v[152:153]
	s_nop 0
	v_max_f32_e32 v240, 0, v70
	v_max_f32_e32 v241, 0, v71
	v_pk_fma_f32 v[160:161], v[250:251], v[152:153], v[240:241] neg_lo:[1,0,0] neg_hi:[1,0,0]
	s_nop 0
	s_nop 1

; __device__ __forceinline__ f32x4 sigm4(f32x4 v) { return (f32x4){sigmoid_f(v[0]), sigmoid_f(v[1]), sigmoid_f(v[2]), sigmoid_f(v[3])}; }
; __device__ __forceinline__ f32x2 gelu_pk(f32x2 v) {
;     const f32x2 av = __builtin_elementwise_abs(v), d = av * 0.2316418882f + 1.0f;
;     f32x2 t; t.x = __builtin_amdgcn_rcpf(d.x); t.y = __builtin_amdgcn_rcpf(d.y);
;     f32x2 q = t * 0.5307027145f + (-0.7265760135f); q = q * t + 0.7107068705f; q = q * t + (-0.142248368f); q = q * t + 0.127414796f; q = q * t;
;     const f32x2 s = (v * v) * (-0.72134752044f);
;     f32x2 e; e.x = __builtin_amdgcn_exp2f(s.x); e.y = __builtin_amdgcn_exp2f(s.y);
;     const f32x2 m = v * (q * e), r = v - m;
;     f32x2 o; o.x = v.x < 0.f ? m.x : r.x; o.y = v.y < 0.f ? m.y : r.y; return o;
; }
; __device__ __forceinline__ f32x4 gelu4(f32x4 v) { f32x2 a = gelu_pk((f32x2){v[0], v[1]}), b = gelu_pk((f32x2){v[2], v[3]}); return (f32x4){a.x, a.y, b.x, b.y}; }
;     __device__ __forceinline__ void operator()(const f32x4 (&acc)[2][2][4][2], const pg8::Unit& u, int wr, int wc, int fr, int fq) const {
;     ...
;                     for (int bj = 0; bj < 2; ++bj) {
;                         f32x4 v0 = acc[ai][bj][m][0], v1 = acc[ai][bj][m][1];
;                         if (act == 5) { v0 = sigm4(v0); v1 = sigm4(v1);
;                             if (bj == 0) { const f32x4 b0 = sigm4(acc[ai][1][m][0]), b1 = sigm4(acc[ai][1][m][1]);
; #pragma unroll
;                                 for (int e = 0; e < 4; ++e) { v0[e] *= __builtin_amdgcn_rcpf(fmaxf(b0[e], 1e-20f)); v1[e] *= __builtin_amdgcn_rcpf(fmaxf(b1[e], 1e-20f)); } } }
;                         else if (act == 1) { v0 = gelu4(v0); v1 = gelu4(v1); }
.LBB0_293:
	s_andn2_b64 vcc, exec, s[16:17]
	s_cbranch_vccnz .LBB0_295
	v_and_b32_e32 v249, 0x7fffffff, v73
	v_and_b32_e32 v248, 0x7fffffff, v72
	v_pk_fma_f32 v[154:155], v[248:249], s[28:29], 1.0 op_sel_hi:[1,0,0]
	v_mov_b64_e32 v[160:161], s[34:35]
	v_rcp_f32_e32 v154, v154
	v_rcp_f32_e32 v155, v155
	v_pk_mul_f32 v[158:159], v[72:73], v[72:73]
	v_and_b32_e32 v251, 0x7fffffff, v75
	v_pk_mul_f32 v[158:159], v[158:159], s[74:75] op_sel_hi:[1,0]
	v_pk_fma_f32 v[156:157], v[154:155], s[30:31], v[160:161] op_sel_hi:[1,0,0]
	v_exp_f32_e32 v158, v158
	v_pk_fma_f32 v[156:157], v[154:155], v[156:157], s[36:37] op_sel_hi:[1,1,0]
	v_exp_f32_e32 v159, v159
	v_pk_fma_f32 v[156:157], v[154:155], v[156:157], s[50:51] op_sel_hi:[1,1,0]
	v_and_b32_e32 v250, 0x7fffffff, v74
	v_pk_fma_f32 v[156:157], v[154:155], v[156:157], s[72:73] op_sel_hi:[1,1,0]
	v_pk_fma_f32 v[168:169], v[250:251], s[28:29], 1.0 op_sel_hi:[1,0,0]
	v_pk_mul_f32 v[154:155], v[154:155], v[156:157]
	v_rcp_f32_e32 v168, v168
	v_rcp_f32_e32 v169, v169
	v_pk_mul_f32 v[154:155], v[158:159], v[154:155]
	v_max_f32_e32 v240, 0, v72
	v_max_f32_e32 v241, 0, v73
	v_pk_fma_f32 v[154:155], v[248:249], v[154:155], v[240:241] neg_lo:[1,0,0] neg_hi:[1,0,0]
	v_pk_mul_f32 v[156:157], v[74:75], v[74:75]
	s_nop 0
	v_pk_mul_f32 v[156:157], v[156:157], s[74:75] op_sel_hi:[1,0]
	v_and_b32_e32 v253, 0x7fffffff, v67
	v_pk_fma_f32 v[158:159], v[168:169], s[30:31], v[160:161] op_sel_hi:[1,0,0]
	v_exp_f32_e32 v156, v156
	v_pk_fma_f32 v[158:159], v[168:169], v[158:159], s[36:37] op_sel_hi:[1,1,0]
	v_exp_f32_e32 v157, v157
	v_pk_fma_f32 v[158:159], v[168:169], v[158:159], s[50:51] op_sel_hi:[1,1,0]
	s_nop 0
	v_pk_fma_f32 v[158:159], v[168:169], v[158:159], s[72:73] op_sel_hi:[1,1,0]
	v_and_b32_e32 v252, 0x7fffffff, v66
	v_pk_mul_f32 v[158:159], v[168:169], v[158:159]
	v_and_b32_e32 v249, 0x7fffffff, v65
	v_and_b32_e32 v248, 0x7fffffff, v64
	v_pk_fma_f32 v[168:169], v[248:249], s[28:29], 1.0 op_sel_hi:[1,0,0]
	v_pk_mul_f32 v[156:157], v[156:157], v[158:159]
	v_rcp_f32_e32 v168, v168
	v_rcp_f32_e32 v169, v169
	v_max_f32_e32 v240, 0, v74
	v_max_f32_e32 v241, 0, v75
	v_pk_fma_f32 v[156:157], v[250:251], v[156:157], v[240:241] neg_lo:[1,0,0] neg_hi:[1,0,0]
	v_pk_fma_f32 v[172:173], v[252:253], s[28:29], 1.0 op_sel_hi:[1,0,0]
	s_nop 0
	v_rcp_f32_e32 v172, v172
	v_rcp_f32_e32 v173, v173
	v_pk_fma_f32 v[158:159], v[168:169], s[30:31], v[160:161] op_sel_hi:[1,0,0]
	v_pk_mul_f32 v[170:171], v[64:65], v[64:65]
	v_pk_fma_f32 v[158:159], v[168:169], v[158:159], s[36:37] op_sel_hi:[1,1,0]
	v_pk_mul_f32 v[170:171], v[170:171], s[74:75] op_sel_hi:[1,0]
	v_pk_fma_f32 v[158:159], v[168:169], v[158:159], s[50:51] op_sel_hi:[1,1,0]
	v_exp_f32_e32 v170, v170
	v_pk_fma_f32 v[158:159], v[168:169], v[158:159], s[72:73] op_sel_hi:[1,1,0]
	v_exp_f32_e32 v171, v171
	v_pk_mul_f32 v[158:159], v[168:169], v[158:159]
	v_pk_mul_f32 v[168:169], v[66:67], v[66:67]
	v_pk_fma_f32 v[160:161], v[172:173], s[30:31], v[160:161] op_sel_hi:[1,0,0]
	v_pk_mul_f32 v[168:169], v[168:169], s[74:75] op_sel_hi:[1,0]
	v_pk_fma_f32 v[160:161], v[172:173], v[160:161], s[36:37] op_sel_hi:[1,1,0]
	v_exp_f32_e32 v168, v168
	v_exp_f32_e32 v169, v169
	v_pk_fma_f32 v[160:161], v[172:173], v[160:161], s[50:51] op_sel_hi:[1,1,0]
	v_pk_mul_f32 v[158:159], v[170:171], v[158:159]
	v_pk_fma_f32 v[160:161], v[172:173], v[160:161], s[72:73] op_sel_hi:[1,1,0]
	v_max_f32_e32 v240, 0, v64
	v_max_f32_e32 v241, 0, v65
	v_pk_fma_f32 v[158:159], v[248:249], v[158:159], v[240:241] neg_lo:[1,0,0] neg_hi:[1,0,0]
	v_pk_mul_f32 v[160:161], v[172:173], v[160:161]
	s_nop 0
	v_pk_mul_f32 v[160:161], v[168:169], v[160:161]
	s_nop 0
	v_max_f32_e32 v240, 0, v66
	v_max_f32_e32 v241, 0, v67
	v_pk_fma_f32 v[160:161], v[252:253], v[160:161], v[240:241] neg_lo:[1,0,0] neg_hi:[1,0,0]
	s_nop 1
	s_nop 1

; __device__ __forceinline__ f32x4 sigm4(f32x4 v) { return (f32x4){sigmoid_f(v[0]), sigmoid_f(v[1]), sigmoid_f(v[2]), sigmoid_f(v[3])}; }
; __device__ __forceinline__ f32x2 gelu_pk(f32x2 v) {
;     const f32x2 av = __builtin_elementwise_abs(v), d = av * 0.2316418882f + 1.0f;
;     f32x2 t; t.x = __builtin_amdgcn_rcpf(d.x); t.y = __builtin_amdgcn_rcpf(d.y);
;     f32x2 q = t * 0.5307027145f + (-0.7265760135f); q = q * t + 0.7107068705f; q = q * t + (-0.142248368f); q = q * t + 0.127414796f; q = q * t;
;     const f32x2 s = (v * v) * (-0.72134752044f);
;     f32x2 e; e.x = __builtin_amdgcn_exp2f(s.x); e.y = __builtin_amdgcn_exp2f(s.y);
;     const f32x2 m = v * (q * e), r = v - m;
;     f32x2 o; o.x = v.x < 0.f ? m.x : r.x; o.y = v.y < 0.f ? m.y : r.y; return o;
; }
; __device__ __forceinline__ f32x4 gelu4(f32x4 v) { f32x2 a = gelu_pk((f32x2){v[0], v[1]}), b = gelu_pk((f32x2){v[2], v[3]}); return (f32x4){a.x, a.y, b.x, b.y}; }
;     __device__ __forceinline__ void operator()(const f32x4 (&acc)[2][2][4][2], const pg8::Unit& u, int wr, int wc, int fr, int fq) const {
;     ...
;                     for (int bj = 0; bj < 2; ++bj) {
;                         f32x4 v0 = acc[ai][bj][m][0], v1 = acc[ai][bj][m][1];
;                         if (act == 5) { v0 = sigm4(v0); v1 = sigm4(v1);
;                             if (bj == 0) { const f32x4 b0 = sigm4(acc[ai][1][m][0]), b1 = sigm4(acc[ai][1][m][1]);
; #pragma unroll
;                                 for (int e = 0; e < 4; ++e) { v0[e] *= __builtin_amdgcn_rcpf(fmaxf(b0[e], 1e-20f)); v1[e] *= __builtin_amdgcn_rcpf(fmaxf(b1[e], 1e-20f)); } } }
;                         else if (act == 1) { v0 = gelu4(v0); v1 = gelu4(v1); }
.LBB0_307:
	s_andn2_b64 vcc, exec, s[16:17]
	s_cbranch_vccnz .LBB0_309
	v_and_b32_e32 v249, 0x7fffffff, v61
	v_and_b32_e32 v248, 0x7fffffff, v60
	v_pk_fma_f32 v[152:153], v[248:249], s[28:29], 1.0 op_sel_hi:[1,0,0]
	v_mov_b64_e32 v[160:161], s[34:35]
	v_rcp_f32_e32 v152, v152
	v_rcp_f32_e32 v153, v153
	v_pk_mul_f32 v[156:157], v[60:61], v[60:61]
	s_nop 0
	v_pk_mul_f32 v[156:157], v[156:157], s[74:75] op_sel_hi:[1,0]
	v_pk_fma_f32 v[154:155], v[152:153], s[30:31], v[160:161] op_sel_hi:[1,0,0]
	v_exp_f32_e32 v156, v156
	v_pk_fma_f32 v[154:155], v[152:153], v[154:155], s[36:37] op_sel_hi:[1,1,0]
	v_exp_f32_e32 v157, v157
	v_pk_fma_f32 v[154:155], v[152:153], v[154:155], s[50:51] op_sel_hi:[1,1,0]
	v_pk_mul_f32 v[158:159], v[62:63], v[62:63]
	v_pk_fma_f32 v[154:155], v[152:153], v[154:155], s[72:73] op_sel_hi:[1,1,0]
	v_pk_mul_f32 v[158:159], v[158:159], s[74:75] op_sel_hi:[1,0]
	v_pk_mul_f32 v[152:153], v[152:153], v[154:155]
	v_exp_f32_e32 v158, v158
	v_pk_mul_f32 v[152:153], v[156:157], v[152:153]
	v_and_b32_e32 v251, 0x7fffffff, v63
	v_and_b32_e32 v250, 0x7fffffff, v62
	v_pk_fma_f32 v[156:157], v[250:251], s[28:29], 1.0 op_sel_hi:[1,0,0]
	s_nop 0
	v_rcp_f32_e32 v156, v156
	v_rcp_f32_e32 v157, v157
	v_max_f32_e32 v240, 0, v60
	v_max_f32_e32 v241, 0, v61
	v_pk_fma_f32 v[154:155], v[248:249], v[152:153], v[240:241] neg_lo:[1,0,0] neg_hi:[1,0,0]
	v_exp_f32_e32 v159, v159
	v_pk_mul_f32 v[168:169], v[52:53], v[52:53]
	v_pk_mul_f32 v[170:171], v[54:55], v[54:55]
	v_pk_fma_f32 v[152:153], v[156:157], s[30:31], v[160:161] op_sel_hi:[1,0,0]
	s_nop 0
	v_pk_fma_f32 v[152:153], v[156:157], v[152:153], s[36:37] op_sel_hi:[1,1,0]
	v_pk_mul_f32 v[168:169], v[168:169], s[74:75] op_sel_hi:[1,0]
	v_pk_fma_f32 v[152:153], v[156:157], v[152:153], s[50:51] op_sel_hi:[1,1,0]
	v_exp_f32_e32 v168, v168
	v_pk_fma_f32 v[152:153], v[156:157], v[152:153], s[72:73] op_sel_hi:[1,1,0]
	v_exp_f32_e32 v169, v169
	v_pk_mul_f32 v[152:153], v[156:157], v[152:153]
	s_nop 0
	v_pk_mul_f32 v[152:153], v[158:159], v[152:153]
	v_and_b32_e32 v249, 0x7fffffff, v53
	v_and_b32_e32 v248, 0x7fffffff, v52
	v_pk_fma_f32 v[158:159], v[248:249], s[28:29], 1.0 op_sel_hi:[1,0,0]
	s_nop 0
	v_rcp_f32_e32 v158, v158
	v_rcp_f32_e32 v159, v159
	v_max_f32_e32 v240, 0, v62
	v_max_f32_e32 v241, 0, v63
	v_pk_fma_f32 v[156:157], v[250:251], v[152:153], v[240:241] neg_lo:[1,0,0] neg_hi:[1,0,0]
	s_nop 0
	s_nop 1
	v_pk_fma_f32 v[152:153], v[158:159], s[30:31], v[160:161] op_sel_hi:[1,0,0]
	s_nop 0
	v_pk_fma_f32 v[152:153], v[158:159], v[152:153], s[36:37] op_sel_hi:[1,1,0]
	s_nop 0
	v_pk_fma_f32 v[152:153], v[158:159], v[152:153], s[50:51] op_sel_hi:[1,1,0]
	s_nop 0
	v_pk_fma_f32 v[152:153], v[158:159], v[152:153], s[72:73] op_sel_hi:[1,1,0]
	s_nop 0
	v_pk_mul_f32 v[152:153], v[158:159], v[152:153]
	s_nop 0
	v_pk_mul_f32 v[152:153], v[168:169], v[152:153]
	v_and_b32_e32 v251, 0x7fffffff, v55
	v_and_b32_e32 v250, 0x7fffffff, v54
	v_pk_fma_f32 v[168:169], v[250:251], s[28:29], 1.0 op_sel_hi:[1,0,0]
	s_nop 0
	v_rcp_f32_e32 v168, v168
	v_rcp_f32_e32 v169, v169
	v_max_f32_e32 v240, 0, v52
	v_max_f32_e32 v241, 0, v53
	v_pk_fma_f32 v[158:159], v[248:249], v[152:153], v[240:241] neg_lo:[1,0,0] neg_hi:[1,0,0]
	s_nop 0
	s_nop 1
	v_pk_fma_f32 v[152:153], v[168:169], s[30:31], v[160:161] op_sel_hi:[1,0,0]
	v_pk_mul_f32 v[160:161], v[170:171], s[74:75] op_sel_hi:[1,0]
	v_pk_fma_f32 v[152:153], v[168:169], v[152:153], s[36:37] op_sel_hi:[1,1,0]
	v_exp_f32_e32 v160, v160
	v_exp_f32_e32 v161, v161
	v_pk_fma_f32 v[152:153], v[168:169], v[152:153], s[50:51] op_sel_hi:[1,1,0]
	s_nop 0
	v_pk_fma_f32 v[152:153], v[168:169], v[152:153], s[72:73] op_sel_hi:[1,1,0]
	s_nop 0
	v_pk_mul_f32 v[152:153], v[168:169], v[152:153]
	s_nop 0
	v_pk_mul_f32 v[152:153], v[160:161], v[152:153]
	s_nop 0
	v_max_f32_e32 v240, 0, v54
	v_max_f32_e32 v241, 0, v55
	v_pk_fma_f32 v[160:161], v[250:251], v[152:153], v[240:241] neg_lo:[1,0,0] neg_hi:[1,0,0]
	s_nop 0
	s_nop 1

; __device__ __forceinline__ f32x4 sigm4(f32x4 v) { return (f32x4){sigmoid_f(v[0]), sigmoid_f(v[1]), sigmoid_f(v[2]), sigmoid_f(v[3])}; }
; __device__ __forceinline__ f32x2 gelu_pk(f32x2 v) {
;     const f32x2 av = __builtin_elementwise_abs(v), d = av * 0.2316418882f + 1.0f;
;     f32x2 t; t.x = __builtin_amdgcn_rcpf(d.x); t.y = __builtin_amdgcn_rcpf(d.y);
;     f32x2 q = t * 0.5307027145f + (-0.7265760135f); q = q * t + 0.7107068705f; q = q * t + (-0.142248368f); q = q * t + 0.127414796f; q = q * t;
;     const f32x2 s = (v * v) * (-0.72134752044f);
;     f32x2 e; e.x = __builtin_amdgcn_exp2f(s.x); e.y = __builtin_amdgcn_exp2f(s.y);
;     const f32x2 m = v * (q * e), r = v - m;
;     f32x2 o; o.x = v.x < 0.f ? m.x : r.x; o.y = v.y < 0.f ? m.y : r.y; return o;
; }
; __device__ __forceinline__ f32x4 gelu4(f32x4 v) { f32x2 a = gelu_pk((f32x2){v[0], v[1]}), b = gelu_pk((f32x2){v[2], v[3]}); return (f32x4){a.x, a.y, b.x, b.y}; }
;     __device__ __forceinline__ void operator()(const f32x4 (&acc)[2][2][4][2], const pg8::Unit& u, int wr, int wc, int fr, int fq) const {
;     ...
;                     for (int bj = 0; bj < 2; ++bj) {
;                         f32x4 v0 = acc[ai][bj][m][0], v1 = acc[ai][bj][m][1];
;                         if (act == 5) { v0 = sigm4(v0); v1 = sigm4(v1);
;                             if (bj == 0) { const f32x4 b0 = sigm4(acc[ai][1][m][0]), b1 = sigm4(acc[ai][1][m][1]);
; #pragma unroll
;                                 for (int e = 0; e < 4; ++e) { v0[e] *= __builtin_amdgcn_rcpf(fmaxf(b0[e], 1e-20f)); v1[e] *= __builtin_amdgcn_rcpf(fmaxf(b1[e], 1e-20f)); } } }
;                         else if (act == 1) { v0 = gelu4(v0); v1 = gelu4(v1); }
.LBB0_321:
	s_andn2_b64 vcc, exec, s[16:17]
	s_cbranch_vccnz .LBB0_323
	v_and_b32_e32 v249, 0x7fffffff, v57
	v_and_b32_e32 v248, 0x7fffffff, v56
	v_pk_fma_f32 v[154:155], v[248:249], s[28:29], 1.0 op_sel_hi:[1,0,0]
	v_mov_b64_e32 v[160:161], s[34:35]
	v_rcp_f32_e32 v154, v154
	v_rcp_f32_e32 v155, v155
	v_pk_mul_f32 v[158:159], v[56:57], v[56:57]
	v_and_b32_e32 v251, 0x7fffffff, v59
	v_pk_mul_f32 v[158:159], v[158:159], s[74:75] op_sel_hi:[1,0]
	v_pk_fma_f32 v[156:157], v[154:155], s[30:31], v[160:161] op_sel_hi:[1,0,0]
	v_exp_f32_e32 v158, v158
	v_pk_fma_f32 v[156:157], v[154:155], v[156:157], s[36:37] op_sel_hi:[1,1,0]
	v_exp_f32_e32 v159, v159
	v_pk_fma_f32 v[156:157], v[154:155], v[156:157], s[50:51] op_sel_hi:[1,1,0]
	v_and_b32_e32 v250, 0x7fffffff, v58
	v_pk_fma_f32 v[156:157], v[154:155], v[156:157], s[72:73] op_sel_hi:[1,1,0]
	v_pk_fma_f32 v[168:169], v[250:251], s[28:29], 1.0 op_sel_hi:[1,0,0]
	v_pk_mul_f32 v[154:155], v[154:155], v[156:157]
	v_rcp_f32_e32 v168, v168
	v_rcp_f32_e32 v169, v169
	v_pk_mul_f32 v[154:155], v[158:159], v[154:155]
	v_max_f32_e32 v240, 0, v56
	v_max_f32_e32 v241, 0, v57
	v_pk_fma_f32 v[154:155], v[248:249], v[154:155], v[240:241] neg_lo:[1,0,0] neg_hi:[1,0,0]
	v_pk_mul_f32 v[156:157], v[58:59], v[58:59]
	s_nop 0
	v_pk_mul_f32 v[156:157], v[156:157], s[74:75] op_sel_hi:[1,0]
	v_and_b32_e32 v253, 0x7fffffff, v51
	v_pk_fma_f32 v[158:159], v[168:169], s[30:31], v[160:161] op_sel_hi:[1,0,0]
	v_exp_f32_e32 v156, v156
	v_pk_fma_f32 v[158:159], v[168:169], v[158:159], s[36:37] op_sel_hi:[1,1,0]
	v_exp_f32_e32 v157, v157
	v_pk_fma_f32 v[158:159], v[168:169], v[158:159], s[50:51] op_sel_hi:[1,1,0]
	s_nop 0
	v_pk_fma_f32 v[158:159], v[168:169], v[158:159], s[72:73] op_sel_hi:[1,1,0]
	v_and_b32_e32 v252, 0x7fffffff, v50
	v_pk_mul_f32 v[158:159], v[168:169], v[158:159]
	v_and_b32_e32 v249, 0x7fffffff, v49
	v_and_b32_e32 v248, 0x7fffffff, v48
	v_pk_fma_f32 v[168:169], v[248:249], s[28:29], 1.0 op_sel_hi:[1,0,0]
	v_pk_mul_f32 v[156:157], v[156:157], v[158:159]
	v_rcp_f32_e32 v168, v168
	v_rcp_f32_e32 v169, v169
	v_max_f32_e32 v240, 0, v58
	v_max_f32_e32 v241, 0, v59
	v_pk_fma_f32 v[156:157], v[250:251], v[156:157], v[240:241] neg_lo:[1,0,0] neg_hi:[1,0,0]
	v_pk_fma_f32 v[172:173], v[252:253], s[28:29], 1.0 op_sel_hi:[1,0,0]
	s_nop 0
	v_rcp_f32_e32 v172, v172
	v_rcp_f32_e32 v173, v173
	v_pk_fma_f32 v[158:159], v[168:169], s[30:31], v[160:161] op_sel_hi:[1,0,0]
	v_pk_mul_f32 v[170:171], v[48:49], v[48:49]
	v_pk_fma_f32 v[158:159], v[168:169], v[158:159], s[36:37] op_sel_hi:[1,1,0]
	v_pk_mul_f32 v[170:171], v[170:171], s[74:75] op_sel_hi:[1,0]
	v_pk_fma_f32 v[158:159], v[168:169], v[158:159], s[50:51] op_sel_hi:[1,1,0]
	v_exp_f32_e32 v170, v170
	v_pk_fma_f32 v[158:159], v[168:169], v[158:159], s[72:73] op_sel_hi:[1,1,0]
	v_exp_f32_e32 v171, v171
	v_pk_mul_f32 v[158:159], v[168:169], v[158:159]
	v_pk_mul_f32 v[168:169], v[50:51], v[50:51]
	v_pk_fma_f32 v[160:161], v[172:173], s[30:31], v[160:161] op_sel_hi:[1,0,0]
	v_pk_mul_f32 v[168:169], v[168:169], s[74:75] op_sel_hi:[1,0]
	v_pk_fma_f32 v[160:161], v[172:173], v[160:161], s[36:37] op_sel_hi:[1,1,0]
	v_exp_f32_e32 v168, v168
	v_exp_f32_e32 v169, v169
	v_pk_fma_f32 v[160:161], v[172:173], v[160:161], s[50:51] op_sel_hi:[1,1,0]
	v_pk_mul_f32 v[158:159], v[170:171], v[158:159]
	v_pk_fma_f32 v[160:161], v[172:173], v[160:161], s[72:73] op_sel_hi:[1,1,0]
	v_max_f32_e32 v240, 0, v48
	v_max_f32_e32 v241, 0, v49
	v_pk_fma_f32 v[158:159], v[248:249], v[158:159], v[240:241] neg_lo:[1,0,0] neg_hi:[1,0,0]
	v_pk_mul_f32 v[160:161], v[172:173], v[160:161]
	s_nop 0
	v_pk_mul_f32 v[160:161], v[168:169], v[160:161]
	s_nop 0
	v_max_f32_e32 v240, 0, v50
	v_max_f32_e32 v241, 0, v51
	v_pk_fma_f32 v[160:161], v[252:253], v[160:161], v[240:241] neg_lo:[1,0,0] neg_hi:[1,0,0]
	s_nop 1
	s_nop 1

; __device__ __forceinline__ f32x4 sigm4(f32x4 v) { return (f32x4){sigmoid_f(v[0]), sigmoid_f(v[1]), sigmoid_f(v[2]), sigmoid_f(v[3])}; }
; __device__ __forceinline__ f32x2 gelu_pk(f32x2 v) {
;     const f32x2 av = __builtin_elementwise_abs(v), d = av * 0.2316418882f + 1.0f;
;     f32x2 t; t.x = __builtin_amdgcn_rcpf(d.x); t.y = __builtin_amdgcn_rcpf(d.y);
;     f32x2 q = t * 0.5307027145f + (-0.7265760135f); q = q * t + 0.7107068705f; q = q * t + (-0.142248368f); q = q * t + 0.127414796f; q = q * t;
;     const f32x2 s = (v * v) * (-0.72134752044f);
;     f32x2 e; e.x = __builtin_amdgcn_exp2f(s.x); e.y = __builtin_amdgcn_exp2f(s.y);
;     const f32x2 m = v * (q * e), r = v - m;
;     f32x2 o; o.x = v.x < 0.f ? m.x : r.x; o.y = v.y < 0.f ? m.y : r.y; return o;
; }
; __device__ __forceinline__ f32x4 gelu4(f32x4 v) { f32x2 a = gelu_pk((f32x2){v[0], v[1]}), b = gelu_pk((f32x2){v[2], v[3]}); return (f32x4){a.x, a.y, b.x, b.y}; }
;     __device__ __forceinline__ void operator()(const f32x4 (&acc)[2][2][4][2], const pg8::Unit& u, int wr, int wc, int fr, int fq) const {
;     ...
;                     for (int bj = 0; bj < 2; ++bj) {
;                         f32x4 v0 = acc[ai][bj][m][0], v1 = acc[ai][bj][m][1];
;                         if (act == 5) { v0 = sigm4(v0); v1 = sigm4(v1);
;                             if (bj == 0) { const f32x4 b0 = sigm4(acc[ai][1][m][0]), b1 = sigm4(acc[ai][1][m][1]);
; #pragma unroll
;                                 for (int e = 0; e < 4; ++e) { v0[e] *= __builtin_amdgcn_rcpf(fmaxf(b0[e], 1e-20f)); v1[e] *= __builtin_amdgcn_rcpf(fmaxf(b1[e], 1e-20f)); } } }
;                         else if (act == 1) { v0 = gelu4(v0); v1 = gelu4(v1); }
.LBB0_335:
	s_andn2_b64 vcc, exec, s[16:17]
	s_cbranch_vccnz .LBB0_337
	v_and_b32_e32 v249, 0x7fffffff, v45
	v_and_b32_e32 v248, 0x7fffffff, v44
	v_pk_fma_f32 v[152:153], v[248:249], s[28:29], 1.0 op_sel_hi:[1,0,0]
	v_mov_b64_e32 v[160:161], s[34:35]
	v_rcp_f32_e32 v152, v152
	v_rcp_f32_e32 v153, v153
	v_pk_mul_f32 v[156:157], v[44:45], v[44:45]
	s_nop 0
	v_pk_mul_f32 v[156:157], v[156:157], s[74:75] op_sel_hi:[1,0]
	v_pk_fma_f32 v[154:155], v[152:153], s[30:31], v[160:161] op_sel_hi:[1,0,0]
	v_exp_f32_e32 v156, v156
	v_pk_fma_f32 v[154:155], v[152:153], v[154:155], s[36:37] op_sel_hi:[1,1,0]
	v_exp_f32_e32 v157, v157
	v_pk_fma_f32 v[154:155], v[152:153], v[154:155], s[50:51] op_sel_hi:[1,1,0]
	v_pk_mul_f32 v[158:159], v[46:47], v[46:47]
	v_pk_fma_f32 v[154:155], v[152:153], v[154:155], s[72:73] op_sel_hi:[1,1,0]
	v_pk_mul_f32 v[158:159], v[158:159], s[74:75] op_sel_hi:[1,0]
	v_pk_mul_f32 v[152:153], v[152:153], v[154:155]
	v_exp_f32_e32 v158, v158
	v_pk_mul_f32 v[152:153], v[156:157], v[152:153]
	v_and_b32_e32 v251, 0x7fffffff, v47
	v_and_b32_e32 v250, 0x7fffffff, v46
	v_pk_fma_f32 v[156:157], v[250:251], s[28:29], 1.0 op_sel_hi:[1,0,0]
	s_nop 0
	v_rcp_f32_e32 v156, v156
	v_rcp_f32_e32 v157, v157
	v_max_f32_e32 v240, 0, v44
	v_max_f32_e32 v241, 0, v45
	v_pk_fma_f32 v[154:155], v[248:249], v[152:153], v[240:241] neg_lo:[1,0,0] neg_hi:[1,0,0]
	v_exp_f32_e32 v159, v159
	v_pk_mul_f32 v[168:169], v[36:37], v[36:37]
	v_pk_mul_f32 v[170:171], v[38:39], v[38:39]
	v_pk_fma_f32 v[152:153], v[156:157], s[30:31], v[160:161] op_sel_hi:[1,0,0]
	s_nop 0
	v_pk_fma_f32 v[152:153], v[156:157], v[152:153], s[36:37] op_sel_hi:[1,1,0]
	v_pk_mul_f32 v[168:169], v[168:169], s[74:75] op_sel_hi:[1,0]
	v_pk_fma_f32 v[152:153], v[156:157], v[152:153], s[50:51] op_sel_hi:[1,1,0]
	v_exp_f32_e32 v168, v168
	v_pk_fma_f32 v[152:153], v[156:157], v[152:153], s[72:73] op_sel_hi:[1,1,0]
	v_exp_f32_e32 v169, v169
	v_pk_mul_f32 v[152:153], v[156:157], v[152:153]
	s_nop 0
	v_pk_mul_f32 v[152:153], v[158:159], v[152:153]
	v_and_b32_e32 v249, 0x7fffffff, v37
	v_and_b32_e32 v248, 0x7fffffff, v36
	v_pk_fma_f32 v[158:159], v[248:249], s[28:29], 1.0 op_sel_hi:[1,0,0]
	s_nop 0
	v_rcp_f32_e32 v158, v158
	v_rcp_f32_e32 v159, v159
	v_max_f32_e32 v240, 0, v46
	v_max_f32_e32 v241, 0, v47
	v_pk_fma_f32 v[156:157], v[250:251], v[152:153], v[240:241] neg_lo:[1,0,0] neg_hi:[1,0,0]
	s_nop 0
	s_nop 1
	v_pk_fma_f32 v[152:153], v[158:159], s[30:31], v[160:161] op_sel_hi:[1,0,0]
	s_nop 0
	v_pk_fma_f32 v[152:153], v[158:159], v[152:153], s[36:37] op_sel_hi:[1,1,0]
	s_nop 0
	v_pk_fma_f32 v[152:153], v[158:159], v[152:153], s[50:51] op_sel_hi:[1,1,0]
	s_nop 0
	v_pk_fma_f32 v[152:153], v[158:159], v[152:153], s[72:73] op_sel_hi:[1,1,0]
	s_nop 0
	v_pk_mul_f32 v[152:153], v[158:159], v[152:153]
	s_nop 0
	v_pk_mul_f32 v[152:153], v[168:169], v[152:153]
	v_and_b32_e32 v251, 0x7fffffff, v39
	v_and_b32_e32 v250, 0x7fffffff, v38
	v_pk_fma_f32 v[168:169], v[250:251], s[28:29], 1.0 op_sel_hi:[1,0,0]
	s_nop 0
	v_rcp_f32_e32 v168, v168
	v_rcp_f32_e32 v169, v169
	v_max_f32_e32 v240, 0, v36
	v_max_f32_e32 v241, 0, v37
	v_pk_fma_f32 v[158:159], v[248:249], v[152:153], v[240:241] neg_lo:[1,0,0] neg_hi:[1,0,0]
	s_nop 0
	s_nop 1
	v_pk_fma_f32 v[152:153], v[168:169], s[30:31], v[160:161] op_sel_hi:[1,0,0]
	v_pk_mul_f32 v[160:161], v[170:171], s[74:75] op_sel_hi:[1,0]
	v_pk_fma_f32 v[152:153], v[168:169], v[152:153], s[36:37] op_sel_hi:[1,1,0]
	v_exp_f32_e32 v160, v160
	v_exp_f32_e32 v161, v161
	v_pk_fma_f32 v[152:153], v[168:169], v[152:153], s[50:51] op_sel_hi:[1,1,0]
	s_nop 0
	v_pk_fma_f32 v[152:153], v[168:169], v[152:153], s[72:73] op_sel_hi:[1,1,0]
	s_nop 0
	v_pk_mul_f32 v[152:153], v[168:169], v[152:153]
	s_nop 0
	v_pk_mul_f32 v[152:153], v[160:161], v[152:153]
	s_nop 0
	v_max_f32_e32 v240, 0, v38
	v_max_f32_e32 v241, 0, v39
	v_pk_fma_f32 v[160:161], v[250:251], v[152:153], v[240:241] neg_lo:[1,0,0] neg_hi:[1,0,0]
	s_nop 0
	s_nop 1

; __device__ __forceinline__ f32x4 sigm4(f32x4 v) { return (f32x4){sigmoid_f(v[0]), sigmoid_f(v[1]), sigmoid_f(v[2]), sigmoid_f(v[3])}; }
; __device__ __forceinline__ f32x2 gelu_pk(f32x2 v) {
;     const f32x2 av = __builtin_elementwise_abs(v), d = av * 0.2316418882f + 1.0f;
;     f32x2 t; t.x = __builtin_amdgcn_rcpf(d.x); t.y = __builtin_amdgcn_rcpf(d.y);
;     f32x2 q = t * 0.5307027145f + (-0.7265760135f); q = q * t + 0.7107068705f; q = q * t + (-0.142248368f); q = q * t + 0.127414796f; q = q * t;
;     const f32x2 s = (v * v) * (-0.72134752044f);
;     f32x2 e; e.x = __builtin_amdgcn_exp2f(s.x); e.y = __builtin_amdgcn_exp2f(s.y);
;     const f32x2 m = v * (q * e), r = v - m;
;     f32x2 o; o.x = v.x < 0.f ? m.x : r.x; o.y = v.y < 0.f ? m.y : r.y; return o;
; }
; __device__ __forceinline__ f32x4 gelu4(f32x4 v) { f32x2 a = gelu_pk((f32x2){v[0], v[1]}), b = gelu_pk((f32x2){v[2], v[3]}); return (f32x4){a.x, a.y, b.x, b.y}; }
;     __device__ __forceinline__ void operator()(const f32x4 (&acc)[2][2][4][2], const pg8::Unit& u, int wr, int wc, int fr, int fq) const {
;     ...
;                     for (int bj = 0; bj < 2; ++bj) {
;                         f32x4 v0 = acc[ai][bj][m][0], v1 = acc[ai][bj][m][1];
;                         if (act == 5) { v0 = sigm4(v0); v1 = sigm4(v1);
;                             if (bj == 0) { const f32x4 b0 = sigm4(acc[ai][1][m][0]), b1 = sigm4(acc[ai][1][m][1]);
; #pragma unroll
;                                 for (int e = 0; e < 4; ++e) { v0[e] *= __builtin_amdgcn_rcpf(fmaxf(b0[e], 1e-20f)); v1[e] *= __builtin_amdgcn_rcpf(fmaxf(b1[e], 1e-20f)); } } }
;                         else if (act == 1) { v0 = gelu4(v0); v1 = gelu4(v1); }
.LBB0_349:
	s_andn2_b64 vcc, exec, s[16:17]
	s_cbranch_vccnz .LBB0_351
	v_and_b32_e32 v249, 0x7fffffff, v41
	v_and_b32_e32 v248, 0x7fffffff, v40
	v_pk_fma_f32 v[154:155], v[248:249], s[28:29], 1.0 op_sel_hi:[1,0,0]
	v_mov_b64_e32 v[160:161], s[34:35]
	v_rcp_f32_e32 v154, v154
	v_rcp_f32_e32 v155, v155
	v_pk_mul_f32 v[158:159], v[40:41], v[40:41]
	v_and_b32_e32 v251, 0x7fffffff, v43
	v_pk_mul_f32 v[158:159], v[158:159], s[74:75] op_sel_hi:[1,0]
	v_pk_fma_f32 v[156:157], v[154:155], s[30:31], v[160:161] op_sel_hi:[1,0,0]
	v_exp_f32_e32 v158, v158
	v_pk_fma_f32 v[156:157], v[154:155], v[156:157], s[36:37] op_sel_hi:[1,1,0]
	v_exp_f32_e32 v159, v159
	v_pk_fma_f32 v[156:157], v[154:155], v[156:157], s[50:51] op_sel_hi:[1,1,0]
	v_and_b32_e32 v250, 0x7fffffff, v42
	v_pk_fma_f32 v[156:157], v[154:155], v[156:157], s[72:73] op_sel_hi:[1,1,0]
	v_pk_fma_f32 v[168:169], v[250:251], s[28:29], 1.0 op_sel_hi:[1,0,0]
	v_pk_mul_f32 v[154:155], v[154:155], v[156:157]
	v_rcp_f32_e32 v168, v168
	v_rcp_f32_e32 v169, v169
	v_pk_mul_f32 v[154:155], v[158:159], v[154:155]
	v_max_f32_e32 v240, 0, v40
	v_max_f32_e32 v241, 0, v41
	v_pk_fma_f32 v[154:155], v[248:249], v[154:155], v[240:241] neg_lo:[1,0,0] neg_hi:[1,0,0]
	v_pk_mul_f32 v[156:157], v[42:43], v[42:43]
	s_nop 0
	v_pk_mul_f32 v[156:157], v[156:157], s[74:75] op_sel_hi:[1,0]
	v_and_b32_e32 v253, 0x7fffffff, v35
	v_pk_fma_f32 v[158:159], v[168:169], s[30:31], v[160:161] op_sel_hi:[1,0,0]
	v_exp_f32_e32 v156, v156
	v_pk_fma_f32 v[158:159], v[168:169], v[158:159], s[36:37] op_sel_hi:[1,1,0]
	v_exp_f32_e32 v157, v157
	v_pk_fma_f32 v[158:159], v[168:169], v[158:159], s[50:51] op_sel_hi:[1,1,0]
	s_nop 0
	v_pk_fma_f32 v[158:159], v[168:169], v[158:159], s[72:73] op_sel_hi:[1,1,0]
	v_and_b32_e32 v252, 0x7fffffff, v34
	v_pk_mul_f32 v[158:159], v[168:169], v[158:159]
	v_and_b32_e32 v249, 0x7fffffff, v33
	v_and_b32_e32 v248, 0x7fffffff, v32
	v_pk_fma_f32 v[168:169], v[248:249], s[28:29], 1.0 op_sel_hi:[1,0,0]
	v_pk_mul_f32 v[156:157], v[156:157], v[158:159]
	v_rcp_f32_e32 v168, v168
	v_rcp_f32_e32 v169, v169
	v_max_f32_e32 v240, 0, v42
	v_max_f32_e32 v241, 0, v43
	v_pk_fma_f32 v[156:157], v[250:251], v[156:157], v[240:241] neg_lo:[1,0,0] neg_hi:[1,0,0]
	v_pk_fma_f32 v[172:173], v[252:253], s[28:29], 1.0 op_sel_hi:[1,0,0]
	s_nop 0
	v_rcp_f32_e32 v172, v172
	v_rcp_f32_e32 v173, v173
	v_pk_fma_f32 v[158:159], v[168:169], s[30:31], v[160:161] op_sel_hi:[1,0,0]
	v_pk_mul_f32 v[170:171], v[32:33], v[32:33]
	v_pk_fma_f32 v[158:159], v[168:169], v[158:159], s[36:37] op_sel_hi:[1,1,0]
	v_pk_mul_f32 v[170:171], v[170:171], s[74:75] op_sel_hi:[1,0]
	v_pk_fma_f32 v[158:159], v[168:169], v[158:159], s[50:51] op_sel_hi:[1,1,0]
	v_exp_f32_e32 v170, v170
	v_pk_fma_f32 v[158:159], v[168:169], v[158:159], s[72:73] op_sel_hi:[1,1,0]
	v_exp_f32_e32 v171, v171
	v_pk_mul_f32 v[158:159], v[168:169], v[158:159]
	v_pk_mul_f32 v[168:169], v[34:35], v[34:35]
	v_pk_fma_f32 v[160:161], v[172:173], s[30:31], v[160:161] op_sel_hi:[1,0,0]
	v_pk_mul_f32 v[168:169], v[168:169], s[74:75] op_sel_hi:[1,0]
	v_pk_fma_f32 v[160:161], v[172:173], v[160:161], s[36:37] op_sel_hi:[1,1,0]
	v_exp_f32_e32 v168, v168
	v_exp_f32_e32 v169, v169
	v_pk_fma_f32 v[160:161], v[172:173], v[160:161], s[50:51] op_sel_hi:[1,1,0]
	v_pk_mul_f32 v[158:159], v[170:171], v[158:159]
	v_pk_fma_f32 v[160:161], v[172:173], v[160:161], s[72:73] op_sel_hi:[1,1,0]
	v_max_f32_e32 v240, 0, v32
	v_max_f32_e32 v241, 0, v33
	v_pk_fma_f32 v[158:159], v[248:249], v[158:159], v[240:241] neg_lo:[1,0,0] neg_hi:[1,0,0]
	v_pk_mul_f32 v[160:161], v[172:173], v[160:161]
	s_nop 0
	v_pk_mul_f32 v[160:161], v[168:169], v[160:161]
	s_nop 0
	v_max_f32_e32 v240, 0, v34
	v_max_f32_e32 v241, 0, v35
	v_pk_fma_f32 v[160:161], v[252:253], v[160:161], v[240:241] neg_lo:[1,0,0] neg_hi:[1,0,0]
	s_nop 1
	s_nop 1

; __device__ __forceinline__ f32x4 sigm4(f32x4 v) { return (f32x4){sigmoid_f(v[0]), sigmoid_f(v[1]), sigmoid_f(v[2]), sigmoid_f(v[3])}; }
; __device__ __forceinline__ f32x2 gelu_pk(f32x2 v) {
;     const f32x2 av = __builtin_elementwise_abs(v), d = av * 0.2316418882f + 1.0f;
;     f32x2 t; t.x = __builtin_amdgcn_rcpf(d.x); t.y = __builtin_amdgcn_rcpf(d.y);
;     f32x2 q = t * 0.5307027145f + (-0.7265760135f); q = q * t + 0.7107068705f; q = q * t + (-0.142248368f); q = q * t + 0.127414796f; q = q * t;
;     const f32x2 s = (v * v) * (-0.72134752044f);
;     f32x2 e; e.x = __builtin_amdgcn_exp2f(s.x); e.y = __builtin_amdgcn_exp2f(s.y);
;     const f32x2 m = v * (q * e), r = v - m;
;     f32x2 o; o.x = v.x < 0.f ? m.x : r.x; o.y = v.y < 0.f ? m.y : r.y; return o;
; }
; __device__ __forceinline__ f32x4 gelu4(f32x4 v) { f32x2 a = gelu_pk((f32x2){v[0], v[1]}), b = gelu_pk((f32x2){v[2], v[3]}); return (f32x4){a.x, a.y, b.x, b.y}; }
;     __device__ __forceinline__ void operator()(const f32x4 (&acc)[2][2][4][2], const pg8::Unit& u, int wr, int wc, int fr, int fq) const {
;     ...
;                     for (int bj = 0; bj < 2; ++bj) {
;                         f32x4 v0 = acc[ai][bj][m][0], v1 = acc[ai][bj][m][1];
;                         if (act == 5) { v0 = sigm4(v0); v1 = sigm4(v1);
;                             if (bj == 0) { const f32x4 b0 = sigm4(acc[ai][1][m][0]), b1 = sigm4(acc[ai][1][m][1]);
; #pragma unroll
;                                 for (int e = 0; e < 4; ++e) { v0[e] *= __builtin_amdgcn_rcpf(fmaxf(b0[e], 1e-20f)); v1[e] *= __builtin_amdgcn_rcpf(fmaxf(b1[e], 1e-20f)); } } }
;                         else if (act == 1) { v0 = gelu4(v0); v1 = gelu4(v1); }
.LBB0_363:
	s_andn2_b64 vcc, exec, s[16:17]
	s_cbranch_vccnz .LBB0_365
	v_and_b32_e32 v249, 0x7fffffff, v29
	v_and_b32_e32 v248, 0x7fffffff, v28
	v_pk_fma_f32 v[152:153], v[248:249], s[28:29], 1.0 op_sel_hi:[1,0,0]
	v_mov_b64_e32 v[160:161], s[34:35]
	v_rcp_f32_e32 v152, v152
	v_rcp_f32_e32 v153, v153
	v_pk_mul_f32 v[156:157], v[28:29], v[28:29]
	s_nop 0
	v_pk_mul_f32 v[156:157], v[156:157], s[74:75] op_sel_hi:[1,0]
	v_pk_fma_f32 v[154:155], v[152:153], s[30:31], v[160:161] op_sel_hi:[1,0,0]
	v_exp_f32_e32 v156, v156
	v_pk_fma_f32 v[154:155], v[152:153], v[154:155], s[36:37] op_sel_hi:[1,1,0]
	v_exp_f32_e32 v157, v157
	v_pk_fma_f32 v[154:155], v[152:153], v[154:155], s[50:51] op_sel_hi:[1,1,0]
	v_pk_mul_f32 v[158:159], v[30:31], v[30:31]
	v_pk_fma_f32 v[154:155], v[152:153], v[154:155], s[72:73] op_sel_hi:[1,1,0]
	v_pk_mul_f32 v[158:159], v[158:159], s[74:75] op_sel_hi:[1,0]
	v_pk_mul_f32 v[152:153], v[152:153], v[154:155]
	v_exp_f32_e32 v158, v158
	v_pk_mul_f32 v[152:153], v[156:157], v[152:153]
	v_and_b32_e32 v251, 0x7fffffff, v31
	v_and_b32_e32 v250, 0x7fffffff, v30
	v_pk_fma_f32 v[156:157], v[250:251], s[28:29], 1.0 op_sel_hi:[1,0,0]
	s_nop 0
	v_rcp_f32_e32 v156, v156
	v_rcp_f32_e32 v157, v157
	v_max_f32_e32 v240, 0, v28
	v_max_f32_e32 v241, 0, v29
	v_pk_fma_f32 v[154:155], v[248:249], v[152:153], v[240:241] neg_lo:[1,0,0] neg_hi:[1,0,0]
	v_exp_f32_e32 v159, v159
	v_pk_mul_f32 v[168:169], v[20:21], v[20:21]
	v_pk_mul_f32 v[170:171], v[22:23], v[22:23]
	v_pk_fma_f32 v[152:153], v[156:157], s[30:31], v[160:161] op_sel_hi:[1,0,0]
	s_nop 0
	v_pk_fma_f32 v[152:153], v[156:157], v[152:153], s[36:37] op_sel_hi:[1,1,0]
	v_pk_mul_f32 v[168:169], v[168:169], s[74:75] op_sel_hi:[1,0]
	v_pk_fma_f32 v[152:153], v[156:157], v[152:153], s[50:51] op_sel_hi:[1,1,0]
	v_exp_f32_e32 v168, v168
	v_pk_fma_f32 v[152:153], v[156:157], v[152:153], s[72:73] op_sel_hi:[1,1,0]
	v_exp_f32_e32 v169, v169
	v_pk_mul_f32 v[152:153], v[156:157], v[152:153]
	s_nop 0
	v_pk_mul_f32 v[152:153], v[158:159], v[152:153]
	v_and_b32_e32 v249, 0x7fffffff, v21
	v_and_b32_e32 v248, 0x7fffffff, v20
	v_pk_fma_f32 v[158:159], v[248:249], s[28:29], 1.0 op_sel_hi:[1,0,0]
	s_nop 0
	v_rcp_f32_e32 v158, v158
	v_rcp_f32_e32 v159, v159
	v_max_f32_e32 v240, 0, v30
	v_max_f32_e32 v241, 0, v31
	v_pk_fma_f32 v[156:157], v[250:251], v[152:153], v[240:241] neg_lo:[1,0,0] neg_hi:[1,0,0]
	s_nop 0
	s_nop 1
	v_pk_fma_f32 v[152:153], v[158:159], s[30:31], v[160:161] op_sel_hi:[1,0,0]
	s_nop 0
	v_pk_fma_f32 v[152:153], v[158:159], v[152:153], s[36:37] op_sel_hi:[1,1,0]
	s_nop 0
	v_pk_fma_f32 v[152:153], v[158:159], v[152:153], s[50:51] op_sel_hi:[1,1,0]
	s_nop 0
	v_pk_fma_f32 v[152:153], v[158:159], v[152:153], s[72:73] op_sel_hi:[1,1,0]
	s_nop 0
	v_pk_mul_f32 v[152:153], v[158:159], v[152:153]
	s_nop 0
	v_pk_mul_f32 v[152:153], v[168:169], v[152:153]
	v_and_b32_e32 v251, 0x7fffffff, v23
	v_and_b32_e32 v250, 0x7fffffff, v22
	v_pk_fma_f32 v[168:169], v[250:251], s[28:29], 1.0 op_sel_hi:[1,0,0]
	s_nop 0
	v_rcp_f32_e32 v168, v168
	v_rcp_f32_e32 v169, v169
	v_max_f32_e32 v240, 0, v20
	v_max_f32_e32 v241, 0, v21
	v_pk_fma_f32 v[158:159], v[248:249], v[152:153], v[240:241] neg_lo:[1,0,0] neg_hi:[1,0,0]
	s_nop 0
	s_nop 1
	v_pk_fma_f32 v[152:153], v[168:169], s[30:31], v[160:161] op_sel_hi:[1,0,0]
	v_pk_mul_f32 v[160:161], v[170:171], s[74:75] op_sel_hi:[1,0]
	v_pk_fma_f32 v[152:153], v[168:169], v[152:153], s[36:37] op_sel_hi:[1,1,0]
	v_exp_f32_e32 v160, v160
	v_exp_f32_e32 v161, v161
	v_pk_fma_f32 v[152:153], v[168:169], v[152:153], s[50:51] op_sel_hi:[1,1,0]
	s_nop 0
	v_pk_fma_f32 v[152:153], v[168:169], v[152:153], s[72:73] op_sel_hi:[1,1,0]
	s_nop 0
	v_pk_mul_f32 v[152:153], v[168:169], v[152:153]
	s_nop 0
	v_pk_mul_f32 v[152:153], v[160:161], v[152:153]
	s_nop 0
	v_max_f32_e32 v240, 0, v22
	v_max_f32_e32 v241, 0, v23
	v_pk_fma_f32 v[160:161], v[250:251], v[152:153], v[240:241] neg_lo:[1,0,0] neg_hi:[1,0,0]
	s_nop 0
	s_nop 1

; __device__ __forceinline__ f32x4 sigm4(f32x4 v) { return (f32x4){sigmoid_f(v[0]), sigmoid_f(v[1]), sigmoid_f(v[2]), sigmoid_f(v[3])}; }
; __device__ __forceinline__ f32x2 gelu_pk(f32x2 v) {
;     const f32x2 av = __builtin_elementwise_abs(v), d = av * 0.2316418882f + 1.0f;
;     f32x2 t; t.x = __builtin_amdgcn_rcpf(d.x); t.y = __builtin_amdgcn_rcpf(d.y);
;     f32x2 q = t * 0.5307027145f + (-0.7265760135f); q = q * t + 0.7107068705f; q = q * t + (-0.142248368f); q = q * t + 0.127414796f; q = q * t;
;     const f32x2 s = (v * v) * (-0.72134752044f);
;     f32x2 e; e.x = __builtin_amdgcn_exp2f(s.x); e.y = __builtin_amdgcn_exp2f(s.y);
;     const f32x2 m = v * (q * e), r = v - m;
;     f32x2 o; o.x = v.x < 0.f ? m.x : r.x; o.y = v.y < 0.f ? m.y : r.y; return o;
; }
; __device__ __forceinline__ f32x4 gelu4(f32x4 v) { f32x2 a = gelu_pk((f32x2){v[0], v[1]}), b = gelu_pk((f32x2){v[2], v[3]}); return (f32x4){a.x, a.y, b.x, b.y}; }
;     __device__ __forceinline__ void operator()(const f32x4 (&acc)[2][2][4][2], const pg8::Unit& u, int wr, int wc, int fr, int fq) const {
;     ...
;                     for (int bj = 0; bj < 2; ++bj) {
;                         f32x4 v0 = acc[ai][bj][m][0], v1 = acc[ai][bj][m][1];
;                         if (act == 5) { v0 = sigm4(v0); v1 = sigm4(v1);
;                             if (bj == 0) { const f32x4 b0 = sigm4(acc[ai][1][m][0]), b1 = sigm4(acc[ai][1][m][1]);
; #pragma unroll
;                                 for (int e = 0; e < 4; ++e) { v0[e] *= __builtin_amdgcn_rcpf(fmaxf(b0[e], 1e-20f)); v1[e] *= __builtin_amdgcn_rcpf(fmaxf(b1[e], 1e-20f)); } } }
;                         else if (act == 1) { v0 = gelu4(v0); v1 = gelu4(v1); }
.LBB0_377:
	s_andn2_b64 vcc, exec, s[16:17]
	s_cbranch_vccnz .LBB0_379
	v_and_b32_e32 v249, 0x7fffffff, v25
	v_and_b32_e32 v248, 0x7fffffff, v24
	v_pk_fma_f32 v[154:155], v[248:249], s[28:29], 1.0 op_sel_hi:[1,0,0]
	v_mov_b64_e32 v[160:161], s[34:35]
	v_rcp_f32_e32 v154, v154
	v_rcp_f32_e32 v155, v155
	v_pk_mul_f32 v[158:159], v[24:25], v[24:25]
	v_and_b32_e32 v251, 0x7fffffff, v27
	v_pk_mul_f32 v[158:159], v[158:159], s[74:75] op_sel_hi:[1,0]
	v_pk_fma_f32 v[156:157], v[154:155], s[30:31], v[160:161] op_sel_hi:[1,0,0]
	v_exp_f32_e32 v158, v158
	v_pk_fma_f32 v[156:157], v[154:155], v[156:157], s[36:37] op_sel_hi:[1,1,0]
	v_exp_f32_e32 v159, v159
	v_pk_fma_f32 v[156:157], v[154:155], v[156:157], s[50:51] op_sel_hi:[1,1,0]
	v_and_b32_e32 v250, 0x7fffffff, v26
	v_pk_fma_f32 v[156:157], v[154:155], v[156:157], s[72:73] op_sel_hi:[1,1,0]
	v_pk_fma_f32 v[168:169], v[250:251], s[28:29], 1.0 op_sel_hi:[1,0,0]
	v_pk_mul_f32 v[154:155], v[154:155], v[156:157]
	v_rcp_f32_e32 v168, v168
	v_rcp_f32_e32 v169, v169
	v_pk_mul_f32 v[154:155], v[158:159], v[154:155]
	v_max_f32_e32 v240, 0, v24
	v_max_f32_e32 v241, 0, v25
	v_pk_fma_f32 v[154:155], v[248:249], v[154:155], v[240:241] neg_lo:[1,0,0] neg_hi:[1,0,0]
	v_pk_mul_f32 v[156:157], v[26:27], v[26:27]
	s_nop 0
	v_pk_mul_f32 v[156:157], v[156:157], s[74:75] op_sel_hi:[1,0]
	v_and_b32_e32 v253, 0x7fffffff, v19
	v_pk_fma_f32 v[158:159], v[168:169], s[30:31], v[160:161] op_sel_hi:[1,0,0]
	v_exp_f32_e32 v156, v156
	v_pk_fma_f32 v[158:159], v[168:169], v[158:159], s[36:37] op_sel_hi:[1,1,0]
	v_exp_f32_e32 v157, v157
	v_pk_fma_f32 v[158:159], v[168:169], v[158:159], s[50:51] op_sel_hi:[1,1,0]
	s_nop 0
	v_pk_fma_f32 v[158:159], v[168:169], v[158:159], s[72:73] op_sel_hi:[1,1,0]
	v_and_b32_e32 v252, 0x7fffffff, v18
	v_pk_mul_f32 v[158:159], v[168:169], v[158:159]
	v_and_b32_e32 v249, 0x7fffffff, v17
	v_and_b32_e32 v248, 0x7fffffff, v16
	v_pk_fma_f32 v[168:169], v[248:249], s[28:29], 1.0 op_sel_hi:[1,0,0]
	v_pk_mul_f32 v[156:157], v[156:157], v[158:159]
	v_rcp_f32_e32 v168, v168
	v_rcp_f32_e32 v169, v169
	v_max_f32_e32 v240, 0, v26
	v_max_f32_e32 v241, 0, v27
	v_pk_fma_f32 v[156:157], v[250:251], v[156:157], v[240:241] neg_lo:[1,0,0] neg_hi:[1,0,0]
	v_pk_fma_f32 v[172:173], v[252:253], s[28:29], 1.0 op_sel_hi:[1,0,0]
	s_nop 0
	v_rcp_f32_e32 v172, v172
	v_rcp_f32_e32 v173, v173
	v_pk_fma_f32 v[158:159], v[168:169], s[30:31], v[160:161] op_sel_hi:[1,0,0]
	v_pk_mul_f32 v[170:171], v[16:17], v[16:17]
	v_pk_fma_f32 v[158:159], v[168:169], v[158:159], s[36:37] op_sel_hi:[1,1,0]
	v_pk_mul_f32 v[170:171], v[170:171], s[74:75] op_sel_hi:[1,0]
	v_pk_fma_f32 v[158:159], v[168:169], v[158:159], s[50:51] op_sel_hi:[1,1,0]
	v_exp_f32_e32 v170, v170
	v_pk_fma_f32 v[158:159], v[168:169], v[158:159], s[72:73] op_sel_hi:[1,1,0]
	v_exp_f32_e32 v171, v171
	v_pk_mul_f32 v[158:159], v[168:169], v[158:159]
	v_pk_mul_f32 v[168:169], v[18:19], v[18:19]
	v_pk_fma_f32 v[160:161], v[172:173], s[30:31], v[160:161] op_sel_hi:[1,0,0]
	v_pk_mul_f32 v[168:169], v[168:169], s[74:75] op_sel_hi:[1,0]
	v_pk_fma_f32 v[160:161], v[172:173], v[160:161], s[36:37] op_sel_hi:[1,1,0]
	v_exp_f32_e32 v168, v168
	v_exp_f32_e32 v169, v169
	v_pk_fma_f32 v[160:161], v[172:173], v[160:161], s[50:51] op_sel_hi:[1,1,0]
	v_pk_mul_f32 v[158:159], v[170:171], v[158:159]
	v_pk_fma_f32 v[160:161], v[172:173], v[160:161], s[72:73] op_sel_hi:[1,1,0]
	v_max_f32_e32 v240, 0, v16
	v_max_f32_e32 v241, 0, v17
	v_pk_fma_f32 v[158:159], v[248:249], v[158:159], v[240:241] neg_lo:[1,0,0] neg_hi:[1,0,0]
	v_pk_mul_f32 v[160:161], v[172:173], v[160:161]
	s_nop 0
	v_pk_mul_f32 v[160:161], v[168:169], v[160:161]
	s_nop 0
	v_max_f32_e32 v240, 0, v18
	v_max_f32_e32 v241, 0, v19
	v_pk_fma_f32 v[160:161], v[252:253], v[160:161], v[240:241] neg_lo:[1,0,0] neg_hi:[1,0,0]
	s_nop 1
	s_nop 1

; __device__ __forceinline__ f32x4 sigm4(f32x4 v) { return (f32x4){sigmoid_f(v[0]), sigmoid_f(v[1]), sigmoid_f(v[2]), sigmoid_f(v[3])}; }
; __device__ __forceinline__ f32x2 gelu_pk(f32x2 v) {
;     const f32x2 av = __builtin_elementwise_abs(v), d = av * 0.2316418882f + 1.0f;
;     f32x2 t; t.x = __builtin_amdgcn_rcpf(d.x); t.y = __builtin_amdgcn_rcpf(d.y);
;     f32x2 q = t * 0.5307027145f + (-0.7265760135f); q = q * t + 0.7107068705f; q = q * t + (-0.142248368f); q = q * t + 0.127414796f; q = q * t;
;     const f32x2 s = (v * v) * (-0.72134752044f);
;     f32x2 e; e.x = __builtin_amdgcn_exp2f(s.x); e.y = __builtin_amdgcn_exp2f(s.y);
;     const f32x2 m = v * (q * e), r = v - m;
;     f32x2 o; o.x = v.x < 0.f ? m.x : r.x; o.y = v.y < 0.f ? m.y : r.y; return o;
; }
; __device__ __forceinline__ f32x4 gelu4(f32x4 v) { f32x2 a = gelu_pk((f32x2){v[0], v[1]}), b = gelu_pk((f32x2){v[2], v[3]}); return (f32x4){a.x, a.y, b.x, b.y}; }
;     __device__ __forceinline__ void operator()(const f32x4 (&acc)[2][2][4][2], const pg8::Unit& u, int wr, int wc, int fr, int fq) const {
;     ...
;                     for (int bj = 0; bj < 2; ++bj) {
;                         f32x4 v0 = acc[ai][bj][m][0], v1 = acc[ai][bj][m][1];
;                         if (act == 5) { v0 = sigm4(v0); v1 = sigm4(v1);
;                             if (bj == 0) { const f32x4 b0 = sigm4(acc[ai][1][m][0]), b1 = sigm4(acc[ai][1][m][1]);
; #pragma unroll
;                                 for (int e = 0; e < 4; ++e) { v0[e] *= __builtin_amdgcn_rcpf(fmaxf(b0[e], 1e-20f)); v1[e] *= __builtin_amdgcn_rcpf(fmaxf(b1[e], 1e-20f)); } } }
;                         else if (act == 1) { v0 = gelu4(v0); v1 = gelu4(v1); }
.LBB0_391:
	s_andn2_b64 vcc, exec, s[16:17]
	s_cbranch_vccnz .LBB0_393
	v_and_b32_e32 v249, 0x7fffffff, v13
	v_and_b32_e32 v248, 0x7fffffff, v12
	v_pk_fma_f32 v[152:153], v[248:249], s[28:29], 1.0 op_sel_hi:[1,0,0]
	v_mov_b64_e32 v[158:159], s[34:35]
	v_rcp_f32_e32 v152, v152
	v_rcp_f32_e32 v153, v153
	v_pk_mul_f32 v[156:157], v[12:13], v[12:13]
	v_and_b32_e32 v251, 0x7fffffff, v15
	v_pk_mul_f32 v[156:157], v[156:157], s[74:75] op_sel_hi:[1,0]
	v_pk_fma_f32 v[154:155], v[152:153], s[30:31], v[158:159] op_sel_hi:[1,0,0]
	v_exp_f32_e32 v156, v156
	v_pk_fma_f32 v[154:155], v[152:153], v[154:155], s[36:37] op_sel_hi:[1,1,0]
	v_exp_f32_e32 v157, v157
	v_pk_fma_f32 v[154:155], v[152:153], v[154:155], s[50:51] op_sel_hi:[1,1,0]
	v_and_b32_e32 v250, 0x7fffffff, v14
	v_pk_fma_f32 v[154:155], v[152:153], v[154:155], s[72:73] op_sel_hi:[1,1,0]
	v_pk_fma_f32 v[160:161], v[250:251], s[28:29], 1.0 op_sel_hi:[1,0,0]
	v_pk_mul_f32 v[152:153], v[152:153], v[154:155]
	v_rcp_f32_e32 v160, v160
	v_rcp_f32_e32 v161, v161
	v_pk_mul_f32 v[152:153], v[156:157], v[152:153]
	v_max_f32_e32 v240, 0, v12
	v_max_f32_e32 v241, 0, v13
	v_pk_fma_f32 v[152:153], v[248:249], v[152:153], v[240:241] neg_lo:[1,0,0] neg_hi:[1,0,0]
	v_pk_mul_f32 v[154:155], v[14:15], v[14:15]
	s_nop 0
	v_pk_mul_f32 v[154:155], v[154:155], s[74:75] op_sel_hi:[1,0]
	v_and_b32_e32 v253, 0x7fffffff, v7
	v_pk_fma_f32 v[156:157], v[160:161], s[30:31], v[158:159] op_sel_hi:[1,0,0]
	v_exp_f32_e32 v154, v154
	v_pk_fma_f32 v[156:157], v[160:161], v[156:157], s[36:37] op_sel_hi:[1,1,0]
	v_exp_f32_e32 v155, v155
	v_pk_fma_f32 v[156:157], v[160:161], v[156:157], s[50:51] op_sel_hi:[1,1,0]
	s_nop 0
	v_pk_fma_f32 v[156:157], v[160:161], v[156:157], s[72:73] op_sel_hi:[1,1,0]
	v_and_b32_e32 v252, 0x7fffffff, v6
	v_pk_mul_f32 v[156:157], v[160:161], v[156:157]
	v_and_b32_e32 v249, 0x7fffffff, v5
	v_and_b32_e32 v248, 0x7fffffff, v4
	v_pk_fma_f32 v[160:161], v[248:249], s[28:29], 1.0 op_sel_hi:[1,0,0]
	v_pk_mul_f32 v[154:155], v[154:155], v[156:157]
	v_rcp_f32_e32 v160, v160
	v_rcp_f32_e32 v161, v161
	v_max_f32_e32 v240, 0, v14
	v_max_f32_e32 v241, 0, v15
	v_pk_fma_f32 v[154:155], v[250:251], v[154:155], v[240:241] neg_lo:[1,0,0] neg_hi:[1,0,0]
	v_pk_fma_f32 v[170:171], v[252:253], s[28:29], 1.0 op_sel_hi:[1,0,0]
	s_nop 0
	v_rcp_f32_e32 v170, v170
	v_rcp_f32_e32 v171, v171
	v_pk_fma_f32 v[156:157], v[160:161], s[30:31], v[158:159] op_sel_hi:[1,0,0]
	v_pk_mul_f32 v[168:169], v[4:5], v[4:5]
	v_pk_fma_f32 v[156:157], v[160:161], v[156:157], s[36:37] op_sel_hi:[1,1,0]
	v_pk_mul_f32 v[168:169], v[168:169], s[74:75] op_sel_hi:[1,0]
	v_pk_fma_f32 v[156:157], v[160:161], v[156:157], s[50:51] op_sel_hi:[1,1,0]
	v_exp_f32_e32 v168, v168
	v_pk_fma_f32 v[156:157], v[160:161], v[156:157], s[72:73] op_sel_hi:[1,1,0]
	v_exp_f32_e32 v169, v169
	v_pk_mul_f32 v[156:157], v[160:161], v[156:157]
	v_pk_mul_f32 v[160:161], v[6:7], v[6:7]
	v_pk_fma_f32 v[158:159], v[170:171], s[30:31], v[158:159] op_sel_hi:[1,0,0]
	v_pk_mul_f32 v[160:161], v[160:161], s[74:75] op_sel_hi:[1,0]
	v_pk_fma_f32 v[158:159], v[170:171], v[158:159], s[36:37] op_sel_hi:[1,1,0]
	v_exp_f32_e32 v160, v160
	v_exp_f32_e32 v161, v161
	v_pk_fma_f32 v[158:159], v[170:171], v[158:159], s[50:51] op_sel_hi:[1,1,0]
	v_pk_mul_f32 v[156:157], v[168:169], v[156:157]
	v_pk_fma_f32 v[158:159], v[170:171], v[158:159], s[72:73] op_sel_hi:[1,1,0]
	v_max_f32_e32 v240, 0, v4
	v_max_f32_e32 v241, 0, v5
	v_pk_fma_f32 v[156:157], v[248:249], v[156:157], v[240:241] neg_lo:[1,0,0] neg_hi:[1,0,0]
	v_pk_mul_f32 v[158:159], v[170:171], v[158:159]
	s_nop 0
	v_pk_mul_f32 v[158:159], v[160:161], v[158:159]
	s_nop 0
	v_max_f32_e32 v240, 0, v6
	v_max_f32_e32 v241, 0, v7
	v_pk_fma_f32 v[158:159], v[252:253], v[158:159], v[240:241] neg_lo:[1,0,0] neg_hi:[1,0,0]
	s_nop 1
	s_nop 1

; __device__ __forceinline__ f32x4 sigm4(f32x4 v) { return (f32x4){sigmoid_f(v[0]), sigmoid_f(v[1]), sigmoid_f(v[2]), sigmoid_f(v[3])}; }
; __device__ __forceinline__ f32x2 gelu_pk(f32x2 v) {
;     const f32x2 av = __builtin_elementwise_abs(v), d = av * 0.2316418882f + 1.0f;
;     f32x2 t; t.x = __builtin_amdgcn_rcpf(d.x); t.y = __builtin_amdgcn_rcpf(d.y);
;     f32x2 q = t * 0.5307027145f + (-0.7265760135f); q = q * t + 0.7107068705f; q = q * t + (-0.142248368f); q = q * t + 0.127414796f; q = q * t;
;     const f32x2 s = (v * v) * (-0.72134752044f);
;     f32x2 e; e.x = __builtin_amdgcn_exp2f(s.x); e.y = __builtin_amdgcn_exp2f(s.y);
;     const f32x2 m = v * (q * e), r = v - m;
;     f32x2 o; o.x = v.x < 0.f ? m.x : r.x; o.y = v.y < 0.f ? m.y : r.y; return o;
; }
; __device__ __forceinline__ f32x4 gelu4(f32x4 v) { f32x2 a = gelu_pk((f32x2){v[0], v[1]}), b = gelu_pk((f32x2){v[2], v[3]}); return (f32x4){a.x, a.y, b.x, b.y}; }
;     __device__ __forceinline__ void operator()(const f32x4 (&acc)[2][2][4][2], const pg8::Unit& u, int wr, int wc, int fr, int fq) const {
;     ...
;                     for (int bj = 0; bj < 2; ++bj) {
;                         f32x4 v0 = acc[ai][bj][m][0], v1 = acc[ai][bj][m][1];
;                         if (act == 5) { v0 = sigm4(v0); v1 = sigm4(v1);
;                             if (bj == 0) { const f32x4 b0 = sigm4(acc[ai][1][m][0]), b1 = sigm4(acc[ai][1][m][1]);
; #pragma unroll
;                                 for (int e = 0; e < 4; ++e) { v0[e] *= __builtin_amdgcn_rcpf(fmaxf(b0[e], 1e-20f)); v1[e] *= __builtin_amdgcn_rcpf(fmaxf(b1[e], 1e-20f)); } } }
;                         else if (act == 1) { v0 = gelu4(v0); v1 = gelu4(v1); }
.LBB0_405:
	s_andn2_b64 vcc, exec, s[6:7]
	s_cbranch_vccnz .LBB0_407
	v_and_b32_e32 v249, 0x7fffffff, v9
	v_and_b32_e32 v248, 0x7fffffff, v8
	v_pk_fma_f32 v[150:151], v[248:249], s[28:29], 1.0 op_sel_hi:[1,0,0]
	v_mov_b64_e32 v[156:157], s[34:35]
	v_rcp_f32_e32 v150, v150
	v_rcp_f32_e32 v151, v151
	v_pk_mul_f32 v[154:155], v[8:9], v[8:9]
	v_and_b32_e32 v251, 0x7fffffff, v11
	v_pk_mul_f32 v[154:155], v[154:155], s[74:75] op_sel_hi:[1,0]
	v_pk_fma_f32 v[152:153], v[150:151], s[30:31], v[156:157] op_sel_hi:[1,0,0]
	v_exp_f32_e32 v154, v154
	v_pk_fma_f32 v[152:153], v[150:151], v[152:153], s[36:37] op_sel_hi:[1,1,0]
	v_exp_f32_e32 v155, v155
	v_pk_fma_f32 v[152:153], v[150:151], v[152:153], s[50:51] op_sel_hi:[1,1,0]
	v_and_b32_e32 v250, 0x7fffffff, v10
	v_pk_fma_f32 v[152:153], v[150:151], v[152:153], s[72:73] op_sel_hi:[1,1,0]
	v_pk_fma_f32 v[158:159], v[250:251], s[28:29], 1.0 op_sel_hi:[1,0,0]
	v_pk_mul_f32 v[150:151], v[150:151], v[152:153]
	v_rcp_f32_e32 v158, v158
	v_rcp_f32_e32 v159, v159
	v_pk_mul_f32 v[150:151], v[154:155], v[150:151]
	v_max_f32_e32 v240, 0, v8
	v_max_f32_e32 v241, 0, v9
	v_pk_fma_f32 v[150:151], v[248:249], v[150:151], v[240:241] neg_lo:[1,0,0] neg_hi:[1,0,0]
	v_pk_mul_f32 v[152:153], v[10:11], v[10:11]
	s_nop 0
	v_pk_mul_f32 v[152:153], v[152:153], s[74:75] op_sel_hi:[1,0]
	v_and_b32_e32 v253, 0x7fffffff, v3
	v_pk_fma_f32 v[154:155], v[158:159], s[30:31], v[156:157] op_sel_hi:[1,0,0]
	v_exp_f32_e32 v152, v152
	v_pk_fma_f32 v[154:155], v[158:159], v[154:155], s[36:37] op_sel_hi:[1,1,0]
	v_exp_f32_e32 v153, v153
	v_pk_fma_f32 v[154:155], v[158:159], v[154:155], s[50:51] op_sel_hi:[1,1,0]
	s_nop 0
	v_pk_fma_f32 v[154:155], v[158:159], v[154:155], s[72:73] op_sel_hi:[1,1,0]
	v_and_b32_e32 v252, 0x7fffffff, v2
	v_pk_mul_f32 v[154:155], v[158:159], v[154:155]
	v_and_b32_e32 v249, 0x7fffffff, v1
	v_and_b32_e32 v248, 0x7fffffff, v0
	v_pk_fma_f32 v[158:159], v[248:249], s[28:29], 1.0 op_sel_hi:[1,0,0]
	v_pk_mul_f32 v[152:153], v[152:153], v[154:155]
	v_rcp_f32_e32 v158, v158
	v_rcp_f32_e32 v159, v159
	v_max_f32_e32 v240, 0, v10
	v_max_f32_e32 v241, 0, v11
	v_pk_fma_f32 v[152:153], v[250:251], v[152:153], v[240:241] neg_lo:[1,0,0] neg_hi:[1,0,0]
	v_pk_fma_f32 v[168:169], v[252:253], s[28:29], 1.0 op_sel_hi:[1,0,0]
	s_nop 0
	v_rcp_f32_e32 v168, v168
	v_rcp_f32_e32 v169, v169
	v_pk_fma_f32 v[154:155], v[158:159], s[30:31], v[156:157] op_sel_hi:[1,0,0]
	v_pk_mul_f32 v[160:161], v[0:1], v[0:1]
	v_pk_fma_f32 v[154:155], v[158:159], v[154:155], s[36:37] op_sel_hi:[1,1,0]
	v_pk_mul_f32 v[160:161], v[160:161], s[74:75] op_sel_hi:[1,0]
	v_pk_fma_f32 v[154:155], v[158:159], v[154:155], s[50:51] op_sel_hi:[1,1,0]
	v_exp_f32_e32 v160, v160
	v_pk_fma_f32 v[154:155], v[158:159], v[154:155], s[72:73] op_sel_hi:[1,1,0]
	v_exp_f32_e32 v161, v161
	v_pk_mul_f32 v[154:155], v[158:159], v[154:155]
	v_pk_mul_f32 v[158:159], v[2:3], v[2:3]
	v_pk_fma_f32 v[156:157], v[168:169], s[30:31], v[156:157] op_sel_hi:[1,0,0]
	v_pk_mul_f32 v[158:159], v[158:159], s[74:75] op_sel_hi:[1,0]
	v_pk_fma_f32 v[156:157], v[168:169], v[156:157], s[36:37] op_sel_hi:[1,1,0]
	v_exp_f32_e32 v158, v158
	v_exp_f32_e32 v159, v159
	v_pk_fma_f32 v[156:157], v[168:169], v[156:157], s[50:51] op_sel_hi:[1,1,0]
	v_pk_mul_f32 v[154:155], v[160:161], v[154:155]
	v_pk_fma_f32 v[156:157], v[168:169], v[156:157], s[72:73] op_sel_hi:[1,1,0]
	v_max_f32_e32 v240, 0, v0
	v_max_f32_e32 v241, 0, v1
	v_pk_fma_f32 v[154:155], v[248:249], v[154:155], v[240:241] neg_lo:[1,0,0] neg_hi:[1,0,0]
	v_pk_mul_f32 v[156:157], v[168:169], v[156:157]
	s_nop 0
	v_pk_mul_f32 v[156:157], v[158:159], v[156:157]
	s_nop 0
	v_max_f32_e32 v240, 0, v2
	v_max_f32_e32 v241, 0, v3
	v_pk_fma_f32 v[156:157], v[252:253], v[156:157], v[240:241] neg_lo:[1,0,0] neg_hi:[1,0,0]
	s_nop 1
	s_nop 1

; __device__ __forceinline__ unsigned cvt_pk_bf16(float lo, float hi) { unsigned r; asm volatile("v_cvt_pk_bf16_f32 %0, %1, %2" : "=v"(r) : "v"(lo), "v"(hi)); return r; }
; __device__ __forceinline__ float sigmoid_f(float x) { return __builtin_amdgcn_rcpf(1.0f + __builtin_amdgcn_exp2f(-1.44269504f * x)); }
; __device__ __forceinline__ f32x2 gelu_pk(f32x2 v) {
;     const f32x2 av = __builtin_elementwise_abs(v), d = av * 0.2316418882f + 1.0f;
;     f32x2 t; t.x = __builtin_amdgcn_rcpf(d.x); t.y = __builtin_amdgcn_rcpf(d.y);
;     f32x2 q = t * 0.5307027145f + (-0.7265760135f); q = q * t + 0.7107068705f; q = q * t + (-0.142248368f); q = q * t + 0.127414796f; q = q * t;
;     const f32x2 s = (v * v) * (-0.72134752044f);
;     f32x2 e; e.x = __builtin_amdgcn_exp2f(s.x); e.y = __builtin_amdgcn_exp2f(s.y);
;     const f32x2 m = v * (q * e), r = v - m;
;     f32x2 o; o.x = v.x < 0.f ? m.x : r.x; o.y = v.y < 0.f ? m.y : r.y; return o;
; }
; __device__ __forceinline__ f32x4 gelu4(f32x4 v) { f32x2 a = gelu_pk((f32x2){v[0], v[1]}), b = gelu_pk((f32x2){v[2], v[3]}); return (f32x4){a.x, a.y, b.x, b.y}; }
; __device__ __forceinline__ f32x4 sigm4(f32x4 v) { return (f32x4){sigmoid_f(v[0]), sigmoid_f(v[1]), sigmoid_f(v[2]), sigmoid_f(v[3])}; }
; __device__ __forceinline__ f32x4 silu4(f32x4 v) { return v * sigm4(v); }
;     __device__ __forceinline__ void operator()(const f32x4 (&acc)[2][2][4][2], const pg8::Unit& u, int wr, int wc, int fr, int fq) const {
;     ...
;                 for (int m = 0; m < 4; ++m) {
;                     bf16_t* rowp = base + (size_t)(row0 + ai * 128 + m * 16) * 1024;
;                     const f32x4 v0 = gelu4(acc[ai][0][m][0]) * silu4(acc[ai][1][m][0]), v1 = gelu4(acc[ai][0][m][1]) * silu4(acc[ai][1][m][1]);
;                     u32x4 w; w.x = cvt_pk_bf16(v0[0], v0[1]); w.y = cvt_pk_bf16(v0[2], v0[3]); w.z = cvt_pk_bf16(v1[0], v1[1]); w.w = cvt_pk_bf16(v1[2], v1[3]);
;                     __builtin_nontemporal_store(w, (u32x4*)rowp);
.LBB0_411:
	v_and_b32_e32 v249, 0x7fffffff, v125
	v_and_b32_e32 v248, 0x7fffffff, v124
	v_pk_fma_f32 v[148:149], v[248:249], s[28:29], 1.0 op_sel_hi:[1,0,0]
	v_mov_b64_e32 v[150:151], s[34:35]
	v_rcp_f32_e32 v154, v148
	v_rcp_f32_e32 v155, v149
	v_pk_mul_f32 v[158:159], v[124:125], v[124:125]
	v_and_b32_e32 v251, 0x7fffffff, v127
	v_pk_mul_f32 v[158:159], v[158:159], s[74:75] op_sel_hi:[1,0]
	v_pk_fma_f32 v[156:157], v[154:155], s[30:31], v[150:151] op_sel_hi:[1,0,0]
	v_exp_f32_e32 v158, v158
	v_pk_fma_f32 v[156:157], v[154:155], v[156:157], s[36:37] op_sel_hi:[1,1,0]
	v_exp_f32_e32 v159, v159
	v_pk_fma_f32 v[156:157], v[154:155], v[156:157], s[50:51] op_sel_hi:[1,1,0]
	v_and_b32_e32 v250, 0x7fffffff, v126
	v_pk_fma_f32 v[156:157], v[154:155], v[156:157], s[72:73] op_sel_hi:[1,1,0]
	v_pk_fma_f32 v[160:161], v[250:251], s[28:29], 1.0 op_sel_hi:[1,0,0]
	v_pk_mul_f32 v[154:155], v[154:155], v[156:157]
	v_rcp_f32_e32 v160, v160
	v_rcp_f32_e32 v161, v161
	v_pk_mul_f32 v[154:155], v[158:159], v[154:155]
	v_max_f32_e32 v240, 0, v124
	v_max_f32_e32 v241, 0, v125
	v_pk_fma_f32 v[124:125], v[248:249], v[154:155], v[240:241] neg_lo:[1,0,0] neg_hi:[1,0,0]
	v_pk_mul_f32 v[156:157], v[126:127], v[126:127]
	s_nop 0
	v_pk_mul_f32 v[156:157], v[156:157], s[74:75] op_sel_hi:[1,0]
	v_ashrrev_i32_e32 v147, 31, v146
	v_pk_fma_f32 v[154:155], v[160:161], s[30:31], v[150:151] op_sel_hi:[1,0,0]
	v_exp_f32_e32 v156, v156
	v_pk_fma_f32 v[154:155], v[160:161], v[154:155], s[36:37] op_sel_hi:[1,1,0]
	v_exp_f32_e32 v157, v157
	v_pk_fma_f32 v[154:155], v[160:161], v[154:155], s[50:51] op_sel_hi:[1,1,0]
	v_lshlrev_b64 v[148:149], 11, v[146:147]
	v_pk_fma_f32 v[154:155], v[160:161], v[154:155], s[72:73] op_sel_hi:[1,1,0]
	s_nop 0
	v_pk_mul_f32 v[154:155], v[160:161], v[154:155]
	v_mul_f32_e32 v147, 0xbfb8aa3b, v120
	v_pk_mul_f32 v[154:155], v[156:157], v[154:155]
	v_exp_f32_e32 v147, v147
	v_max_f32_e32 v240, 0, v126
	v_max_f32_e32 v241, 0, v127
	v_pk_fma_f32 v[126:127], v[250:251], v[154:155], v[240:241] neg_lo:[1,0,0] neg_hi:[1,0,0]
	s_lshl_b32 s6, s84, 7
	v_mul_f32_e32 v154, 0xbfb8aa3b, v121
	v_exp_f32_e32 v156, v154
	v_add_f32_e32 v147, 1.0, v147
	v_rcp_f32_e32 v154, v147
	v_mul_f32_e32 v155, 0xbfb8aa3b, v122
	v_add_f32_e32 v147, 1.0, v156
	v_exp_f32_e32 v156, v155
	v_mul_f32_e32 v155, 0xbfb8aa3b, v123
	v_exp_f32_e32 v157, v155
	v_rcp_f32_e32 v155, v147
	v_add_f32_e32 v147, 1.0, v156
	v_rcp_f32_e32 v156, v147
	v_add_f32_e32 v147, 1.0, v157
	v_rcp_f32_e32 v157, v147
	v_pk_mul_f32 v[120:121], v[120:121], v[154:155]
	v_and_b32_e32 v249, 0x7fffffff, v117
	v_and_b32_e32 v248, 0x7fffffff, v116
	v_pk_fma_f32 v[154:155], v[248:249], s[28:29], 1.0 op_sel_hi:[1,0,0]
	v_pk_mul_f32 v[122:123], v[122:123], v[156:157]
	v_rcp_f32_e32 v154, v154
	v_rcp_f32_e32 v155, v155
	v_pk_mul_f32 v[122:123], v[126:127], v[122:123]
	v_pk_mul_f32 v[126:127], v[116:117], v[116:117]
	v_pk_mul_f32 v[120:121], v[124:125], v[120:121]
	v_pk_fma_f32 v[124:125], v[154:155], s[30:31], v[150:151] op_sel_hi:[1,0,0]
	v_pk_mul_f32 v[126:127], v[126:127], s[74:75] op_sel_hi:[1,0]
	v_pk_fma_f32 v[124:125], v[154:155], v[124:125], s[36:37] op_sel_hi:[1,1,0]
	v_exp_f32_e32 v126, v126
	v_exp_f32_e32 v127, v127
	v_pk_fma_f32 v[124:125], v[154:155], v[124:125], s[50:51] op_sel_hi:[1,1,0]
	v_and_b32_e32 v251, 0x7fffffff, v119
	v_and_b32_e32 v250, 0x7fffffff, v118
	v_pk_fma_f32 v[124:125], v[154:155], v[124:125], s[72:73] op_sel_hi:[1,1,0]
	v_pk_fma_f32 v[156:157], v[250:251], s[28:29], 1.0 op_sel_hi:[1,0,0]
	v_pk_mul_f32 v[124:125], v[154:155], v[124:125]
	v_rcp_f32_e32 v156, v156
	v_rcp_f32_e32 v157, v157
	v_pk_mul_f32 v[124:125], v[126:127], v[124:125]
	v_max_f32_e32 v240, 0, v116
	v_max_f32_e32 v241, 0, v117
	v_pk_fma_f32 v[116:117], v[248:249], v[124:125], v[240:241] neg_lo:[1,0,0] neg_hi:[1,0,0]
	v_pk_mul_f32 v[154:155], v[118:119], v[118:119]
	v_mul_f32_e32 v147, 0xbfb8aa3b, v112
	v_exp_f32_e32 v147, v147
	v_pk_fma_f32 v[124:125], v[156:157], s[30:31], v[150:151] op_sel_hi:[1,0,0]
	v_pk_mul_f32 v[126:127], v[154:155], s[74:75] op_sel_hi:[1,0]
	v_pk_fma_f32 v[124:125], v[156:157], v[124:125], s[36:37] op_sel_hi:[1,1,0]
	v_exp_f32_e32 v126, v126
	v_exp_f32_e32 v127, v127
	v_pk_fma_f32 v[124:125], v[156:157], v[124:125], s[50:51] op_sel_hi:[1,1,0]
	v_mul_f32_e32 v154, 0xbfb8aa3b, v113
	v_pk_fma_f32 v[124:125], v[156:157], v[124:125], s[72:73] op_sel_hi:[1,1,0]
	s_nop 0
	v_pk_mul_f32 v[124:125], v[156:157], v[124:125]
	v_exp_f32_e32 v155, v154
	v_pk_mul_f32 v[124:125], v[126:127], v[124:125]
	s_ashr_i32 s7, s6, 31
	v_max_f32_e32 v240, 0, v118
	v_max_f32_e32 v241, 0, v119
	v_pk_fma_f32 v[118:119], v[250:251], v[124:125], v[240:241] neg_lo:[1,0,0] neg_hi:[1,0,0]
	v_lshl_add_u64 v[152:153], s[6:7], 1, v[136:137]
	v_mul_f32_e32 v126, 0xbfb8aa3b, v114
	v_add_f32_e32 v124, 1.0, v147
	v_exp_f32_e32 v126, v126
	v_mul_f32_e32 v147, 0xbfb8aa3b, v115
	v_exp_f32_e32 v147, v147
	v_rcp_f32_e32 v154, v124
	v_add_f32_e32 v124, 1.0, v155
	v_rcp_f32_e32 v155, v124
	v_add_f32_e32 v124, 1.0, v126
	v_rcp_f32_e32 v156, v124
	v_add_f32_e32 v124, 1.0, v147
	v_rcp_f32_e32 v157, v124
	v_pk_mul_f32 v[112:113], v[112:113], v[154:155]
	v_lshl_add_u64 v[148:149], v[152:153], 0, v[148:149]
	v_pk_mul_f32 v[114:115], v[114:115], v[156:157]
	s_nop 0
	v_pk_mul_f32 v[118:119], v[118:119], v[114:115]
	v_pk_mul_f32 v[114:115], v[116:117], v[112:113]
	v_cvt_pk_bf16_f32 v112, v120, v121
	v_cvt_pk_bf16_f32 v113, v122, v123
	v_and_b32_e32 v251, 0x7fffffff, v111
	v_cvt_pk_bf16_f32 v114, v114, v115
	v_cvt_pk_bf16_f32 v115, v118, v119
	global_store_dwordx4 v[148:149], v[112:115], off nt
	s_cmp_lg_u64 s[24:25], 0
	s_cbranch_scc0 .Lepi_nb_b
	s_barrier
; __device__ __forceinline__ unsigned cvt_pk_bf16(float lo, float hi) { unsigned r; asm volatile("v_cvt_pk_bf16_f32 %0, %1, %2" : "=v"(r) : "v"(lo), "v"(hi)); return r; }
; __device__ __forceinline__ float sigmoid_f(float x) { return __builtin_amdgcn_rcpf(1.0f + __builtin_amdgcn_exp2f(-1.44269504f * x)); }
; __device__ __forceinline__ f32x2 gelu_pk(f32x2 v) {
;     const f32x2 av = __builtin_elementwise_abs(v), d = av * 0.2316418882f + 1.0f;
;     f32x2 t; t.x = __builtin_amdgcn_rcpf(d.x); t.y = __builtin_amdgcn_rcpf(d.y);
;     f32x2 q = t * 0.5307027145f + (-0.7265760135f); q = q * t + 0.7107068705f; q = q * t + (-0.142248368f); q = q * t + 0.127414796f; q = q * t;
;     const f32x2 s = (v * v) * (-0.72134752044f);
;     f32x2 e; e.x = __builtin_amdgcn_exp2f(s.x); e.y = __builtin_amdgcn_exp2f(s.y);
;     const f32x2 m = v * (q * e), r = v - m;
;     f32x2 o; o.x = v.x < 0.f ? m.x : r.x; o.y = v.y < 0.f ? m.y : r.y; return o;
; }
; __device__ __forceinline__ f32x4 gelu4(f32x4 v) { f32x2 a = gelu_pk((f32x2){v[0], v[1]}), b = gelu_pk((f32x2){v[2], v[3]}); return (f32x4){a.x, a.y, b.x, b.y}; }
; __device__ __forceinline__ f32x4 sigm4(f32x4 v) { return (f32x4){sigmoid_f(v[0]), sigmoid_f(v[1]), sigmoid_f(v[2]), sigmoid_f(v[3])}; }
; __device__ __forceinline__ f32x4 silu4(f32x4 v) { return v * sigm4(v); }
;     __device__ __forceinline__ void operator()(const f32x4 (&acc)[2][2][4][2], const pg8::Unit& u, int wr, int wc, int fr, int fq) const {
;     ...
;                 for (int m = 0; m < 4; ++m) {
;                     bf16_t* rowp = base + (size_t)(row0 + ai * 128 + m * 16) * 1024;
;                     const f32x4 v0 = gelu4(acc[ai][0][m][0]) * silu4(acc[ai][1][m][0]), v1 = gelu4(acc[ai][0][m][1]) * silu4(acc[ai][1][m][1]);
;                     u32x4 w; w.x = cvt_pk_bf16(v0[0], v0[1]); w.y = cvt_pk_bf16(v0[2], v0[3]); w.z = cvt_pk_bf16(v1[0], v1[1]); w.w = cvt_pk_bf16(v1[2], v1[3]);
;                     __builtin_nontemporal_store(w, (u32x4*)rowp);
.Lepi_nb_b:
	v_pk_mul_f32 v[118:119], v[108:109], v[108:109]
	v_and_b32_e32 v250, 0x7fffffff, v110
	v_and_b32_e32 v249, 0x7fffffff, v109
	v_and_b32_e32 v248, 0x7fffffff, v108
	v_pk_fma_f32 v[114:115], v[248:249], s[28:29], 1.0 op_sel_hi:[1,0,0]
	v_pk_mul_f32 v[118:119], v[118:119], s[74:75] op_sel_hi:[1,0]
	v_rcp_f32_e32 v114, v114
	v_rcp_f32_e32 v115, v115
	v_exp_f32_e32 v118, v118
	v_exp_f32_e32 v119, v119
	v_pk_fma_f32 v[120:121], v[250:251], s[28:29], 1.0 op_sel_hi:[1,0,0]
	v_pk_fma_f32 v[116:117], v[114:115], s[30:31], v[150:151] op_sel_hi:[1,0,0]
	v_rcp_f32_e32 v120, v120
	v_pk_fma_f32 v[116:117], v[114:115], v[116:117], s[36:37] op_sel_hi:[1,1,0]
	v_rcp_f32_e32 v121, v121
	v_pk_fma_f32 v[116:117], v[114:115], v[116:117], s[50:51] op_sel_hi:[1,1,0]
	v_or_b32_e32 v112, 16, v146
	v_pk_fma_f32 v[116:117], v[114:115], v[116:117], s[72:73] op_sel_hi:[1,1,0]
	v_ashrrev_i32_e32 v113, 31, v112
	v_pk_mul_f32 v[114:115], v[114:115], v[116:117]
	v_pk_mul_f32 v[116:117], v[110:111], v[110:111]
	v_pk_mul_f32 v[114:115], v[118:119], v[114:115]
	v_pk_mul_f32 v[116:117], v[116:117], s[74:75] op_sel_hi:[1,0]
	v_max_f32_e32 v240, 0, v108
	v_max_f32_e32 v241, 0, v109
	v_pk_fma_f32 v[108:109], v[248:249], v[114:115], v[240:241] neg_lo:[1,0,0] neg_hi:[1,0,0]
	v_exp_f32_e32 v116, v116
	v_exp_f32_e32 v117, v117
	v_lshlrev_b64 v[112:113], 11, v[112:113]
	v_pk_fma_f32 v[114:115], v[120:121], s[30:31], v[150:151] op_sel_hi:[1,0,0]
	s_nop 0
	v_pk_fma_f32 v[114:115], v[120:121], v[114:115], s[36:37] op_sel_hi:[1,1,0]
	v_lshl_add_u64 v[112:113], v[152:153], 0, v[112:113]
	v_pk_fma_f32 v[114:115], v[120:121], v[114:115], s[50:51] op_sel_hi:[1,1,0]
	s_mov_b32 s6, 0x40000
	v_pk_fma_f32 v[114:115], v[120:121], v[114:115], s[72:73] op_sel_hi:[1,1,0]
	s_nop 0
	v_pk_mul_f32 v[114:115], v[120:121], v[114:115]
	s_nop 0
	v_pk_mul_f32 v[114:115], v[116:117], v[114:115]
	s_nop 0
	v_max_f32_e32 v240, 0, v110
	v_max_f32_e32 v241, 0, v111
	v_pk_fma_f32 v[110:111], v[250:251], v[114:115], v[240:241] neg_lo:[1,0,0] neg_hi:[1,0,0]
	s_nop 0
	v_mul_f32_e32 v116, 0xbfb8aa3b, v105
	v_mul_f32_e32 v114, 0xbfb8aa3b, v104
	v_exp_f32_e32 v116, v116
	v_exp_f32_e32 v114, v114
	s_nop 0
	v_add_f32_e32 v114, 1.0, v114
	s_nop 0
	v_add_f32_e32 v115, 1.0, v116
	v_mul_f32_e32 v116, 0xbfb8aa3b, v106
	v_mul_f32_e32 v117, 0xbfb8aa3b, v107
	v_exp_f32_e32 v116, v116
	v_exp_f32_e32 v117, v117
	v_rcp_f32_e32 v114, v114
	v_rcp_f32_e32 v115, v115
	v_add_f32_e32 v116, 1.0, v116
	v_add_f32_e32 v117, 1.0, v117
	v_rcp_f32_e32 v116, v116
	v_rcp_f32_e32 v117, v117
	v_pk_mul_f32 v[104:105], v[104:105], v[114:115]
	v_and_b32_e32 v249, 0x7fffffff, v101
	v_and_b32_e32 v248, 0x7fffffff, v100
	v_pk_fma_f32 v[114:115], v[248:249], s[28:29], 1.0 op_sel_hi:[1,0,0]
	v_pk_mul_f32 v[106:107], v[106:107], v[116:117]
	v_rcp_f32_e32 v114, v114
	v_rcp_f32_e32 v115, v115
	v_pk_mul_f32 v[106:107], v[110:111], v[106:107]
	v_pk_mul_f32 v[110:111], v[100:101], v[100:101]
	v_pk_mul_f32 v[104:105], v[108:109], v[104:105]
	v_pk_fma_f32 v[108:109], v[114:115], s[30:31], v[150:151] op_sel_hi:[1,0,0]
	v_pk_mul_f32 v[110:111], v[110:111], s[74:75] op_sel_hi:[1,0]
	v_pk_fma_f32 v[108:109], v[114:115], v[108:109], s[36:37] op_sel_hi:[1,1,0]
	v_exp_f32_e32 v110, v110
	v_exp_f32_e32 v111, v111
	v_pk_fma_f32 v[108:109], v[114:115], v[108:109], s[50:51] op_sel_hi:[1,1,0]
	v_and_b32_e32 v251, 0x7fffffff, v103
	v_and_b32_e32 v250, 0x7fffffff, v102
	v_pk_fma_f32 v[108:109], v[114:115], v[108:109], s[72:73] op_sel_hi:[1,1,0]
	v_pk_fma_f32 v[116:117], v[250:251], s[28:29], 1.0 op_sel_hi:[1,0,0]
	v_pk_mul_f32 v[108:109], v[114:115], v[108:109]
	v_rcp_f32_e32 v116, v116
	v_rcp_f32_e32 v117, v117
	v_pk_mul_f32 v[108:109], v[110:111], v[108:109]
	v_max_f32_e32 v240, 0, v100
	v_max_f32_e32 v241, 0, v101
	v_pk_fma_f32 v[100:101], v[248:249], v[108:109], v[240:241] neg_lo:[1,0,0] neg_hi:[1,0,0]
	v_pk_mul_f32 v[114:115], v[102:103], v[102:103]
	s_nop 1
	v_pk_fma_f32 v[108:109], v[116:117], s[30:31], v[150:151] op_sel_hi:[1,0,0]
	v_pk_mul_f32 v[110:111], v[114:115], s[74:75] op_sel_hi:[1,0]
	v_pk_fma_f32 v[108:109], v[116:117], v[108:109], s[36:37] op_sel_hi:[1,1,0]
	v_exp_f32_e32 v110, v110
	v_exp_f32_e32 v111, v111
	v_pk_fma_f32 v[108:109], v[116:117], v[108:109], s[50:51] op_sel_hi:[1,1,0]
	v_mul_f32_e32 v114, 0xbfb8aa3b, v96
	v_pk_fma_f32 v[108:109], v[116:117], v[108:109], s[72:73] op_sel_hi:[1,1,0]
	v_exp_f32_e32 v114, v114
	v_mul_f32_e32 v115, 0xbfb8aa3b, v97
	v_pk_mul_f32 v[108:109], v[116:117], v[108:109]
	v_exp_f32_e32 v115, v115
	v_pk_mul_f32 v[108:109], v[110:111], v[108:109]
	v_max_f32_e32 v240, 0, v102
	v_max_f32_e32 v241, 0, v103
	v_pk_fma_f32 v[102:103], v[250:251], v[108:109], v[240:241] neg_lo:[1,0,0] neg_hi:[1,0,0]
	s_nop 0
	v_add_f32_e32 v108, 1.0, v114
	v_mul_f32_e32 v110, 0xbfb8aa3b, v98
	v_rcp_f32_e32 v114, v108
	v_add_f32_e32 v108, 1.0, v115
	v_exp_f32_e32 v110, v110
	v_mul_f32_e32 v115, 0xbfb8aa3b, v99
	v_exp_f32_e32 v117, v115
	v_rcp_f32_e32 v115, v108
	v_add_f32_e32 v108, 1.0, v110
	v_rcp_f32_e32 v116, v108
	v_add_f32_e32 v108, 1.0, v117
	v_rcp_f32_e32 v117, v108
	v_pk_mul_f32 v[96:97], v[96:97], v[114:115]
	v_pk_mul_f32 v[98:99], v[98:99], v[116:117]
	s_nop 0
	v_pk_mul_f32 v[102:103], v[102:103], v[98:99]
	v_pk_mul_f32 v[98:99], v[100:101], v[96:97]
	v_cvt_pk_bf16_f32 v96, v104, v105
	v_cvt_pk_bf16_f32 v97, v106, v107
	v_and_b32_e32 v251, 0x7fffffff, v95
	v_cvt_pk_bf16_f32 v98, v98, v99
	v_cvt_pk_bf16_f32 v99, v102, v103
	global_store_dwordx4 v[112:113], v[96:99], off nt
	v_pk_mul_f32 v[102:103], v[92:93], v[92:93]
	v_and_b32_e32 v250, 0x7fffffff, v94
	v_and_b32_e32 v249, 0x7fffffff, v93
	v_and_b32_e32 v248, 0x7fffffff, v92
; __device__ __forceinline__ unsigned cvt_pk_bf16(float lo, float hi) { unsigned r; asm volatile("v_cvt_pk_bf16_f32 %0, %1, %2" : "=v"(r) : "v"(lo), "v"(hi)); return r; }
; __device__ __forceinline__ float sigmoid_f(float x) { return __builtin_amdgcn_rcpf(1.0f + __builtin_amdgcn_exp2f(-1.44269504f * x)); }
; __device__ __forceinline__ f32x2 gelu_pk(f32x2 v) {
;     const f32x2 av = __builtin_elementwise_abs(v), d = av * 0.2316418882f + 1.0f;
;     f32x2 t; t.x = __builtin_amdgcn_rcpf(d.x); t.y = __builtin_amdgcn_rcpf(d.y);
;     f32x2 q = t * 0.5307027145f + (-0.7265760135f); q = q * t + 0.7107068705f; q = q * t + (-0.142248368f); q = q * t + 0.127414796f; q = q * t;
;     const f32x2 s = (v * v) * (-0.72134752044f);
;     f32x2 e; e.x = __builtin_amdgcn_exp2f(s.x); e.y = __builtin_amdgcn_exp2f(s.y);
;     const f32x2 m = v * (q * e), r = v - m;
;     f32x2 o; o.x = v.x < 0.f ? m.x : r.x; o.y = v.y < 0.f ? m.y : r.y; return o;
; }
; __device__ __forceinline__ f32x4 gelu4(f32x4 v) { f32x2 a = gelu_pk((f32x2){v[0], v[1]}), b = gelu_pk((f32x2){v[2], v[3]}); return (f32x4){a.x, a.y, b.x, b.y}; }
; __device__ __forceinline__ f32x4 sigm4(f32x4 v) { return (f32x4){sigmoid_f(v[0]), sigmoid_f(v[1]), sigmoid_f(v[2]), sigmoid_f(v[3])}; }
; __device__ __forceinline__ f32x4 silu4(f32x4 v) { return v * sigm4(v); }
;     __device__ __forceinline__ void operator()(const f32x4 (&acc)[2][2][4][2], const pg8::Unit& u, int wr, int wc, int fr, int fq) const {
;     ...
;                 for (int m = 0; m < 4; ++m) {
;                     bf16_t* rowp = base + (size_t)(row0 + ai * 128 + m * 16) * 1024;
;                     const f32x4 v0 = gelu4(acc[ai][0][m][0]) * silu4(acc[ai][1][m][0]), v1 = gelu4(acc[ai][0][m][1]) * silu4(acc[ai][1][m][1]);
;                     u32x4 w; w.x = cvt_pk_bf16(v0[0], v0[1]); w.y = cvt_pk_bf16(v0[2], v0[3]); w.z = cvt_pk_bf16(v1[0], v1[1]); w.w = cvt_pk_bf16(v1[2], v1[3]);
;                     __builtin_nontemporal_store(w, (u32x4*)rowp);
	v_pk_fma_f32 v[98:99], v[248:249], s[28:29], 1.0 op_sel_hi:[1,0,0]
	v_pk_mul_f32 v[102:103], v[102:103], s[74:75] op_sel_hi:[1,0]
	v_rcp_f32_e32 v98, v98
	v_rcp_f32_e32 v99, v99
	v_exp_f32_e32 v102, v102
	v_exp_f32_e32 v103, v103
	v_pk_fma_f32 v[104:105], v[250:251], s[28:29], 1.0 op_sel_hi:[1,0,0]
	v_pk_fma_f32 v[100:101], v[98:99], s[30:31], v[150:151] op_sel_hi:[1,0,0]
	v_rcp_f32_e32 v104, v104
	v_pk_fma_f32 v[100:101], v[98:99], v[100:101], s[36:37] op_sel_hi:[1,1,0]
	v_rcp_f32_e32 v105, v105
	v_pk_fma_f32 v[100:101], v[98:99], v[100:101], s[50:51] op_sel_hi:[1,1,0]
	s_nop 0
	v_pk_fma_f32 v[100:101], v[98:99], v[100:101], s[72:73] op_sel_hi:[1,1,0]
	v_or_b32_e32 v96, 32, v146
	v_pk_mul_f32 v[98:99], v[98:99], v[100:101]
	v_pk_mul_f32 v[100:101], v[94:95], v[94:95]
	v_pk_mul_f32 v[98:99], v[102:103], v[98:99]
	v_pk_mul_f32 v[100:101], v[100:101], s[74:75] op_sel_hi:[1,0]
	v_max_f32_e32 v240, 0, v92
	v_max_f32_e32 v241, 0, v93
	v_pk_fma_f32 v[92:93], v[248:249], v[98:99], v[240:241] neg_lo:[1,0,0] neg_hi:[1,0,0]
	v_exp_f32_e32 v100, v100
	v_exp_f32_e32 v101, v101
	v_ashrrev_i32_e32 v97, 31, v96
	v_pk_fma_f32 v[98:99], v[104:105], s[30:31], v[150:151] op_sel_hi:[1,0,0]
	s_nop 0
	v_pk_fma_f32 v[98:99], v[104:105], v[98:99], s[36:37] op_sel_hi:[1,1,0]
	v_lshlrev_b64 v[96:97], 11, v[96:97]
	v_pk_fma_f32 v[98:99], v[104:105], v[98:99], s[50:51] op_sel_hi:[1,1,0]
	v_lshl_add_u64 v[96:97], v[152:153], 0, v[96:97]
	v_pk_fma_f32 v[98:99], v[104:105], v[98:99], s[72:73] op_sel_hi:[1,1,0]
	s_nop 0
	v_pk_mul_f32 v[98:99], v[104:105], v[98:99]
	s_nop 0
	v_pk_mul_f32 v[98:99], v[100:101], v[98:99]
	s_nop 0
	v_max_f32_e32 v240, 0, v94
	v_max_f32_e32 v241, 0, v95
	v_pk_fma_f32 v[94:95], v[250:251], v[98:99], v[240:241] neg_lo:[1,0,0] neg_hi:[1,0,0]
	s_nop 0
	v_mul_f32_e32 v100, 0xbfb8aa3b, v89
	v_mul_f32_e32 v98, 0xbfb8aa3b, v88
	v_exp_f32_e32 v100, v100
	v_exp_f32_e32 v98, v98
	s_nop 0
	v_add_f32_e32 v98, 1.0, v98
	s_nop 0
	v_add_f32_e32 v99, 1.0, v100
	v_mul_f32_e32 v100, 0xbfb8aa3b, v90
	v_mul_f32_e32 v101, 0xbfb8aa3b, v91
	v_exp_f32_e32 v100, v100
	v_exp_f32_e32 v101, v101
	v_rcp_f32_e32 v98, v98
	v_rcp_f32_e32 v99, v99
	v_add_f32_e32 v100, 1.0, v100
	v_add_f32_e32 v101, 1.0, v101
	v_rcp_f32_e32 v100, v100
	v_rcp_f32_e32 v101, v101
	v_pk_mul_f32 v[88:89], v[88:89], v[98:99]
	v_and_b32_e32 v249, 0x7fffffff, v85
	v_and_b32_e32 v248, 0x7fffffff, v84
	v_pk_fma_f32 v[98:99], v[248:249], s[28:29], 1.0 op_sel_hi:[1,0,0]
	v_pk_mul_f32 v[90:91], v[90:91], v[100:101]
	v_rcp_f32_e32 v98, v98
	v_rcp_f32_e32 v99, v99
	v_pk_mul_f32 v[90:91], v[94:95], v[90:91]
	v_pk_mul_f32 v[94:95], v[84:85], v[84:85]
	v_pk_mul_f32 v[88:89], v[92:93], v[88:89]
	v_pk_fma_f32 v[92:93], v[98:99], s[30:31], v[150:151] op_sel_hi:[1,0,0]
	v_pk_mul_f32 v[94:95], v[94:95], s[74:75] op_sel_hi:[1,0]
	v_pk_fma_f32 v[92:93], v[98:99], v[92:93], s[36:37] op_sel_hi:[1,1,0]
	v_exp_f32_e32 v94, v94
	v_exp_f32_e32 v95, v95
	v_pk_fma_f32 v[92:93], v[98:99], v[92:93], s[50:51] op_sel_hi:[1,1,0]
	v_and_b32_e32 v251, 0x7fffffff, v87
	v_and_b32_e32 v250, 0x7fffffff, v86
	v_pk_fma_f32 v[92:93], v[98:99], v[92:93], s[72:73] op_sel_hi:[1,1,0]
	v_pk_fma_f32 v[100:101], v[250:251], s[28:29], 1.0 op_sel_hi:[1,0,0]
	v_pk_mul_f32 v[92:93], v[98:99], v[92:93]
	v_rcp_f32_e32 v100, v100
	v_rcp_f32_e32 v101, v101
	v_pk_mul_f32 v[92:93], v[94:95], v[92:93]
	v_max_f32_e32 v240, 0, v84
	v_max_f32_e32 v241, 0, v85
	v_pk_fma_f32 v[84:85], v[248:249], v[92:93], v[240:241] neg_lo:[1,0,0] neg_hi:[1,0,0]
	v_pk_mul_f32 v[98:99], v[86:87], v[86:87]
	s_nop 1
	v_pk_fma_f32 v[92:93], v[100:101], s[30:31], v[150:151] op_sel_hi:[1,0,0]
	v_pk_mul_f32 v[94:95], v[98:99], s[74:75] op_sel_hi:[1,0]
	v_pk_fma_f32 v[92:93], v[100:101], v[92:93], s[36:37] op_sel_hi:[1,1,0]
	v_exp_f32_e32 v94, v94
	v_exp_f32_e32 v95, v95
	v_pk_fma_f32 v[92:93], v[100:101], v[92:93], s[50:51] op_sel_hi:[1,1,0]
	v_mul_f32_e32 v98, 0xbfb8aa3b, v80
	v_pk_fma_f32 v[92:93], v[100:101], v[92:93], s[72:73] op_sel_hi:[1,1,0]
	v_exp_f32_e32 v98, v98
	v_mul_f32_e32 v99, 0xbfb8aa3b, v81
	v_pk_mul_f32 v[92:93], v[100:101], v[92:93]
	v_exp_f32_e32 v99, v99
	v_pk_mul_f32 v[92:93], v[94:95], v[92:93]
	v_max_f32_e32 v240, 0, v86
	v_max_f32_e32 v241, 0, v87
	v_pk_fma_f32 v[86:87], v[250:251], v[92:93], v[240:241] neg_lo:[1,0,0] neg_hi:[1,0,0]
	s_nop 0
	v_add_f32_e32 v92, 1.0, v98
	v_mul_f32_e32 v94, 0xbfb8aa3b, v82
	v_rcp_f32_e32 v98, v92
	v_add_f32_e32 v92, 1.0, v99
	v_exp_f32_e32 v94, v94
	v_mul_f32_e32 v99, 0xbfb8aa3b, v83
	v_exp_f32_e32 v101, v99
	v_rcp_f32_e32 v99, v92
	v_add_f32_e32 v92, 1.0, v94
	v_rcp_f32_e32 v100, v92
	v_add_f32_e32 v92, 1.0, v101
	v_rcp_f32_e32 v101, v92
	v_pk_mul_f32 v[80:81], v[80:81], v[98:99]
	v_pk_mul_f32 v[82:83], v[82:83], v[100:101]
	s_nop 0
	v_pk_mul_f32 v[86:87], v[86:87], v[82:83]
	v_pk_mul_f32 v[82:83], v[84:85], v[80:81]
	v_cvt_pk_bf16_f32 v80, v88, v89
	v_cvt_pk_bf16_f32 v81, v90, v91
	v_and_b32_e32 v251, 0x7fffffff, v79
	v_cvt_pk_bf16_f32 v82, v82, v83
	v_cvt_pk_bf16_f32 v83, v86, v87
	global_store_dwordx4 v[96:97], v[80:83], off nt
	v_pk_mul_f32 v[86:87], v[76:77], v[76:77]
	v_and_b32_e32 v250, 0x7fffffff, v78
	v_and_b32_e32 v249, 0x7fffffff, v77
	v_and_b32_e32 v248, 0x7fffffff, v76
	v_pk_fma_f32 v[82:83], v[248:249], s[28:29], 1.0 op_sel_hi:[1,0,0]
	v_pk_mul_f32 v[86:87], v[86:87], s[74:75] op_sel_hi:[1,0]
	v_rcp_f32_e32 v82, v82
	v_rcp_f32_e32 v83, v83
	v_exp_f32_e32 v86, v86
	v_exp_f32_e32 v87, v87
	v_pk_fma_f32 v[88:89], v[250:251], s[28:29], 1.0 op_sel_hi:[1,0,0]
	v_pk_fma_f32 v[84:85], v[82:83], s[30:31], v[150:151] op_sel_hi:[1,0,0]
	v_rcp_f32_e32 v88, v88
	v_pk_fma_f32 v[84:85], v[82:83], v[84:85], s[36:37] op_sel_hi:[1,1,0]
; __device__ __forceinline__ unsigned cvt_pk_bf16(float lo, float hi) { unsigned r; asm volatile("v_cvt_pk_bf16_f32 %0, %1, %2" : "=v"(r) : "v"(lo), "v"(hi)); return r; }
; __device__ __forceinline__ float sigmoid_f(float x) { return __builtin_amdgcn_rcpf(1.0f + __builtin_amdgcn_exp2f(-1.44269504f * x)); }
; __device__ __forceinline__ f32x2 gelu_pk(f32x2 v) {
;     const f32x2 av = __builtin_elementwise_abs(v), d = av * 0.2316418882f + 1.0f;
;     f32x2 t; t.x = __builtin_amdgcn_rcpf(d.x); t.y = __builtin_amdgcn_rcpf(d.y);
;     f32x2 q = t * 0.5307027145f + (-0.7265760135f); q = q * t + 0.7107068705f; q = q * t + (-0.142248368f); q = q * t + 0.127414796f; q = q * t;
;     const f32x2 s = (v * v) * (-0.72134752044f);
;     f32x2 e; e.x = __builtin_amdgcn_exp2f(s.x); e.y = __builtin_amdgcn_exp2f(s.y);
;     const f32x2 m = v * (q * e), r = v - m;
;     f32x2 o; o.x = v.x < 0.f ? m.x : r.x; o.y = v.y < 0.f ? m.y : r.y; return o;
; }
; __device__ __forceinline__ f32x4 gelu4(f32x4 v) { f32x2 a = gelu_pk((f32x2){v[0], v[1]}), b = gelu_pk((f32x2){v[2], v[3]}); return (f32x4){a.x, a.y, b.x, b.y}; }
; __device__ __forceinline__ f32x4 sigm4(f32x4 v) { return (f32x4){sigmoid_f(v[0]), sigmoid_f(v[1]), sigmoid_f(v[2]), sigmoid_f(v[3])}; }
; __device__ __forceinline__ f32x4 silu4(f32x4 v) { return v * sigm4(v); }
;     __device__ __forceinline__ void operator()(const f32x4 (&acc)[2][2][4][2], const pg8::Unit& u, int wr, int wc, int fr, int fq) const {
;     ...
;                 for (int m = 0; m < 4; ++m) {
;                     bf16_t* rowp = base + (size_t)(row0 + ai * 128 + m * 16) * 1024;
;                     const f32x4 v0 = gelu4(acc[ai][0][m][0]) * silu4(acc[ai][1][m][0]), v1 = gelu4(acc[ai][0][m][1]) * silu4(acc[ai][1][m][1]);
;                     u32x4 w; w.x = cvt_pk_bf16(v0[0], v0[1]); w.y = cvt_pk_bf16(v0[2], v0[3]); w.z = cvt_pk_bf16(v1[0], v1[1]); w.w = cvt_pk_bf16(v1[2], v1[3]);
;                     __builtin_nontemporal_store(w, (u32x4*)rowp);
	v_rcp_f32_e32 v89, v89
	v_pk_fma_f32 v[84:85], v[82:83], v[84:85], s[50:51] op_sel_hi:[1,1,0]
	s_nop 0
	v_pk_fma_f32 v[84:85], v[82:83], v[84:85], s[72:73] op_sel_hi:[1,1,0]
	v_or_b32_e32 v80, 48, v146
	v_pk_mul_f32 v[82:83], v[82:83], v[84:85]
	v_pk_mul_f32 v[84:85], v[78:79], v[78:79]
	v_pk_mul_f32 v[82:83], v[86:87], v[82:83]
	v_pk_mul_f32 v[84:85], v[84:85], s[74:75] op_sel_hi:[1,0]
	v_max_f32_e32 v240, 0, v76
	v_max_f32_e32 v241, 0, v77
	v_pk_fma_f32 v[76:77], v[248:249], v[82:83], v[240:241] neg_lo:[1,0,0] neg_hi:[1,0,0]
	v_exp_f32_e32 v84, v84
	v_exp_f32_e32 v85, v85
	v_ashrrev_i32_e32 v81, 31, v80
	v_pk_fma_f32 v[82:83], v[88:89], s[30:31], v[150:151] op_sel_hi:[1,0,0]
	s_nop 0
	v_pk_fma_f32 v[82:83], v[88:89], v[82:83], s[36:37] op_sel_hi:[1,1,0]
	v_lshlrev_b64 v[80:81], 11, v[80:81]
	v_pk_fma_f32 v[82:83], v[88:89], v[82:83], s[50:51] op_sel_hi:[1,1,0]
	v_lshl_add_u64 v[80:81], v[152:153], 0, v[80:81]
	v_pk_fma_f32 v[82:83], v[88:89], v[82:83], s[72:73] op_sel_hi:[1,1,0]
	s_nop 0
	v_pk_mul_f32 v[82:83], v[88:89], v[82:83]
	s_nop 0
	v_pk_mul_f32 v[82:83], v[84:85], v[82:83]
	s_nop 0
	v_max_f32_e32 v240, 0, v78
	v_max_f32_e32 v241, 0, v79
	v_pk_fma_f32 v[78:79], v[250:251], v[82:83], v[240:241] neg_lo:[1,0,0] neg_hi:[1,0,0]
	s_nop 0
	v_mul_f32_e32 v84, 0xbfb8aa3b, v73
	v_mul_f32_e32 v82, 0xbfb8aa3b, v72
	v_exp_f32_e32 v84, v84
	v_exp_f32_e32 v82, v82
	s_nop 0
	v_add_f32_e32 v82, 1.0, v82
	s_nop 0
	v_add_f32_e32 v83, 1.0, v84
	v_mul_f32_e32 v84, 0xbfb8aa3b, v74
	v_mul_f32_e32 v85, 0xbfb8aa3b, v75
	v_exp_f32_e32 v84, v84
	v_exp_f32_e32 v85, v85
	v_rcp_f32_e32 v82, v82
	v_rcp_f32_e32 v83, v83
	v_add_f32_e32 v84, 1.0, v84
	v_add_f32_e32 v85, 1.0, v85
	v_rcp_f32_e32 v84, v84
	v_rcp_f32_e32 v85, v85
	v_pk_mul_f32 v[72:73], v[72:73], v[82:83]
	v_and_b32_e32 v249, 0x7fffffff, v69
	v_and_b32_e32 v248, 0x7fffffff, v68
	v_pk_fma_f32 v[82:83], v[248:249], s[28:29], 1.0 op_sel_hi:[1,0,0]
	v_pk_mul_f32 v[74:75], v[74:75], v[84:85]
	v_rcp_f32_e32 v82, v82
	v_rcp_f32_e32 v83, v83
	v_pk_mul_f32 v[74:75], v[78:79], v[74:75]
	v_pk_mul_f32 v[78:79], v[68:69], v[68:69]
	v_pk_mul_f32 v[72:73], v[76:77], v[72:73]
	v_pk_fma_f32 v[76:77], v[82:83], s[30:31], v[150:151] op_sel_hi:[1,0,0]
	v_pk_mul_f32 v[78:79], v[78:79], s[74:75] op_sel_hi:[1,0]
	v_pk_fma_f32 v[76:77], v[82:83], v[76:77], s[36:37] op_sel_hi:[1,1,0]
	v_exp_f32_e32 v78, v78
	v_exp_f32_e32 v79, v79
	v_pk_fma_f32 v[76:77], v[82:83], v[76:77], s[50:51] op_sel_hi:[1,1,0]
	v_and_b32_e32 v251, 0x7fffffff, v71
	v_and_b32_e32 v250, 0x7fffffff, v70
	v_pk_fma_f32 v[76:77], v[82:83], v[76:77], s[72:73] op_sel_hi:[1,1,0]
	v_pk_fma_f32 v[84:85], v[250:251], s[28:29], 1.0 op_sel_hi:[1,0,0]
	v_pk_mul_f32 v[76:77], v[82:83], v[76:77]
	v_rcp_f32_e32 v84, v84
	v_rcp_f32_e32 v85, v85
	v_pk_mul_f32 v[76:77], v[78:79], v[76:77]
	v_max_f32_e32 v240, 0, v68
	v_max_f32_e32 v241, 0, v69
	v_pk_fma_f32 v[68:69], v[248:249], v[76:77], v[240:241] neg_lo:[1,0,0] neg_hi:[1,0,0]
	v_pk_mul_f32 v[82:83], v[70:71], v[70:71]
	s_nop 1
	v_pk_fma_f32 v[76:77], v[84:85], s[30:31], v[150:151] op_sel_hi:[1,0,0]
	v_pk_mul_f32 v[78:79], v[82:83], s[74:75] op_sel_hi:[1,0]
	v_pk_fma_f32 v[76:77], v[84:85], v[76:77], s[36:37] op_sel_hi:[1,1,0]
	v_exp_f32_e32 v78, v78
	v_exp_f32_e32 v79, v79
	v_pk_fma_f32 v[76:77], v[84:85], v[76:77], s[50:51] op_sel_hi:[1,1,0]
	v_mul_f32_e32 v82, 0xbfb8aa3b, v64
	v_pk_fma_f32 v[76:77], v[84:85], v[76:77], s[72:73] op_sel_hi:[1,1,0]
	v_exp_f32_e32 v82, v82
	v_mul_f32_e32 v83, 0xbfb8aa3b, v65
	v_pk_mul_f32 v[76:77], v[84:85], v[76:77]
	v_exp_f32_e32 v83, v83
	v_pk_mul_f32 v[76:77], v[78:79], v[76:77]
	v_max_f32_e32 v240, 0, v70
	v_max_f32_e32 v241, 0, v71
	v_pk_fma_f32 v[70:71], v[250:251], v[76:77], v[240:241] neg_lo:[1,0,0] neg_hi:[1,0,0]
	s_nop 0
	v_add_f32_e32 v76, 1.0, v82
	v_mul_f32_e32 v78, 0xbfb8aa3b, v66
	v_rcp_f32_e32 v82, v76
	v_add_f32_e32 v76, 1.0, v83
	v_exp_f32_e32 v78, v78
	v_mul_f32_e32 v83, 0xbfb8aa3b, v67
	v_exp_f32_e32 v85, v83
	v_rcp_f32_e32 v83, v76
	v_add_f32_e32 v76, 1.0, v78
	v_rcp_f32_e32 v84, v76
	v_add_f32_e32 v76, 1.0, v85
	v_rcp_f32_e32 v85, v76
	v_pk_mul_f32 v[64:65], v[64:65], v[82:83]
	v_pk_mul_f32 v[66:67], v[66:67], v[84:85]
	s_nop 0
	v_pk_mul_f32 v[70:71], v[70:71], v[66:67]
	v_pk_mul_f32 v[66:67], v[68:69], v[64:65]
	v_and_b32_e32 v249, 0x7fffffff, v61
	v_and_b32_e32 v248, 0x7fffffff, v60
	v_pk_fma_f32 v[68:69], v[248:249], s[28:29], 1.0 op_sel_hi:[1,0,0]
	v_cvt_pk_bf16_f32 v64, v72, v73
	v_cvt_pk_bf16_f32 v65, v74, v75
	v_cvt_pk_bf16_f32 v66, v66, v67
	v_cvt_pk_bf16_f32 v67, v70, v71
	global_store_dwordx4 v[80:81], v[64:67], off nt
	v_rcp_f32_e32 v68, v68
	v_rcp_f32_e32 v69, v69
	v_pk_mul_f32 v[66:67], v[60:61], v[60:61]
	v_and_b32_e32 v251, 0x7fffffff, v63
	v_pk_mul_f32 v[66:67], v[66:67], s[74:75] op_sel_hi:[1,0]
	v_pk_fma_f32 v[64:65], v[68:69], s[30:31], v[150:151] op_sel_hi:[1,0,0]
	v_exp_f32_e32 v66, v66
	v_pk_fma_f32 v[64:65], v[68:69], v[64:65], s[36:37] op_sel_hi:[1,1,0]
	v_exp_f32_e32 v67, v67
	v_pk_fma_f32 v[64:65], v[68:69], v[64:65], s[50:51] op_sel_hi:[1,1,0]
	v_and_b32_e32 v250, 0x7fffffff, v62
	v_pk_fma_f32 v[64:65], v[68:69], v[64:65], s[72:73] op_sel_hi:[1,1,0]
	v_pk_fma_f32 v[70:71], v[250:251], s[28:29], 1.0 op_sel_hi:[1,0,0]
	v_pk_mul_f32 v[64:65], v[68:69], v[64:65]
	v_rcp_f32_e32 v70, v70
	v_rcp_f32_e32 v71, v71
	v_pk_mul_f32 v[64:65], v[66:67], v[64:65]
	v_max_f32_e32 v240, 0, v60
	v_max_f32_e32 v241, 0, v61
	v_pk_fma_f32 v[60:61], v[248:249], v[64:65], v[240:241] neg_lo:[1,0,0] neg_hi:[1,0,0]
	v_pk_mul_f32 v[68:69], v[62:63], v[62:63]
	s_nop 1
	v_pk_fma_f32 v[64:65], v[70:71], s[30:31], v[150:151] op_sel_hi:[1,0,0]
; __device__ __forceinline__ unsigned cvt_pk_bf16(float lo, float hi) { unsigned r; asm volatile("v_cvt_pk_bf16_f32 %0, %1, %2" : "=v"(r) : "v"(lo), "v"(hi)); return r; }
; __device__ __forceinline__ float sigmoid_f(float x) { return __builtin_amdgcn_rcpf(1.0f + __builtin_amdgcn_exp2f(-1.44269504f * x)); }
; __device__ __forceinline__ f32x2 gelu_pk(f32x2 v) {
;     const f32x2 av = __builtin_elementwise_abs(v), d = av * 0.2316418882f + 1.0f;
;     f32x2 t; t.x = __builtin_amdgcn_rcpf(d.x); t.y = __builtin_amdgcn_rcpf(d.y);
;     f32x2 q = t * 0.5307027145f + (-0.7265760135f); q = q * t + 0.7107068705f; q = q * t + (-0.142248368f); q = q * t + 0.127414796f; q = q * t;
;     const f32x2 s = (v * v) * (-0.72134752044f);
;     f32x2 e; e.x = __builtin_amdgcn_exp2f(s.x); e.y = __builtin_amdgcn_exp2f(s.y);
;     const f32x2 m = v * (q * e), r = v - m;
;     f32x2 o; o.x = v.x < 0.f ? m.x : r.x; o.y = v.y < 0.f ? m.y : r.y; return o;
; }
; __device__ __forceinline__ f32x4 gelu4(f32x4 v) { f32x2 a = gelu_pk((f32x2){v[0], v[1]}), b = gelu_pk((f32x2){v[2], v[3]}); return (f32x4){a.x, a.y, b.x, b.y}; }
; __device__ __forceinline__ f32x4 sigm4(f32x4 v) { return (f32x4){sigmoid_f(v[0]), sigmoid_f(v[1]), sigmoid_f(v[2]), sigmoid_f(v[3])}; }
; __device__ __forceinline__ f32x4 silu4(f32x4 v) { return v * sigm4(v); }
;     __device__ __forceinline__ void operator()(const f32x4 (&acc)[2][2][4][2], const pg8::Unit& u, int wr, int wc, int fr, int fq) const {
;     ...
;                 for (int m = 0; m < 4; ++m) {
;                     bf16_t* rowp = base + (size_t)(row0 + ai * 128 + m * 16) * 1024;
;                     const f32x4 v0 = gelu4(acc[ai][0][m][0]) * silu4(acc[ai][1][m][0]), v1 = gelu4(acc[ai][0][m][1]) * silu4(acc[ai][1][m][1]);
;                     u32x4 w; w.x = cvt_pk_bf16(v0[0], v0[1]); w.y = cvt_pk_bf16(v0[2], v0[3]); w.z = cvt_pk_bf16(v1[0], v1[1]); w.w = cvt_pk_bf16(v1[2], v1[3]);
;                     __builtin_nontemporal_store(w, (u32x4*)rowp);
	v_pk_mul_f32 v[66:67], v[68:69], s[74:75] op_sel_hi:[1,0]
	v_pk_fma_f32 v[64:65], v[70:71], v[64:65], s[36:37] op_sel_hi:[1,1,0]
	v_exp_f32_e32 v66, v66
	v_exp_f32_e32 v67, v67
	v_pk_fma_f32 v[64:65], v[70:71], v[64:65], s[50:51] op_sel_hi:[1,1,0]
	s_nop 0
	v_pk_fma_f32 v[64:65], v[70:71], v[64:65], s[72:73] op_sel_hi:[1,1,0]
	s_nop 0
	v_pk_mul_f32 v[64:65], v[70:71], v[64:65]
	s_nop 0
	v_pk_mul_f32 v[64:65], v[66:67], v[64:65]
	s_nop 0
	v_max_f32_e32 v240, 0, v62
	v_max_f32_e32 v241, 0, v63
	v_pk_fma_f32 v[62:63], v[250:251], v[64:65], v[240:241] neg_lo:[1,0,0] neg_hi:[1,0,0]
	s_nop 0
	v_mul_f32_e32 v66, 0xbfb8aa3b, v57
	v_mul_f32_e32 v64, 0xbfb8aa3b, v56
	v_exp_f32_e32 v66, v66
	v_exp_f32_e32 v64, v64
	s_nop 0
	v_add_f32_e32 v64, 1.0, v64
	s_nop 0
	v_add_f32_e32 v65, 1.0, v66
	v_mul_f32_e32 v66, 0xbfb8aa3b, v58
	v_mul_f32_e32 v67, 0xbfb8aa3b, v59
	v_exp_f32_e32 v66, v66
	v_exp_f32_e32 v67, v67
	v_rcp_f32_e32 v64, v64
	v_rcp_f32_e32 v65, v65
	v_add_f32_e32 v66, 1.0, v66
	v_add_f32_e32 v67, 1.0, v67
	v_rcp_f32_e32 v66, v66
	v_rcp_f32_e32 v67, v67
	v_pk_mul_f32 v[56:57], v[56:57], v[64:65]
	v_and_b32_e32 v249, 0x7fffffff, v53
	v_and_b32_e32 v248, 0x7fffffff, v52
	v_pk_fma_f32 v[64:65], v[248:249], s[28:29], 1.0 op_sel_hi:[1,0,0]
	v_pk_mul_f32 v[58:59], v[58:59], v[66:67]
	v_rcp_f32_e32 v64, v64
	v_rcp_f32_e32 v65, v65
	v_pk_mul_f32 v[58:59], v[62:63], v[58:59]
	v_pk_mul_f32 v[62:63], v[52:53], v[52:53]
	v_pk_mul_f32 v[56:57], v[60:61], v[56:57]
	v_pk_fma_f32 v[60:61], v[64:65], s[30:31], v[150:151] op_sel_hi:[1,0,0]
	v_pk_mul_f32 v[62:63], v[62:63], s[74:75] op_sel_hi:[1,0]
	v_pk_fma_f32 v[60:61], v[64:65], v[60:61], s[36:37] op_sel_hi:[1,1,0]
	v_exp_f32_e32 v62, v62
	v_exp_f32_e32 v63, v63
	v_pk_fma_f32 v[60:61], v[64:65], v[60:61], s[50:51] op_sel_hi:[1,1,0]
	v_and_b32_e32 v251, 0x7fffffff, v55
	v_and_b32_e32 v250, 0x7fffffff, v54
	v_pk_fma_f32 v[60:61], v[64:65], v[60:61], s[72:73] op_sel_hi:[1,1,0]
	v_pk_fma_f32 v[66:67], v[250:251], s[28:29], 1.0 op_sel_hi:[1,0,0]
	v_pk_mul_f32 v[60:61], v[64:65], v[60:61]
	v_rcp_f32_e32 v66, v66
	v_rcp_f32_e32 v67, v67
	v_pk_mul_f32 v[60:61], v[62:63], v[60:61]
	v_max_f32_e32 v240, 0, v52
	v_max_f32_e32 v241, 0, v53
	v_pk_fma_f32 v[52:53], v[248:249], v[60:61], v[240:241] neg_lo:[1,0,0] neg_hi:[1,0,0]
	v_pk_mul_f32 v[64:65], v[54:55], v[54:55]
	s_nop 1
	v_pk_fma_f32 v[60:61], v[66:67], s[30:31], v[150:151] op_sel_hi:[1,0,0]
	v_pk_mul_f32 v[62:63], v[64:65], s[74:75] op_sel_hi:[1,0]
	v_pk_fma_f32 v[60:61], v[66:67], v[60:61], s[36:37] op_sel_hi:[1,1,0]
	v_exp_f32_e32 v62, v62
	v_exp_f32_e32 v63, v63
	v_pk_fma_f32 v[60:61], v[66:67], v[60:61], s[50:51] op_sel_hi:[1,1,0]
	v_mul_f32_e32 v64, 0xbfb8aa3b, v48
	v_pk_fma_f32 v[60:61], v[66:67], v[60:61], s[72:73] op_sel_hi:[1,1,0]
	v_exp_f32_e32 v64, v64
	v_mul_f32_e32 v65, 0xbfb8aa3b, v49
	v_pk_mul_f32 v[60:61], v[66:67], v[60:61]
	v_exp_f32_e32 v65, v65
	v_pk_mul_f32 v[60:61], v[62:63], v[60:61]
	v_max_f32_e32 v240, 0, v54
	v_max_f32_e32 v241, 0, v55
	v_pk_fma_f32 v[54:55], v[250:251], v[60:61], v[240:241] neg_lo:[1,0,0] neg_hi:[1,0,0]
	s_nop 0
	v_add_f32_e32 v60, 1.0, v64
	v_mul_f32_e32 v62, 0xbfb8aa3b, v50
	v_rcp_f32_e32 v64, v60
	v_add_f32_e32 v60, 1.0, v65
	v_exp_f32_e32 v62, v62
	v_mul_f32_e32 v65, 0xbfb8aa3b, v51
	v_exp_f32_e32 v67, v65
	v_rcp_f32_e32 v65, v60
	v_add_f32_e32 v60, 1.0, v62
	v_rcp_f32_e32 v66, v60
	v_add_f32_e32 v60, 1.0, v67
	v_rcp_f32_e32 v67, v60
	v_pk_mul_f32 v[48:49], v[48:49], v[64:65]
	v_pk_mul_f32 v[50:51], v[50:51], v[66:67]
	s_nop 0
	v_pk_mul_f32 v[54:55], v[54:55], v[50:51]
	v_pk_mul_f32 v[50:51], v[52:53], v[48:49]
	v_and_b32_e32 v249, 0x7fffffff, v45
	v_and_b32_e32 v248, 0x7fffffff, v44
	v_pk_fma_f32 v[52:53], v[248:249], s[28:29], 1.0 op_sel_hi:[1,0,0]
	v_cvt_pk_bf16_f32 v48, v56, v57
	v_cvt_pk_bf16_f32 v49, v58, v59
	v_cvt_pk_bf16_f32 v50, v50, v51
	v_cvt_pk_bf16_f32 v51, v54, v55
	v_add_co_u32_e32 v54, vcc, s6, v148
	v_rcp_f32_e32 v52, v52
	v_rcp_f32_e32 v53, v53
	v_addc_co_u32_e32 v55, vcc, 0, v149, vcc
	global_store_dwordx4 v[54:55], v[48:51], off nt
	v_and_b32_e32 v251, 0x7fffffff, v47
	v_and_b32_e32 v250, 0x7fffffff, v46
	v_pk_mul_f32 v[50:51], v[44:45], v[44:45]
	v_pk_fma_f32 v[48:49], v[52:53], s[30:31], v[150:151] op_sel_hi:[1,0,0]
	v_pk_mul_f32 v[50:51], v[50:51], s[74:75] op_sel_hi:[1,0]
	v_pk_fma_f32 v[48:49], v[52:53], v[48:49], s[36:37] op_sel_hi:[1,1,0]
	v_exp_f32_e32 v50, v50
	v_exp_f32_e32 v51, v51
	v_pk_fma_f32 v[48:49], v[52:53], v[48:49], s[50:51] op_sel_hi:[1,1,0]
	v_pk_fma_f32 v[54:55], v[250:251], s[28:29], 1.0 op_sel_hi:[1,0,0]
	v_pk_fma_f32 v[48:49], v[52:53], v[48:49], s[72:73] op_sel_hi:[1,1,0]
	v_rcp_f32_e32 v54, v54
	v_pk_mul_f32 v[48:49], v[52:53], v[48:49]
	v_rcp_f32_e32 v55, v55
	v_pk_mul_f32 v[48:49], v[50:51], v[48:49]
	v_max_f32_e32 v240, 0, v44
	v_max_f32_e32 v241, 0, v45
	v_pk_fma_f32 v[44:45], v[248:249], v[48:49], v[240:241] neg_lo:[1,0,0] neg_hi:[1,0,0]
	v_pk_mul_f32 v[52:53], v[46:47], v[46:47]
	s_mov_b32 s6, 0x48000
	s_nop 0
	v_pk_fma_f32 v[48:49], v[54:55], s[30:31], v[150:151] op_sel_hi:[1,0,0]
	v_pk_mul_f32 v[50:51], v[52:53], s[74:75] op_sel_hi:[1,0]
	v_pk_fma_f32 v[48:49], v[54:55], v[48:49], s[36:37] op_sel_hi:[1,1,0]
	v_exp_f32_e32 v50, v50
	v_exp_f32_e32 v51, v51
	v_pk_fma_f32 v[48:49], v[54:55], v[48:49], s[50:51] op_sel_hi:[1,1,0]
	s_nop 0
	v_pk_fma_f32 v[48:49], v[54:55], v[48:49], s[72:73] op_sel_hi:[1,1,0]
	s_nop 0
	v_pk_mul_f32 v[48:49], v[54:55], v[48:49]
	s_nop 0
	v_pk_mul_f32 v[48:49], v[50:51], v[48:49]
	s_nop 0
	v_max_f32_e32 v240, 0, v46
	v_max_f32_e32 v241, 0, v47
	v_pk_fma_f32 v[46:47], v[250:251], v[48:49], v[240:241] neg_lo:[1,0,0] neg_hi:[1,0,0]
	s_nop 0
; __device__ __forceinline__ unsigned cvt_pk_bf16(float lo, float hi) { unsigned r; asm volatile("v_cvt_pk_bf16_f32 %0, %1, %2" : "=v"(r) : "v"(lo), "v"(hi)); return r; }
; __device__ __forceinline__ float sigmoid_f(float x) { return __builtin_amdgcn_rcpf(1.0f + __builtin_amdgcn_exp2f(-1.44269504f * x)); }
; __device__ __forceinline__ f32x2 gelu_pk(f32x2 v) {
;     const f32x2 av = __builtin_elementwise_abs(v), d = av * 0.2316418882f + 1.0f;
;     f32x2 t; t.x = __builtin_amdgcn_rcpf(d.x); t.y = __builtin_amdgcn_rcpf(d.y);
;     f32x2 q = t * 0.5307027145f + (-0.7265760135f); q = q * t + 0.7107068705f; q = q * t + (-0.142248368f); q = q * t + 0.127414796f; q = q * t;
;     const f32x2 s = (v * v) * (-0.72134752044f);
;     f32x2 e; e.x = __builtin_amdgcn_exp2f(s.x); e.y = __builtin_amdgcn_exp2f(s.y);
;     const f32x2 m = v * (q * e), r = v - m;
;     f32x2 o; o.x = v.x < 0.f ? m.x : r.x; o.y = v.y < 0.f ? m.y : r.y; return o;
; }
; __device__ __forceinline__ f32x4 gelu4(f32x4 v) { f32x2 a = gelu_pk((f32x2){v[0], v[1]}), b = gelu_pk((f32x2){v[2], v[3]}); return (f32x4){a.x, a.y, b.x, b.y}; }
; __device__ __forceinline__ f32x4 sigm4(f32x4 v) { return (f32x4){sigmoid_f(v[0]), sigmoid_f(v[1]), sigmoid_f(v[2]), sigmoid_f(v[3])}; }
; __device__ __forceinline__ f32x4 silu4(f32x4 v) { return v * sigm4(v); }
;     __device__ __forceinline__ void operator()(const f32x4 (&acc)[2][2][4][2], const pg8::Unit& u, int wr, int wc, int fr, int fq) const {
;     ...
;                 for (int m = 0; m < 4; ++m) {
;                     bf16_t* rowp = base + (size_t)(row0 + ai * 128 + m * 16) * 1024;
;                     const f32x4 v0 = gelu4(acc[ai][0][m][0]) * silu4(acc[ai][1][m][0]), v1 = gelu4(acc[ai][0][m][1]) * silu4(acc[ai][1][m][1]);
;                     u32x4 w; w.x = cvt_pk_bf16(v0[0], v0[1]); w.y = cvt_pk_bf16(v0[2], v0[3]); w.z = cvt_pk_bf16(v1[0], v1[1]); w.w = cvt_pk_bf16(v1[2], v1[3]);
;                     __builtin_nontemporal_store(w, (u32x4*)rowp);
	v_mul_f32_e32 v50, 0xbfb8aa3b, v41
	v_mul_f32_e32 v48, 0xbfb8aa3b, v40
	v_exp_f32_e32 v50, v50
	v_exp_f32_e32 v48, v48
	s_nop 0
	v_add_f32_e32 v48, 1.0, v48
	s_nop 0
	v_add_f32_e32 v49, 1.0, v50
	v_mul_f32_e32 v50, 0xbfb8aa3b, v42
	v_mul_f32_e32 v51, 0xbfb8aa3b, v43
	v_exp_f32_e32 v50, v50
	v_exp_f32_e32 v51, v51
	v_rcp_f32_e32 v48, v48
	v_rcp_f32_e32 v49, v49
	v_add_f32_e32 v50, 1.0, v50
	v_add_f32_e32 v51, 1.0, v51
	v_rcp_f32_e32 v50, v50
	v_rcp_f32_e32 v51, v51
	v_pk_mul_f32 v[40:41], v[40:41], v[48:49]
	v_and_b32_e32 v249, 0x7fffffff, v37
	v_and_b32_e32 v248, 0x7fffffff, v36
	v_pk_fma_f32 v[48:49], v[248:249], s[28:29], 1.0 op_sel_hi:[1,0,0]
	v_pk_mul_f32 v[42:43], v[42:43], v[50:51]
	v_rcp_f32_e32 v48, v48
	v_rcp_f32_e32 v49, v49
	v_pk_mul_f32 v[42:43], v[46:47], v[42:43]
	v_pk_mul_f32 v[46:47], v[36:37], v[36:37]
	v_pk_mul_f32 v[40:41], v[44:45], v[40:41]
	v_pk_fma_f32 v[44:45], v[48:49], s[30:31], v[150:151] op_sel_hi:[1,0,0]
	v_pk_mul_f32 v[46:47], v[46:47], s[74:75] op_sel_hi:[1,0]
	v_pk_fma_f32 v[44:45], v[48:49], v[44:45], s[36:37] op_sel_hi:[1,1,0]
	v_exp_f32_e32 v46, v46
	v_exp_f32_e32 v47, v47
	v_pk_fma_f32 v[44:45], v[48:49], v[44:45], s[50:51] op_sel_hi:[1,1,0]
	v_and_b32_e32 v251, 0x7fffffff, v39
	v_and_b32_e32 v250, 0x7fffffff, v38
	v_pk_fma_f32 v[44:45], v[48:49], v[44:45], s[72:73] op_sel_hi:[1,1,0]
	v_pk_fma_f32 v[50:51], v[250:251], s[28:29], 1.0 op_sel_hi:[1,0,0]
	v_pk_mul_f32 v[44:45], v[48:49], v[44:45]
	v_rcp_f32_e32 v50, v50
	v_rcp_f32_e32 v51, v51
	v_pk_mul_f32 v[44:45], v[46:47], v[44:45]
	v_max_f32_e32 v240, 0, v36
	v_max_f32_e32 v241, 0, v37
	v_pk_fma_f32 v[36:37], v[248:249], v[44:45], v[240:241] neg_lo:[1,0,0] neg_hi:[1,0,0]
	v_pk_mul_f32 v[48:49], v[38:39], v[38:39]
	s_nop 1
	v_pk_fma_f32 v[44:45], v[50:51], s[30:31], v[150:151] op_sel_hi:[1,0,0]
	v_pk_mul_f32 v[46:47], v[48:49], s[74:75] op_sel_hi:[1,0]
	v_pk_fma_f32 v[44:45], v[50:51], v[44:45], s[36:37] op_sel_hi:[1,1,0]
	v_exp_f32_e32 v46, v46
	v_exp_f32_e32 v47, v47
	v_pk_fma_f32 v[44:45], v[50:51], v[44:45], s[50:51] op_sel_hi:[1,1,0]
	v_mul_f32_e32 v48, 0xbfb8aa3b, v32
	v_pk_fma_f32 v[44:45], v[50:51], v[44:45], s[72:73] op_sel_hi:[1,1,0]
	v_exp_f32_e32 v48, v48
	v_mul_f32_e32 v49, 0xbfb8aa3b, v33
	v_pk_mul_f32 v[44:45], v[50:51], v[44:45]
	v_exp_f32_e32 v49, v49
	v_pk_mul_f32 v[44:45], v[46:47], v[44:45]
	v_max_f32_e32 v240, 0, v38
	v_max_f32_e32 v241, 0, v39
	v_pk_fma_f32 v[38:39], v[250:251], v[44:45], v[240:241] neg_lo:[1,0,0] neg_hi:[1,0,0]
	s_nop 0
	v_add_f32_e32 v44, 1.0, v48
	v_mul_f32_e32 v46, 0xbfb8aa3b, v34
	v_rcp_f32_e32 v48, v44
	v_add_f32_e32 v44, 1.0, v49
	v_exp_f32_e32 v46, v46
	v_mul_f32_e32 v49, 0xbfb8aa3b, v35
	v_exp_f32_e32 v51, v49
	v_rcp_f32_e32 v49, v44
	v_add_f32_e32 v44, 1.0, v46
	v_rcp_f32_e32 v50, v44
	v_add_f32_e32 v44, 1.0, v51
	v_rcp_f32_e32 v51, v44
	v_pk_mul_f32 v[32:33], v[32:33], v[48:49]
	v_pk_mul_f32 v[34:35], v[34:35], v[50:51]
	s_nop 0
	v_pk_mul_f32 v[38:39], v[38:39], v[34:35]
	v_pk_mul_f32 v[34:35], v[36:37], v[32:33]
	v_and_b32_e32 v249, 0x7fffffff, v29
	v_and_b32_e32 v248, 0x7fffffff, v28
	v_pk_fma_f32 v[36:37], v[248:249], s[28:29], 1.0 op_sel_hi:[1,0,0]
	v_cvt_pk_bf16_f32 v32, v40, v41
	v_cvt_pk_bf16_f32 v33, v42, v43
	v_cvt_pk_bf16_f32 v34, v34, v35
	v_cvt_pk_bf16_f32 v35, v38, v39
	v_add_co_u32_e32 v38, vcc, s6, v148
	v_rcp_f32_e32 v36, v36
	v_rcp_f32_e32 v37, v37
	v_addc_co_u32_e32 v39, vcc, 0, v149, vcc
	global_store_dwordx4 v[38:39], v[32:35], off nt
	v_and_b32_e32 v251, 0x7fffffff, v31
	v_and_b32_e32 v250, 0x7fffffff, v30
	v_pk_mul_f32 v[34:35], v[28:29], v[28:29]
	v_pk_fma_f32 v[32:33], v[36:37], s[30:31], v[150:151] op_sel_hi:[1,0,0]
	v_pk_mul_f32 v[34:35], v[34:35], s[74:75] op_sel_hi:[1,0]
	v_pk_fma_f32 v[32:33], v[36:37], v[32:33], s[36:37] op_sel_hi:[1,1,0]
	v_exp_f32_e32 v34, v34
	v_exp_f32_e32 v35, v35
	v_pk_fma_f32 v[32:33], v[36:37], v[32:33], s[50:51] op_sel_hi:[1,1,0]
	v_pk_fma_f32 v[38:39], v[250:251], s[28:29], 1.0 op_sel_hi:[1,0,0]
	v_pk_fma_f32 v[32:33], v[36:37], v[32:33], s[72:73] op_sel_hi:[1,1,0]
	v_rcp_f32_e32 v38, v38
	v_pk_mul_f32 v[32:33], v[36:37], v[32:33]
	v_rcp_f32_e32 v39, v39
	v_pk_mul_f32 v[32:33], v[34:35], v[32:33]
	v_max_f32_e32 v240, 0, v28
	v_max_f32_e32 v241, 0, v29
	v_pk_fma_f32 v[28:29], v[248:249], v[32:33], v[240:241] neg_lo:[1,0,0] neg_hi:[1,0,0]
	v_pk_mul_f32 v[36:37], v[30:31], v[30:31]
	s_mov_b32 s6, 0x50000
	s_nop 0
	v_pk_fma_f32 v[32:33], v[38:39], s[30:31], v[150:151] op_sel_hi:[1,0,0]
	v_pk_mul_f32 v[34:35], v[36:37], s[74:75] op_sel_hi:[1,0]
	v_pk_fma_f32 v[32:33], v[38:39], v[32:33], s[36:37] op_sel_hi:[1,1,0]
	v_exp_f32_e32 v34, v34
	v_exp_f32_e32 v35, v35
	v_pk_fma_f32 v[32:33], v[38:39], v[32:33], s[50:51] op_sel_hi:[1,1,0]
	s_nop 0
	v_pk_fma_f32 v[32:33], v[38:39], v[32:33], s[72:73] op_sel_hi:[1,1,0]
	s_nop 0
	v_pk_mul_f32 v[32:33], v[38:39], v[32:33]
	s_nop 0
	v_pk_mul_f32 v[32:33], v[34:35], v[32:33]
	s_nop 0
	v_max_f32_e32 v240, 0, v30
	v_max_f32_e32 v241, 0, v31
	v_pk_fma_f32 v[30:31], v[250:251], v[32:33], v[240:241] neg_lo:[1,0,0] neg_hi:[1,0,0]
	s_nop 0
	v_mul_f32_e32 v34, 0xbfb8aa3b, v25
	v_mul_f32_e32 v32, 0xbfb8aa3b, v24
	v_exp_f32_e32 v34, v34
	v_exp_f32_e32 v32, v32
	s_nop 0
	v_add_f32_e32 v32, 1.0, v32
	s_nop 0
	v_add_f32_e32 v33, 1.0, v34
	v_mul_f32_e32 v34, 0xbfb8aa3b, v26
	v_mul_f32_e32 v35, 0xbfb8aa3b, v27
	v_exp_f32_e32 v34, v34
	v_exp_f32_e32 v35, v35
	v_rcp_f32_e32 v32, v32
	v_rcp_f32_e32 v33, v33
	v_add_f32_e32 v34, 1.0, v34
	v_add_f32_e32 v35, 1.0, v35
	v_rcp_f32_e32 v34, v34
	v_rcp_f32_e32 v35, v35
	v_pk_mul_f32 v[24:25], v[24:25], v[32:33]
	v_and_b32_e32 v249, 0x7fffffff, v21
	v_and_b32_e32 v248, 0x7fffffff, v20
; __device__ __forceinline__ unsigned cvt_pk_bf16(float lo, float hi) { unsigned r; asm volatile("v_cvt_pk_bf16_f32 %0, %1, %2" : "=v"(r) : "v"(lo), "v"(hi)); return r; }
; __device__ __forceinline__ float sigmoid_f(float x) { return __builtin_amdgcn_rcpf(1.0f + __builtin_amdgcn_exp2f(-1.44269504f * x)); }
; __device__ __forceinline__ f32x2 gelu_pk(f32x2 v) {
;     const f32x2 av = __builtin_elementwise_abs(v), d = av * 0.2316418882f + 1.0f;
;     f32x2 t; t.x = __builtin_amdgcn_rcpf(d.x); t.y = __builtin_amdgcn_rcpf(d.y);
;     f32x2 q = t * 0.5307027145f + (-0.7265760135f); q = q * t + 0.7107068705f; q = q * t + (-0.142248368f); q = q * t + 0.127414796f; q = q * t;
;     const f32x2 s = (v * v) * (-0.72134752044f);
;     f32x2 e; e.x = __builtin_amdgcn_exp2f(s.x); e.y = __builtin_amdgcn_exp2f(s.y);
;     const f32x2 m = v * (q * e), r = v - m;
;     f32x2 o; o.x = v.x < 0.f ? m.x : r.x; o.y = v.y < 0.f ? m.y : r.y; return o;
; }
; __device__ __forceinline__ f32x4 gelu4(f32x4 v) { f32x2 a = gelu_pk((f32x2){v[0], v[1]}), b = gelu_pk((f32x2){v[2], v[3]}); return (f32x4){a.x, a.y, b.x, b.y}; }
; __device__ __forceinline__ f32x4 sigm4(f32x4 v) { return (f32x4){sigmoid_f(v[0]), sigmoid_f(v[1]), sigmoid_f(v[2]), sigmoid_f(v[3])}; }
; __device__ __forceinline__ f32x4 silu4(f32x4 v) { return v * sigm4(v); }
;     __device__ __forceinline__ void operator()(const f32x4 (&acc)[2][2][4][2], const pg8::Unit& u, int wr, int wc, int fr, int fq) const {
;     ...
;                 for (int m = 0; m < 4; ++m) {
;                     bf16_t* rowp = base + (size_t)(row0 + ai * 128 + m * 16) * 1024;
;                     const f32x4 v0 = gelu4(acc[ai][0][m][0]) * silu4(acc[ai][1][m][0]), v1 = gelu4(acc[ai][0][m][1]) * silu4(acc[ai][1][m][1]);
;                     u32x4 w; w.x = cvt_pk_bf16(v0[0], v0[1]); w.y = cvt_pk_bf16(v0[2], v0[3]); w.z = cvt_pk_bf16(v1[0], v1[1]); w.w = cvt_pk_bf16(v1[2], v1[3]);
;                     __builtin_nontemporal_store(w, (u32x4*)rowp);
	v_pk_fma_f32 v[32:33], v[248:249], s[28:29], 1.0 op_sel_hi:[1,0,0]
	v_pk_mul_f32 v[26:27], v[26:27], v[34:35]
	v_rcp_f32_e32 v32, v32
	v_rcp_f32_e32 v33, v33
	v_pk_mul_f32 v[26:27], v[30:31], v[26:27]
	v_pk_mul_f32 v[30:31], v[20:21], v[20:21]
	v_pk_mul_f32 v[24:25], v[28:29], v[24:25]
	v_pk_fma_f32 v[28:29], v[32:33], s[30:31], v[150:151] op_sel_hi:[1,0,0]
	v_pk_mul_f32 v[30:31], v[30:31], s[74:75] op_sel_hi:[1,0]
	v_pk_fma_f32 v[28:29], v[32:33], v[28:29], s[36:37] op_sel_hi:[1,1,0]
	v_exp_f32_e32 v30, v30
	v_exp_f32_e32 v31, v31
	v_pk_fma_f32 v[28:29], v[32:33], v[28:29], s[50:51] op_sel_hi:[1,1,0]
	v_and_b32_e32 v251, 0x7fffffff, v23
	v_and_b32_e32 v250, 0x7fffffff, v22
	v_pk_fma_f32 v[28:29], v[32:33], v[28:29], s[72:73] op_sel_hi:[1,1,0]
	v_pk_fma_f32 v[34:35], v[250:251], s[28:29], 1.0 op_sel_hi:[1,0,0]
	v_pk_mul_f32 v[28:29], v[32:33], v[28:29]
	v_rcp_f32_e32 v34, v34
	v_rcp_f32_e32 v35, v35
	v_pk_mul_f32 v[28:29], v[30:31], v[28:29]
	v_max_f32_e32 v240, 0, v20
	v_max_f32_e32 v241, 0, v21
	v_pk_fma_f32 v[20:21], v[248:249], v[28:29], v[240:241] neg_lo:[1,0,0] neg_hi:[1,0,0]
	v_pk_mul_f32 v[32:33], v[22:23], v[22:23]
	s_nop 1
	v_pk_fma_f32 v[28:29], v[34:35], s[30:31], v[150:151] op_sel_hi:[1,0,0]
	v_pk_mul_f32 v[30:31], v[32:33], s[74:75] op_sel_hi:[1,0]
	v_pk_fma_f32 v[28:29], v[34:35], v[28:29], s[36:37] op_sel_hi:[1,1,0]
	v_exp_f32_e32 v30, v30
	v_exp_f32_e32 v31, v31
	v_pk_fma_f32 v[28:29], v[34:35], v[28:29], s[50:51] op_sel_hi:[1,1,0]
	v_mul_f32_e32 v32, 0xbfb8aa3b, v16
	v_pk_fma_f32 v[28:29], v[34:35], v[28:29], s[72:73] op_sel_hi:[1,1,0]
	v_exp_f32_e32 v32, v32
	v_mul_f32_e32 v33, 0xbfb8aa3b, v17
	v_pk_mul_f32 v[28:29], v[34:35], v[28:29]
	v_exp_f32_e32 v33, v33
	v_pk_mul_f32 v[28:29], v[30:31], v[28:29]
	v_max_f32_e32 v240, 0, v22
	v_max_f32_e32 v241, 0, v23
	v_pk_fma_f32 v[22:23], v[250:251], v[28:29], v[240:241] neg_lo:[1,0,0] neg_hi:[1,0,0]
	s_nop 0
	v_add_f32_e32 v28, 1.0, v32
	v_mul_f32_e32 v30, 0xbfb8aa3b, v18
	v_rcp_f32_e32 v32, v28
	v_add_f32_e32 v28, 1.0, v33
	v_exp_f32_e32 v30, v30
	v_mul_f32_e32 v33, 0xbfb8aa3b, v19
	v_exp_f32_e32 v35, v33
	v_rcp_f32_e32 v33, v28
	v_add_f32_e32 v28, 1.0, v30
	v_rcp_f32_e32 v34, v28
	v_add_f32_e32 v28, 1.0, v35
	v_rcp_f32_e32 v35, v28
	v_pk_mul_f32 v[16:17], v[16:17], v[32:33]
	v_pk_mul_f32 v[18:19], v[18:19], v[34:35]
	s_nop 0
	v_pk_mul_f32 v[22:23], v[22:23], v[18:19]
	v_pk_mul_f32 v[18:19], v[20:21], v[16:17]
	v_and_b32_e32 v249, 0x7fffffff, v13
	v_and_b32_e32 v248, 0x7fffffff, v12
	v_pk_fma_f32 v[20:21], v[248:249], s[28:29], 1.0 op_sel_hi:[1,0,0]
	v_cvt_pk_bf16_f32 v16, v24, v25
	v_cvt_pk_bf16_f32 v17, v26, v27
	v_cvt_pk_bf16_f32 v18, v18, v19
	v_cvt_pk_bf16_f32 v19, v22, v23
	v_add_co_u32_e32 v22, vcc, s6, v148
	v_rcp_f32_e32 v20, v20
	v_rcp_f32_e32 v21, v21
	v_addc_co_u32_e32 v23, vcc, 0, v149, vcc
	global_store_dwordx4 v[22:23], v[16:19], off nt
	v_and_b32_e32 v251, 0x7fffffff, v15
	v_and_b32_e32 v250, 0x7fffffff, v14
	v_pk_mul_f32 v[18:19], v[12:13], v[12:13]
	v_pk_fma_f32 v[16:17], v[20:21], s[30:31], v[150:151] op_sel_hi:[1,0,0]
	v_pk_mul_f32 v[18:19], v[18:19], s[74:75] op_sel_hi:[1,0]
	v_pk_fma_f32 v[16:17], v[20:21], v[16:17], s[36:37] op_sel_hi:[1,1,0]
	v_exp_f32_e32 v18, v18
	v_exp_f32_e32 v19, v19
	v_pk_fma_f32 v[16:17], v[20:21], v[16:17], s[50:51] op_sel_hi:[1,1,0]
	v_pk_fma_f32 v[22:23], v[250:251], s[28:29], 1.0 op_sel_hi:[1,0,0]
	v_pk_fma_f32 v[16:17], v[20:21], v[16:17], s[72:73] op_sel_hi:[1,1,0]
	v_rcp_f32_e32 v22, v22
	v_pk_mul_f32 v[16:17], v[20:21], v[16:17]
	v_rcp_f32_e32 v23, v23
	v_pk_mul_f32 v[16:17], v[18:19], v[16:17]
	v_max_f32_e32 v240, 0, v12
	v_max_f32_e32 v241, 0, v13
	v_pk_fma_f32 v[12:13], v[248:249], v[16:17], v[240:241] neg_lo:[1,0,0] neg_hi:[1,0,0]
	v_pk_mul_f32 v[20:21], v[14:15], v[14:15]
	s_nop 1
	v_pk_fma_f32 v[16:17], v[22:23], s[30:31], v[150:151] op_sel_hi:[1,0,0]
; __device__ __forceinline__ unsigned cvt_pk_bf16(float lo, float hi) { unsigned r; asm volatile("v_cvt_pk_bf16_f32 %0, %1, %2" : "=v"(r) : "v"(lo), "v"(hi)); return r; }
; __device__ __forceinline__ float sigmoid_f(float x) { return __builtin_amdgcn_rcpf(1.0f + __builtin_amdgcn_exp2f(-1.44269504f * x)); }
; __device__ __forceinline__ f32x2 gelu_pk(f32x2 v) {
;     const f32x2 av = __builtin_elementwise_abs(v), d = av * 0.2316418882f + 1.0f;
;     f32x2 t; t.x = __builtin_amdgcn_rcpf(d.x); t.y = __builtin_amdgcn_rcpf(d.y);
;     f32x2 q = t * 0.5307027145f + (-0.7265760135f); q = q * t + 0.7107068705f; q = q * t + (-0.142248368f); q = q * t + 0.127414796f; q = q * t;
;     const f32x2 s = (v * v) * (-0.72134752044f);
;     f32x2 e; e.x = __builtin_amdgcn_exp2f(s.x); e.y = __builtin_amdgcn_exp2f(s.y);
;     const f32x2 m = v * (q * e), r = v - m;
;     f32x2 o; o.x = v.x < 0.f ? m.x : r.x; o.y = v.y < 0.f ? m.y : r.y; return o;
; }
; __device__ __forceinline__ f32x4 gelu4(f32x4 v) { f32x2 a = gelu_pk((f32x2){v[0], v[1]}), b = gelu_pk((f32x2){v[2], v[3]}); return (f32x4){a.x, a.y, b.x, b.y}; }
; __device__ __forceinline__ f32x4 sigm4(f32x4 v) { return (f32x4){sigmoid_f(v[0]), sigmoid_f(v[1]), sigmoid_f(v[2]), sigmoid_f(v[3])}; }
; __device__ __forceinline__ f32x4 silu4(f32x4 v) { return v * sigm4(v); }
;     __device__ __forceinline__ void operator()(const f32x4 (&acc)[2][2][4][2], const pg8::Unit& u, int wr, int wc, int fr, int fq) const {
;     ...
;                 for (int m = 0; m < 4; ++m) {
;                     bf16_t* rowp = base + (size_t)(row0 + ai * 128 + m * 16) * 1024;
;                     const f32x4 v0 = gelu4(acc[ai][0][m][0]) * silu4(acc[ai][1][m][0]), v1 = gelu4(acc[ai][0][m][1]) * silu4(acc[ai][1][m][1]);
;                     u32x4 w; w.x = cvt_pk_bf16(v0[0], v0[1]); w.y = cvt_pk_bf16(v0[2], v0[3]); w.z = cvt_pk_bf16(v1[0], v1[1]); w.w = cvt_pk_bf16(v1[2], v1[3]);
;                     __builtin_nontemporal_store(w, (u32x4*)rowp);
	v_pk_mul_f32 v[18:19], v[20:21], s[74:75] op_sel_hi:[1,0]
	v_pk_fma_f32 v[16:17], v[22:23], v[16:17], s[36:37] op_sel_hi:[1,1,0]
	v_exp_f32_e32 v18, v18
	v_exp_f32_e32 v19, v19
	v_pk_fma_f32 v[16:17], v[22:23], v[16:17], s[50:51] op_sel_hi:[1,1,0]
	s_nop 0
	v_pk_fma_f32 v[16:17], v[22:23], v[16:17], s[72:73] op_sel_hi:[1,1,0]
	s_nop 0
	v_pk_mul_f32 v[16:17], v[22:23], v[16:17]
	s_nop 0
	v_pk_mul_f32 v[16:17], v[18:19], v[16:17]
	s_nop 0
	v_max_f32_e32 v240, 0, v14
	v_max_f32_e32 v241, 0, v15
	v_pk_fma_f32 v[14:15], v[250:251], v[16:17], v[240:241] neg_lo:[1,0,0] neg_hi:[1,0,0]
	s_nop 0
	v_mul_f32_e32 v18, 0xbfb8aa3b, v9
	v_mul_f32_e32 v16, 0xbfb8aa3b, v8
	v_exp_f32_e32 v18, v18
	v_exp_f32_e32 v16, v16
	s_nop 0
	v_add_f32_e32 v16, 1.0, v16
	s_nop 0
	v_add_f32_e32 v17, 1.0, v18
	v_mul_f32_e32 v18, 0xbfb8aa3b, v10
	v_mul_f32_e32 v19, 0xbfb8aa3b, v11
	v_exp_f32_e32 v18, v18
	v_exp_f32_e32 v19, v19
	v_rcp_f32_e32 v16, v16
	v_rcp_f32_e32 v17, v17
	v_add_f32_e32 v18, 1.0, v18
	v_add_f32_e32 v19, 1.0, v19
	v_rcp_f32_e32 v18, v18
	v_rcp_f32_e32 v19, v19
	v_pk_mul_f32 v[8:9], v[8:9], v[16:17]
	v_and_b32_e32 v249, 0x7fffffff, v5
	v_and_b32_e32 v248, 0x7fffffff, v4
	v_pk_fma_f32 v[16:17], v[248:249], s[28:29], 1.0 op_sel_hi:[1,0,0]
	v_pk_mul_f32 v[10:11], v[10:11], v[18:19]
	v_rcp_f32_e32 v16, v16
	v_rcp_f32_e32 v17, v17
	v_pk_mul_f32 v[10:11], v[14:15], v[10:11]
	v_pk_mul_f32 v[14:15], v[4:5], v[4:5]
	v_pk_mul_f32 v[8:9], v[12:13], v[8:9]
	v_pk_fma_f32 v[12:13], v[16:17], s[30:31], v[150:151] op_sel_hi:[1,0,0]
	v_pk_mul_f32 v[14:15], v[14:15], s[74:75] op_sel_hi:[1,0]
	v_pk_fma_f32 v[12:13], v[16:17], v[12:13], s[36:37] op_sel_hi:[1,1,0]
	v_exp_f32_e32 v14, v14
	v_exp_f32_e32 v15, v15
	v_pk_fma_f32 v[12:13], v[16:17], v[12:13], s[50:51] op_sel_hi:[1,1,0]
	v_and_b32_e32 v251, 0x7fffffff, v7
	v_and_b32_e32 v250, 0x7fffffff, v6
	v_pk_fma_f32 v[12:13], v[16:17], v[12:13], s[72:73] op_sel_hi:[1,1,0]
	v_pk_fma_f32 v[18:19], v[250:251], s[28:29], 1.0 op_sel_hi:[1,0,0]
	v_pk_mul_f32 v[12:13], v[16:17], v[12:13]
	v_rcp_f32_e32 v18, v18
	v_rcp_f32_e32 v19, v19
	v_pk_mul_f32 v[12:13], v[14:15], v[12:13]
	v_max_f32_e32 v240, 0, v4
	v_max_f32_e32 v241, 0, v5
	v_pk_fma_f32 v[4:5], v[248:249], v[12:13], v[240:241] neg_lo:[1,0,0] neg_hi:[1,0,0]
	v_pk_mul_f32 v[16:17], v[6:7], v[6:7]
	s_nop 1
	v_pk_fma_f32 v[12:13], v[18:19], s[30:31], v[150:151] op_sel_hi:[1,0,0]
	v_pk_mul_f32 v[14:15], v[16:17], s[74:75] op_sel_hi:[1,0]
	v_pk_fma_f32 v[12:13], v[18:19], v[12:13], s[36:37] op_sel_hi:[1,1,0]
	v_exp_f32_e32 v14, v14
	v_exp_f32_e32 v15, v15
	v_pk_fma_f32 v[12:13], v[18:19], v[12:13], s[50:51] op_sel_hi:[1,1,0]
	v_mul_f32_e32 v16, 0xbfb8aa3b, v0
	v_pk_fma_f32 v[12:13], v[18:19], v[12:13], s[72:73] op_sel_hi:[1,1,0]
	v_exp_f32_e32 v16, v16
	v_mul_f32_e32 v17, 0xbfb8aa3b, v1
	v_pk_mul_f32 v[12:13], v[18:19], v[12:13]
	v_exp_f32_e32 v17, v17
	v_pk_mul_f32 v[12:13], v[14:15], v[12:13]
	v_max_f32_e32 v240, 0, v6
	v_max_f32_e32 v241, 0, v7
	v_pk_fma_f32 v[6:7], v[250:251], v[12:13], v[240:241] neg_lo:[1,0,0] neg_hi:[1,0,0]
	s_nop 0
	v_add_f32_e32 v12, 1.0, v16
	v_mul_f32_e32 v14, 0xbfb8aa3b, v2
	v_rcp_f32_e32 v16, v12
	v_add_f32_e32 v12, 1.0, v17
	v_exp_f32_e32 v14, v14
	v_mul_f32_e32 v17, 0xbfb8aa3b, v3
	v_exp_f32_e32 v19, v17
	v_rcp_f32_e32 v17, v12
	v_add_f32_e32 v12, 1.0, v14
	v_rcp_f32_e32 v18, v12
	v_add_f32_e32 v12, 1.0, v19
	v_rcp_f32_e32 v19, v12
	v_pk_mul_f32 v[0:1], v[0:1], v[16:17]
	v_pk_mul_f32 v[2:3], v[2:3], v[18:19]
	s_nop 0
	v_pk_mul_f32 v[6:7], v[6:7], v[2:3]
	v_pk_mul_f32 v[2:3], v[4:5], v[0:1]
	v_add_co_u32_e32 v4, vcc, 0x58000, v148
	v_cvt_pk_bf16_f32 v0, v8, v9
	v_cvt_pk_bf16_f32 v1, v10, v11
	v_cvt_pk_bf16_f32 v2, v2, v3
	v_cvt_pk_bf16_f32 v3, v6, v7
	s_nop 1
	v_addc_co_u32_e32 v5, vcc, 0, v149, vcc
	s_waitcnt vmcnt(7)
	global_store_dwordx4 v[4:5], v[0:3], off nt
	s_andn2_b64 vcc, exec, s[4:5]
	s_mov_b64 s[4:5], -1
	s_cbranch_vccnz .LBB0_152
